# inproj epilogue: fast paths for single-destination and two-region column tiles (16-byte stores via permlane16 swap, no per-store waits), workgroup stagger inside the inproj phase using the slack of 11
# speedup vs baseline: 1.2108x; 1.0118x over previous
.LBB0_982:
	s_andn2_b64 vcc, exec, s[0:1]
	s_mov_b64 s[2:3], 0
	s_cbranch_vccnz .LBB0_1587
	v_readlane_b32 s0, v252, 61
	v_readlane_b32 s1, v252, 62
	s_lshl_b64 s[0:1], s[0:1], 22
	v_writelane_b32 v253, s0, 10
	s_nop 1
	v_writelane_b32 v253, s1, 11
	s_nop 0
	v_readlane_b32 s0, v253, 1
	s_cmp_gt_i32 s0, 0
	s_mov_b64 s[0:1], -1
	s_cbranch_scc0 .LBB0_1585
	v_readlane_b32 s4, v252, 61
	s_lshl_b32 s0, s4, 11
	s_ashr_i32 s1, s0, 31
	v_readlane_b32 s2, v253, 4
	v_readlane_b32 s5, v252, 62
	v_readlane_b32 s3, v253, 5
	s_add_u32 s64, s2, 0x3080000
	s_addc_u32 s65, s3, 0
	s_lshl_b64 s[2:3], s[4:5], 15
	s_add_u32 s66, s2, 0x35d2000
	s_addc_u32 s67, s3, 0
	v_readlane_b32 s2, v253, 10
	v_readlane_b32 s3, v253, 11
	s_add_u32 s68, s2, 0x2880000
	s_addc_u32 s69, s3, 0
	v_readlane_b32 s8, v253, 8
	v_readlane_b32 s9, v253, 9
	s_add_u32 s70, s8, 0x35b2000
	s_addc_u32 s71, s9, 0
	s_add_u32 s72, s2, 0x2080000
	s_addc_u32 s73, s3, 0
	s_add_u32 s74, s8, 0x3592000
	s_addc_u32 s75, s9, 0
	s_lshl_b64 s[0:1], s[0:1], 2
	v_readlane_b32 s16, v252, 38
	v_readlane_b32 s17, v252, 39
	v_readlane_b32 s18, v252, 40
	v_readlane_b32 s19, v252, 41
	v_readlane_b32 s20, v252, 42
	v_readlane_b32 s21, v252, 43
	v_readlane_b32 s22, v252, 44
	v_readlane_b32 s23, v252, 45
	v_readlane_b32 s24, v252, 46
	v_readlane_b32 s25, v252, 47
	v_readlane_b32 s26, v252, 48
	v_readlane_b32 s27, v252, 49
	v_readlane_b32 s28, v252, 50
	v_readlane_b32 s29, v252, 51
	v_readlane_b32 s30, v252, 52
	v_readlane_b32 s31, v252, 53
	s_add_u32 s10, s16, s0
	s_addc_u32 s11, s17, s1
	v_readlane_b32 s16, v251, 1
	v_readlane_b32 s30, v251, 15
	v_readlane_b32 s31, v251, 16
	s_mov_b64 s[12:13], s[30:31]
	s_add_u32 s76, s12, 0x1f80000
	v_readlane_b32 s18, v251, 3
	s_addc_u32 s77, s13, 0
	v_readlane_b32 s19, v251, 4
	s_add_u32 s18, s12, 0x12380000
	v_readlane_b32 s20, v251, 5
	s_addc_u32 s19, s13, 0
	v_readlane_b32 s21, v251, 6
	s_add_u32 s20, s12, 0xa180000
	v_readlane_b32 s22, v251, 7
	s_addc_u32 s21, s13, 0
	v_readlane_b32 s23, v251, 8
	s_add_u32 s22, s12, 0x22982200
	v_readlane_b32 s24, v251, 9
	s_addc_u32 s23, s13, 0
	v_readlane_b32 s25, v251, 10
	s_add_u32 s24, s12, 0x23d82200
	v_readlane_b32 s26, v251, 11
	s_addc_u32 s25, s13, 0
	v_readlane_b32 s27, v251, 12
	s_add_u32 s26, s12, 0x22182200
	v_readlane_b32 s17, v251, 2
	v_readlane_b32 s28, v251, 13
	v_readlane_b32 s29, v251, 14
	s_addc_u32 s27, s13, 0
	s_mov_b64 s[16:17], s[28:29]
	s_add_u32 s28, s12, 0x21982200
	s_addc_u32 s29, s13, 0
	s_mul_hi_i32 s0, s4, 0x90000
	s_mul_i32 s1, s4, 0x90000
	s_mul_hi_i32 s2, s4, 0x24000
	s_mul_i32 s3, s4, 0x24000
	v_mov_b32_e32 v0, v211
	v_readlane_b32 s4, v251, 21
	s_add_u32 s30, s12, 0x6080000
	v_readlane_b32 s5, v251, 22
	s_waitcnt vmcnt(0)
	v_lshrrev_b32_e32 v4, 2, v0
	s_addc_u32 s31, s13, 0
	s_load_dword s78, s[4:5], 0x0
	v_lshrrev_b32_e32 v3, 1, v0
	v_and_b32_e32 v4, 12, v4
	s_movk_i32 s4, 0x60
	s_add_u32 s3, s16, s3
	v_and_b32_e32 v2, 15, v0
	v_and_or_b32 v135, v3, s4, v4
	v_ashrrev_i32_e32 v0, 2, v0
	s_movk_i32 s4, 0xffc0
	s_addc_u32 s2, s17, s2
	v_and_or_b32 v150, v0, s4, v2
	s_add_u32 s34, s3, 0xd200000
	v_subrev_co_u32_e64 v134, s[4:5], 13, v2
	s_addc_u32 s35, s2, 0
	s_xor_b64 s[36:37], s[4:5], -1
	s_add_u32 s1, s16, s1
	s_addc_u32 s0, s17, s0
	s_add_u32 s38, s1, 0xd788000
	s_addc_u32 s39, s0, 0
	s_mov_b32 s79, 0
	v_readlane_b32 s0, v251, 0
	s_cmp_lt_u32 s0, 44
	s_cbranch_scc1 .Lstag_ip_done
	s_lshr_b32 s0, s0, 3
	s_and_b32 s0, s0, 3
	s_mul_i32 s0, s0, 3
.Lstag_ip_loop:
	s_cmp_eq_u32 s0, 0
	s_cbranch_scc1 .Lstag_ip_done
	s_sleep 127
	s_sub_u32 s0, s0, 1
	s_branch .Lstag_ip_loop
.Lstag_ip_done:
	s_branch .LBB0_988
.LBB0_985:
	v_lshl_add_u64 v[8:9], v[0:1], 2, s[2:3]
	s_movk_i32 s0, 0x1800
	v_mad_i64_i32 v[6:7], s[0:1], v6, s0, v[8:9]
	flat_store_dwordx4 v[6:7], v[2:5]

.LBB0_1001:
	s_or_b64 exec, exec, s[0:1]
	s_mov_b32 s53, 0
	s_cmp_lt_u32 s80, 2
	s_cbranch_scc1 .Lipf_hq
	s_sub_u32 s0, s80, 3
	s_cmp_lt_u32 s0, 2
	s_cbranch_scc1 .Lipf_hqi
	s_sub_u32 s0, s80, 6
	s_cmp_lt_u32 s0, 5
	s_cbranch_scc1 .Lipf_hqkv
	s_cmp_eq_u32 s80, 12
	s_cbranch_scc1 .Lipf_hgb
	s_sub_u32 s0, s80, 14
	s_cmp_lt_u32 s0, 7
	s_cbranch_scc1 .Lipf_hg
	s_cmp_eq_u32 s80, 11
	s_cbranch_scc1 .Lipg_11
	s_cmp_eq_u32 s80, 13
	s_cbranch_scc1 .Lipg_13
	s_cmp_eq_u32 s80, 21
	s_cbranch_scc1 .Lipg_21
	s_branch .Lipf_slow
.Lipf_hq:
	s_mov_b32 s44, 0x6080000
	s_movk_i32 s45, 0x0
	s_movk_i32 s52, 0x400
	s_branch .Lipf_common
.Lipf_hqi:
	s_mov_b32 s44, 0x8100000
	s_movk_i32 s45, 0x300
	s_movk_i32 s52, 0x400
	s_branch .Lipf_common
.Lipf_hqkv:
	s_cmpk_gt_i32 s81, 0x7f
	s_cbranch_scc1 .Lipf_slow
	s_and_b32 s0, s81, 15
	s_cmp_eq_u32 s0, 15
	s_cbranch_scc1 .Lipf_slow
	s_mov_b32 s44, 0xa180000
	s_movk_i32 s45, 0x548
	s_movk_i32 s52, 0xc00
	s_branch .Lipf_common
.Lipf_hgb:
	s_mov_b32 s44, 0x10300000
	s_movk_i32 s45, 0xb50
	s_movk_i32 s52, 0x400
	s_branch .Lipf_common
.Lipf_hg:
	s_mov_b32 s53, 1
	s_mov_b32 s44, 0x12380000
	s_movk_i32 s45, 0xd50
	s_movk_i32 s52, 0x1000
.Lipf_common:
	s_lshl_b32 s54, s80, 8
	s_sub_u32 s45, s54, s45
	s_lshl_b32 s0, s45, 1
	s_add_u32 s44, s44, s0
	s_add_u32 s56, s12, s44
	s_addc_u32 s57, s13, 0
	s_lshl_b32 s60, s81, 8
	s_mov_b32 s43, 0
	v_add_u32_e32 v176, s60, v150
	v_lshrrev_b32_e32 v178, 4, v219
	v_and_b32_e32 v179, 1, v178
	v_lshrrev_b32_e32 v178, 1, v178
	v_lshl_add_u32 v178, v179, 1, v178
	v_lshlrev_b32_e32 v178, 4, v178
	v_bfe_u32 v179, v211, 6, 2
	v_lshl_add_u32 v158, v179, 6, v178
	v_mov_b32_e32 v159, 0
	s_nop 7
	s_nop 7
	v_mad_u64_u32 v[152:153], s[58:59], v176, s52, v[158:159]
	v_lshl_add_u64 v[152:153], v[152:153], 0, s[56:57]
	s_cmp_eq_u32 s53, 0
	s_cbranch_scc1 .Lipf_plain
	v_add_u32_e32 v178, s45, v135
	v_mov_b32_e32 v179, 0
	v_lshl_add_u64 v[178:179], v[178:179], 2, s[10:11]
	global_load_dwordx4 v[160:163], v[178:179], off offset:0
	global_load_dwordx4 v[164:167], v[178:179], off offset:64
	global_load_dwordx4 v[168:171], v[178:179], off offset:512
	global_load_dwordx4 v[172:175], v[178:179], off offset:576
	s_waitcnt vmcnt(0)
	v_mov_b32_e32 v154, v152
	v_mov_b32_e32 v155, v153
	v_add_f32_e32 v130, v130, v160
	v_add_f32_e32 v131, v131, v161
	v_add_f32_e32 v132, v132, v162
	v_add_f32_e32 v133, v133, v163
	v_add_f32_e32 v94, v94, v164
	v_add_f32_e32 v95, v95, v165
	v_add_f32_e32 v96, v96, v166
	v_add_f32_e32 v97, v97, v167
	v_mul_f32_e32 v130, 0xbfb8aa3b, v130
	v_mul_f32_e32 v131, 0xbfb8aa3b, v131
	v_mul_f32_e32 v132, 0xbfb8aa3b, v132
	v_mul_f32_e32 v133, 0xbfb8aa3b, v133
	v_mul_f32_e32 v94, 0xbfb8aa3b, v94
	v_mul_f32_e32 v95, 0xbfb8aa3b, v95
	v_mul_f32_e32 v96, 0xbfb8aa3b, v96
	v_mul_f32_e32 v97, 0xbfb8aa3b, v97
	v_exp_f32_e32 v130, v130
	v_exp_f32_e32 v131, v131
	v_exp_f32_e32 v132, v132
	v_exp_f32_e32 v133, v133
	v_exp_f32_e32 v94, v94
	v_exp_f32_e32 v95, v95
	v_exp_f32_e32 v96, v96
	v_exp_f32_e32 v97, v97
	v_add_f32_e32 v130, 1.0, v130
	v_add_f32_e32 v131, 1.0, v131
	v_add_f32_e32 v132, 1.0, v132
	v_add_f32_e32 v133, 1.0, v133
	v_add_f32_e32 v94, 1.0, v94
	v_add_f32_e32 v95, 1.0, v95
	v_add_f32_e32 v96, 1.0, v96
	v_add_f32_e32 v97, 1.0, v97
	v_rcp_f32_e32 v130, v130
	v_rcp_f32_e32 v131, v131
	v_rcp_f32_e32 v132, v132
	v_rcp_f32_e32 v133, v133
	v_rcp_f32_e32 v94, v94
	v_rcp_f32_e32 v95, v95
	v_rcp_f32_e32 v96, v96
	v_rcp_f32_e32 v97, v97
	v_add_f32_e32 v62, v62, v168
	v_add_f32_e32 v63, v63, v169
	v_add_f32_e32 v64, v64, v170
	v_add_f32_e32 v65, v65, v171
	v_add_f32_e32 v30, v30, v172
	v_add_f32_e32 v31, v31, v173
	v_add_f32_e32 v32, v32, v174
	v_add_f32_e32 v33, v33, v175
	v_mul_f32_e32 v62, 0xbfb8aa3b, v62
	v_mul_f32_e32 v63, 0xbfb8aa3b, v63
	v_mul_f32_e32 v64, 0xbfb8aa3b, v64
	v_mul_f32_e32 v65, 0xbfb8aa3b, v65
	v_mul_f32_e32 v30, 0xbfb8aa3b, v30
	v_mul_f32_e32 v31, 0xbfb8aa3b, v31
	v_mul_f32_e32 v32, 0xbfb8aa3b, v32
	v_mul_f32_e32 v33, 0xbfb8aa3b, v33
	v_exp_f32_e32 v62, v62
	v_exp_f32_e32 v63, v63
	v_exp_f32_e32 v64, v64
	v_exp_f32_e32 v65, v65
	v_exp_f32_e32 v30, v30
	v_exp_f32_e32 v31, v31
	v_exp_f32_e32 v32, v32
	v_exp_f32_e32 v33, v33
	v_add_f32_e32 v62, 1.0, v62
	v_add_f32_e32 v63, 1.0, v63
	v_add_f32_e32 v64, 1.0, v64
	v_add_f32_e32 v65, 1.0, v65
	v_add_f32_e32 v30, 1.0, v30
	v_add_f32_e32 v31, 1.0, v31
	v_add_f32_e32 v32, 1.0, v32
	v_add_f32_e32 v33, 1.0, v33
	v_rcp_f32_e32 v62, v62
	v_rcp_f32_e32 v63, v63
	v_rcp_f32_e32 v64, v64
	v_rcp_f32_e32 v65, v65
	v_rcp_f32_e32 v30, v30
	v_rcp_f32_e32 v31, v31
	v_rcp_f32_e32 v32, v32
	v_rcp_f32_e32 v33, v33
	v_cvt_pk_bf16_f32 v130, v130, v131
	v_cvt_pk_bf16_f32 v131, v132, v133
	v_cvt_pk_bf16_f32 v132, v94, v95
	v_cvt_pk_bf16_f32 v133, v96, v97
	v_cvt_pk_bf16_f32 v62, v62, v63
	v_cvt_pk_bf16_f32 v63, v64, v65
	v_cvt_pk_bf16_f32 v64, v30, v31
	v_cvt_pk_bf16_f32 v65, v32, v33
	v_permlane16_swap_b32_e32 v130, v132
	v_permlane16_swap_b32_e32 v131, v133
	v_permlane16_swap_b32_e32 v62, v64
	v_permlane16_swap_b32_e32 v63, v65
	global_store_dwordx4 v[154:155], v[130:133], off offset:0
	global_store_dwordx4 v[154:155], v[62:65], off offset:256
	s_mul_i32 s42, s52, 16
	v_lshl_add_u64 v[156:157], v[152:153], 0, s[42:43]
	v_add_f32_e32 v126, v126, v160
	v_add_f32_e32 v127, v127, v161
	v_add_f32_e32 v128, v128, v162
	v_add_f32_e32 v129, v129, v163
	v_add_f32_e32 v90, v90, v164
	v_add_f32_e32 v91, v91, v165
	v_add_f32_e32 v92, v92, v166
	v_add_f32_e32 v93, v93, v167
	v_mul_f32_e32 v126, 0xbfb8aa3b, v126
	v_mul_f32_e32 v127, 0xbfb8aa3b, v127
	v_mul_f32_e32 v128, 0xbfb8aa3b, v128
	v_mul_f32_e32 v129, 0xbfb8aa3b, v129
	v_mul_f32_e32 v90, 0xbfb8aa3b, v90
	v_mul_f32_e32 v91, 0xbfb8aa3b, v91
	v_mul_f32_e32 v92, 0xbfb8aa3b, v92
	v_mul_f32_e32 v93, 0xbfb8aa3b, v93
	v_exp_f32_e32 v126, v126
	v_exp_f32_e32 v127, v127
	v_exp_f32_e32 v128, v128
	v_exp_f32_e32 v129, v129
	v_exp_f32_e32 v90, v90
	v_exp_f32_e32 v91, v91
	v_exp_f32_e32 v92, v92
	v_exp_f32_e32 v93, v93
	v_add_f32_e32 v126, 1.0, v126
	v_add_f32_e32 v127, 1.0, v127
	v_add_f32_e32 v128, 1.0, v128
	v_add_f32_e32 v129, 1.0, v129
	v_add_f32_e32 v90, 1.0, v90
	v_add_f32_e32 v91, 1.0, v91
	v_add_f32_e32 v92, 1.0, v92
	v_add_f32_e32 v93, 1.0, v93
	v_rcp_f32_e32 v126, v126
	v_rcp_f32_e32 v127, v127
	v_rcp_f32_e32 v128, v128
	v_rcp_f32_e32 v129, v129
	v_rcp_f32_e32 v90, v90
	v_rcp_f32_e32 v91, v91
	v_rcp_f32_e32 v92, v92
	v_rcp_f32_e32 v93, v93
	v_add_f32_e32 v58, v58, v168
	v_add_f32_e32 v59, v59, v169
	v_add_f32_e32 v60, v60, v170
	v_add_f32_e32 v61, v61, v171
	v_add_f32_e32 v26, v26, v172
	v_add_f32_e32 v27, v27, v173
	v_add_f32_e32 v28, v28, v174
	v_add_f32_e32 v29, v29, v175
	v_mul_f32_e32 v58, 0xbfb8aa3b, v58
	v_mul_f32_e32 v59, 0xbfb8aa3b, v59
	v_mul_f32_e32 v60, 0xbfb8aa3b, v60
	v_mul_f32_e32 v61, 0xbfb8aa3b, v61
	v_mul_f32_e32 v26, 0xbfb8aa3b, v26
	v_mul_f32_e32 v27, 0xbfb8aa3b, v27
	v_mul_f32_e32 v28, 0xbfb8aa3b, v28
	v_mul_f32_e32 v29, 0xbfb8aa3b, v29
	v_exp_f32_e32 v58, v58
	v_exp_f32_e32 v59, v59
	v_exp_f32_e32 v60, v60
	v_exp_f32_e32 v61, v61
	v_exp_f32_e32 v26, v26
	v_exp_f32_e32 v27, v27
	v_exp_f32_e32 v28, v28
	v_exp_f32_e32 v29, v29
	v_add_f32_e32 v58, 1.0, v58
	v_add_f32_e32 v59, 1.0, v59
	v_add_f32_e32 v60, 1.0, v60
	v_add_f32_e32 v61, 1.0, v61
	v_add_f32_e32 v26, 1.0, v26
	v_add_f32_e32 v27, 1.0, v27
	v_add_f32_e32 v28, 1.0, v28
	v_add_f32_e32 v29, 1.0, v29
	v_rcp_f32_e32 v58, v58
	v_rcp_f32_e32 v59, v59
	v_rcp_f32_e32 v60, v60
	v_rcp_f32_e32 v61, v61
	v_rcp_f32_e32 v26, v26
	v_rcp_f32_e32 v27, v27
	v_rcp_f32_e32 v28, v28
	v_rcp_f32_e32 v29, v29
	v_cvt_pk_bf16_f32 v126, v126, v127
	v_cvt_pk_bf16_f32 v127, v128, v129
	v_cvt_pk_bf16_f32 v128, v90, v91
	v_cvt_pk_bf16_f32 v129, v92, v93
	v_cvt_pk_bf16_f32 v58, v58, v59
	v_cvt_pk_bf16_f32 v59, v60, v61
	v_cvt_pk_bf16_f32 v60, v26, v27
	v_cvt_pk_bf16_f32 v61, v28, v29
	v_permlane16_swap_b32_e32 v126, v128
	v_permlane16_swap_b32_e32 v127, v129
	v_permlane16_swap_b32_e32 v58, v60
	v_permlane16_swap_b32_e32 v59, v61
	global_store_dwordx4 v[156:157], v[126:129], off offset:0
	global_store_dwordx4 v[156:157], v[58:61], off offset:256
	s_mul_i32 s42, s52, 32
	v_lshl_add_u64 v[154:155], v[152:153], 0, s[42:43]
	v_add_f32_e32 v122, v122, v160
	v_add_f32_e32 v123, v123, v161
	v_add_f32_e32 v124, v124, v162
	v_add_f32_e32 v125, v125, v163
	v_add_f32_e32 v86, v86, v164
	v_add_f32_e32 v87, v87, v165
	v_add_f32_e32 v88, v88, v166
	v_add_f32_e32 v89, v89, v167
	v_mul_f32_e32 v122, 0xbfb8aa3b, v122
	v_mul_f32_e32 v123, 0xbfb8aa3b, v123
	v_mul_f32_e32 v124, 0xbfb8aa3b, v124
	v_mul_f32_e32 v125, 0xbfb8aa3b, v125
	v_mul_f32_e32 v86, 0xbfb8aa3b, v86
	v_mul_f32_e32 v87, 0xbfb8aa3b, v87
	v_mul_f32_e32 v88, 0xbfb8aa3b, v88
	v_mul_f32_e32 v89, 0xbfb8aa3b, v89
	v_exp_f32_e32 v122, v122
	v_exp_f32_e32 v123, v123
	v_exp_f32_e32 v124, v124
	v_exp_f32_e32 v125, v125
	v_exp_f32_e32 v86, v86
	v_exp_f32_e32 v87, v87
	v_exp_f32_e32 v88, v88
	v_exp_f32_e32 v89, v89
	v_add_f32_e32 v122, 1.0, v122
	v_add_f32_e32 v123, 1.0, v123
	v_add_f32_e32 v124, 1.0, v124
	v_add_f32_e32 v125, 1.0, v125
	v_add_f32_e32 v86, 1.0, v86
	v_add_f32_e32 v87, 1.0, v87
	v_add_f32_e32 v88, 1.0, v88
	v_add_f32_e32 v89, 1.0, v89
	v_rcp_f32_e32 v122, v122
	v_rcp_f32_e32 v123, v123
	v_rcp_f32_e32 v124, v124
	v_rcp_f32_e32 v125, v125
	v_rcp_f32_e32 v86, v86
	v_rcp_f32_e32 v87, v87
	v_rcp_f32_e32 v88, v88
	v_rcp_f32_e32 v89, v89
	v_add_f32_e32 v54, v54, v168
	v_add_f32_e32 v55, v55, v169
	v_add_f32_e32 v56, v56, v170
	v_add_f32_e32 v57, v57, v171
	v_add_f32_e32 v22, v22, v172
	v_add_f32_e32 v23, v23, v173
	v_add_f32_e32 v24, v24, v174
	v_add_f32_e32 v25, v25, v175
	v_mul_f32_e32 v54, 0xbfb8aa3b, v54
	v_mul_f32_e32 v55, 0xbfb8aa3b, v55
	v_mul_f32_e32 v56, 0xbfb8aa3b, v56
	v_mul_f32_e32 v57, 0xbfb8aa3b, v57
	v_mul_f32_e32 v22, 0xbfb8aa3b, v22
	v_mul_f32_e32 v23, 0xbfb8aa3b, v23
	v_mul_f32_e32 v24, 0xbfb8aa3b, v24
	v_mul_f32_e32 v25, 0xbfb8aa3b, v25
	v_exp_f32_e32 v54, v54
	v_exp_f32_e32 v55, v55
	v_exp_f32_e32 v56, v56
	v_exp_f32_e32 v57, v57
	v_exp_f32_e32 v22, v22
	v_exp_f32_e32 v23, v23
	v_exp_f32_e32 v24, v24
	v_exp_f32_e32 v25, v25
	v_add_f32_e32 v54, 1.0, v54
	v_add_f32_e32 v55, 1.0, v55
	v_add_f32_e32 v56, 1.0, v56
	v_add_f32_e32 v57, 1.0, v57
	v_add_f32_e32 v22, 1.0, v22
	v_add_f32_e32 v23, 1.0, v23
	v_add_f32_e32 v24, 1.0, v24
	v_add_f32_e32 v25, 1.0, v25
	v_rcp_f32_e32 v54, v54
	v_rcp_f32_e32 v55, v55
	v_rcp_f32_e32 v56, v56
	v_rcp_f32_e32 v57, v57
	v_rcp_f32_e32 v22, v22
	v_rcp_f32_e32 v23, v23
	v_rcp_f32_e32 v24, v24
	v_rcp_f32_e32 v25, v25
	v_cvt_pk_bf16_f32 v122, v122, v123
	v_cvt_pk_bf16_f32 v123, v124, v125
	v_cvt_pk_bf16_f32 v124, v86, v87
	v_cvt_pk_bf16_f32 v125, v88, v89
	v_cvt_pk_bf16_f32 v54, v54, v55
	v_cvt_pk_bf16_f32 v55, v56, v57
	v_cvt_pk_bf16_f32 v56, v22, v23
	v_cvt_pk_bf16_f32 v57, v24, v25
	v_permlane16_swap_b32_e32 v122, v124
	v_permlane16_swap_b32_e32 v123, v125
	v_permlane16_swap_b32_e32 v54, v56
	v_permlane16_swap_b32_e32 v55, v57
	global_store_dwordx4 v[154:155], v[122:125], off offset:0
	global_store_dwordx4 v[154:155], v[54:57], off offset:256
	s_mul_i32 s42, s52, 48
	v_lshl_add_u64 v[156:157], v[152:153], 0, s[42:43]
	v_add_f32_e32 v118, v118, v160
	v_add_f32_e32 v119, v119, v161
	v_add_f32_e32 v120, v120, v162
	v_add_f32_e32 v121, v121, v163
	v_add_f32_e32 v82, v82, v164
	v_add_f32_e32 v83, v83, v165
	v_add_f32_e32 v84, v84, v166
	v_add_f32_e32 v85, v85, v167
	v_mul_f32_e32 v118, 0xbfb8aa3b, v118
	v_mul_f32_e32 v119, 0xbfb8aa3b, v119
	v_mul_f32_e32 v120, 0xbfb8aa3b, v120
	v_mul_f32_e32 v121, 0xbfb8aa3b, v121
	v_mul_f32_e32 v82, 0xbfb8aa3b, v82
	v_mul_f32_e32 v83, 0xbfb8aa3b, v83
	v_mul_f32_e32 v84, 0xbfb8aa3b, v84
	v_mul_f32_e32 v85, 0xbfb8aa3b, v85
	v_exp_f32_e32 v118, v118
	v_exp_f32_e32 v119, v119
	v_exp_f32_e32 v120, v120
	v_exp_f32_e32 v121, v121
	v_exp_f32_e32 v82, v82
	v_exp_f32_e32 v83, v83
	v_exp_f32_e32 v84, v84
	v_exp_f32_e32 v85, v85
	v_add_f32_e32 v118, 1.0, v118
	v_add_f32_e32 v119, 1.0, v119
	v_add_f32_e32 v120, 1.0, v120
	v_add_f32_e32 v121, 1.0, v121
	v_add_f32_e32 v82, 1.0, v82
	v_add_f32_e32 v83, 1.0, v83
	v_add_f32_e32 v84, 1.0, v84
	v_add_f32_e32 v85, 1.0, v85
	v_rcp_f32_e32 v118, v118
	v_rcp_f32_e32 v119, v119
	v_rcp_f32_e32 v120, v120
	v_rcp_f32_e32 v121, v121
	v_rcp_f32_e32 v82, v82
	v_rcp_f32_e32 v83, v83
	v_rcp_f32_e32 v84, v84
	v_rcp_f32_e32 v85, v85
	v_add_f32_e32 v50, v50, v168
	v_add_f32_e32 v51, v51, v169
	v_add_f32_e32 v52, v52, v170
	v_add_f32_e32 v53, v53, v171
	v_add_f32_e32 v18, v18, v172
	v_add_f32_e32 v19, v19, v173
	v_add_f32_e32 v20, v20, v174
	v_add_f32_e32 v21, v21, v175
	v_mul_f32_e32 v50, 0xbfb8aa3b, v50
	v_mul_f32_e32 v51, 0xbfb8aa3b, v51
	v_mul_f32_e32 v52, 0xbfb8aa3b, v52
	v_mul_f32_e32 v53, 0xbfb8aa3b, v53
	v_mul_f32_e32 v18, 0xbfb8aa3b, v18
	v_mul_f32_e32 v19, 0xbfb8aa3b, v19
	v_mul_f32_e32 v20, 0xbfb8aa3b, v20
	v_mul_f32_e32 v21, 0xbfb8aa3b, v21
	v_exp_f32_e32 v50, v50
	v_exp_f32_e32 v51, v51
	v_exp_f32_e32 v52, v52
	v_exp_f32_e32 v53, v53
	v_exp_f32_e32 v18, v18
	v_exp_f32_e32 v19, v19
	v_exp_f32_e32 v20, v20
	v_exp_f32_e32 v21, v21
	v_add_f32_e32 v50, 1.0, v50
	v_add_f32_e32 v51, 1.0, v51
	v_add_f32_e32 v52, 1.0, v52
	v_add_f32_e32 v53, 1.0, v53
	v_add_f32_e32 v18, 1.0, v18
	v_add_f32_e32 v19, 1.0, v19
	v_add_f32_e32 v20, 1.0, v20
	v_add_f32_e32 v21, 1.0, v21
	v_rcp_f32_e32 v50, v50
	v_rcp_f32_e32 v51, v51
	v_rcp_f32_e32 v52, v52
	v_rcp_f32_e32 v53, v53
	v_rcp_f32_e32 v18, v18
	v_rcp_f32_e32 v19, v19
	v_rcp_f32_e32 v20, v20
	v_rcp_f32_e32 v21, v21
	v_cvt_pk_bf16_f32 v118, v118, v119
	v_cvt_pk_bf16_f32 v119, v120, v121
	v_cvt_pk_bf16_f32 v120, v82, v83
	v_cvt_pk_bf16_f32 v121, v84, v85
	v_cvt_pk_bf16_f32 v50, v50, v51
	v_cvt_pk_bf16_f32 v51, v52, v53
	v_cvt_pk_bf16_f32 v52, v18, v19
	v_cvt_pk_bf16_f32 v53, v20, v21
	v_permlane16_swap_b32_e32 v118, v120
	v_permlane16_swap_b32_e32 v119, v121
	v_permlane16_swap_b32_e32 v50, v52
	v_permlane16_swap_b32_e32 v51, v53
	global_store_dwordx4 v[156:157], v[118:121], off offset:0
	global_store_dwordx4 v[156:157], v[50:53], off offset:256
	s_mul_i32 s42, s52, 128
	v_lshl_add_u64 v[154:155], v[152:153], 0, s[42:43]
	v_add_f32_e32 v114, v114, v160
	v_add_f32_e32 v115, v115, v161
	v_add_f32_e32 v116, v116, v162
	v_add_f32_e32 v117, v117, v163
	v_add_f32_e32 v78, v78, v164
	v_add_f32_e32 v79, v79, v165
	v_add_f32_e32 v80, v80, v166
	v_add_f32_e32 v81, v81, v167
	v_mul_f32_e32 v114, 0xbfb8aa3b, v114
	v_mul_f32_e32 v115, 0xbfb8aa3b, v115
	v_mul_f32_e32 v116, 0xbfb8aa3b, v116
	v_mul_f32_e32 v117, 0xbfb8aa3b, v117
	v_mul_f32_e32 v78, 0xbfb8aa3b, v78
	v_mul_f32_e32 v79, 0xbfb8aa3b, v79
	v_mul_f32_e32 v80, 0xbfb8aa3b, v80
	v_mul_f32_e32 v81, 0xbfb8aa3b, v81
	v_exp_f32_e32 v114, v114
	v_exp_f32_e32 v115, v115
	v_exp_f32_e32 v116, v116
	v_exp_f32_e32 v117, v117
	v_exp_f32_e32 v78, v78
	v_exp_f32_e32 v79, v79
	v_exp_f32_e32 v80, v80
	v_exp_f32_e32 v81, v81
	v_add_f32_e32 v114, 1.0, v114
	v_add_f32_e32 v115, 1.0, v115
	v_add_f32_e32 v116, 1.0, v116
	v_add_f32_e32 v117, 1.0, v117
	v_add_f32_e32 v78, 1.0, v78
	v_add_f32_e32 v79, 1.0, v79
	v_add_f32_e32 v80, 1.0, v80
	v_add_f32_e32 v81, 1.0, v81
	v_rcp_f32_e32 v114, v114
	v_rcp_f32_e32 v115, v115
	v_rcp_f32_e32 v116, v116
	v_rcp_f32_e32 v117, v117
	v_rcp_f32_e32 v78, v78
	v_rcp_f32_e32 v79, v79
	v_rcp_f32_e32 v80, v80
	v_rcp_f32_e32 v81, v81
	v_add_f32_e32 v46, v46, v168
	v_add_f32_e32 v47, v47, v169
	v_add_f32_e32 v48, v48, v170
	v_add_f32_e32 v49, v49, v171
	v_add_f32_e32 v14, v14, v172
	v_add_f32_e32 v15, v15, v173
	v_add_f32_e32 v16, v16, v174
	v_add_f32_e32 v17, v17, v175
	v_mul_f32_e32 v46, 0xbfb8aa3b, v46
	v_mul_f32_e32 v47, 0xbfb8aa3b, v47
	v_mul_f32_e32 v48, 0xbfb8aa3b, v48
	v_mul_f32_e32 v49, 0xbfb8aa3b, v49
	v_mul_f32_e32 v14, 0xbfb8aa3b, v14
	v_mul_f32_e32 v15, 0xbfb8aa3b, v15
	v_mul_f32_e32 v16, 0xbfb8aa3b, v16
	v_mul_f32_e32 v17, 0xbfb8aa3b, v17
	v_exp_f32_e32 v46, v46
	v_exp_f32_e32 v47, v47
	v_exp_f32_e32 v48, v48
	v_exp_f32_e32 v49, v49
	v_exp_f32_e32 v14, v14
	v_exp_f32_e32 v15, v15
	v_exp_f32_e32 v16, v16
	v_exp_f32_e32 v17, v17
	v_add_f32_e32 v46, 1.0, v46
	v_add_f32_e32 v47, 1.0, v47
	v_add_f32_e32 v48, 1.0, v48
	v_add_f32_e32 v49, 1.0, v49
	v_add_f32_e32 v14, 1.0, v14
	v_add_f32_e32 v15, 1.0, v15
	v_add_f32_e32 v16, 1.0, v16
	v_add_f32_e32 v17, 1.0, v17
	v_rcp_f32_e32 v46, v46
	v_rcp_f32_e32 v47, v47
	v_rcp_f32_e32 v48, v48
	v_rcp_f32_e32 v49, v49
	v_rcp_f32_e32 v14, v14
	v_rcp_f32_e32 v15, v15
	v_rcp_f32_e32 v16, v16
	v_rcp_f32_e32 v17, v17
	v_cvt_pk_bf16_f32 v114, v114, v115
	v_cvt_pk_bf16_f32 v115, v116, v117
	v_cvt_pk_bf16_f32 v116, v78, v79
	v_cvt_pk_bf16_f32 v117, v80, v81
	v_cvt_pk_bf16_f32 v46, v46, v47
	v_cvt_pk_bf16_f32 v47, v48, v49
	v_cvt_pk_bf16_f32 v48, v14, v15
	v_cvt_pk_bf16_f32 v49, v16, v17
	v_permlane16_swap_b32_e32 v114, v116
	v_permlane16_swap_b32_e32 v115, v117
	v_permlane16_swap_b32_e32 v46, v48
	v_permlane16_swap_b32_e32 v47, v49
	global_store_dwordx4 v[154:155], v[114:117], off offset:0
	global_store_dwordx4 v[154:155], v[46:49], off offset:256
	s_mul_i32 s42, s52, 144
	v_lshl_add_u64 v[156:157], v[152:153], 0, s[42:43]
	v_add_f32_e32 v106, v106, v160
	v_add_f32_e32 v107, v107, v161
	v_add_f32_e32 v108, v108, v162
	v_add_f32_e32 v109, v109, v163
	v_add_f32_e32 v74, v74, v164
	v_add_f32_e32 v75, v75, v165
	v_add_f32_e32 v76, v76, v166
	v_add_f32_e32 v77, v77, v167
	v_mul_f32_e32 v106, 0xbfb8aa3b, v106
	v_mul_f32_e32 v107, 0xbfb8aa3b, v107
	v_mul_f32_e32 v108, 0xbfb8aa3b, v108
	v_mul_f32_e32 v109, 0xbfb8aa3b, v109
	v_mul_f32_e32 v74, 0xbfb8aa3b, v74
	v_mul_f32_e32 v75, 0xbfb8aa3b, v75
	v_mul_f32_e32 v76, 0xbfb8aa3b, v76
	v_mul_f32_e32 v77, 0xbfb8aa3b, v77
	v_exp_f32_e32 v106, v106
	v_exp_f32_e32 v107, v107
	v_exp_f32_e32 v108, v108
	v_exp_f32_e32 v109, v109
	v_exp_f32_e32 v74, v74
	v_exp_f32_e32 v75, v75
	v_exp_f32_e32 v76, v76
	v_exp_f32_e32 v77, v77
	v_add_f32_e32 v106, 1.0, v106
	v_add_f32_e32 v107, 1.0, v107
	v_add_f32_e32 v108, 1.0, v108
	v_add_f32_e32 v109, 1.0, v109
	v_add_f32_e32 v74, 1.0, v74
	v_add_f32_e32 v75, 1.0, v75
	v_add_f32_e32 v76, 1.0, v76
	v_add_f32_e32 v77, 1.0, v77
	v_rcp_f32_e32 v106, v106
	v_rcp_f32_e32 v107, v107
	v_rcp_f32_e32 v108, v108
	v_rcp_f32_e32 v109, v109
	v_rcp_f32_e32 v74, v74
	v_rcp_f32_e32 v75, v75
	v_rcp_f32_e32 v76, v76
	v_rcp_f32_e32 v77, v77
	v_add_f32_e32 v42, v42, v168
	v_add_f32_e32 v43, v43, v169
	v_add_f32_e32 v44, v44, v170
	v_add_f32_e32 v45, v45, v171
	v_add_f32_e32 v10, v10, v172
	v_add_f32_e32 v11, v11, v173
	v_add_f32_e32 v12, v12, v174
	v_add_f32_e32 v13, v13, v175
	v_mul_f32_e32 v42, 0xbfb8aa3b, v42
	v_mul_f32_e32 v43, 0xbfb8aa3b, v43
	v_mul_f32_e32 v44, 0xbfb8aa3b, v44
	v_mul_f32_e32 v45, 0xbfb8aa3b, v45
	v_mul_f32_e32 v10, 0xbfb8aa3b, v10
	v_mul_f32_e32 v11, 0xbfb8aa3b, v11
	v_mul_f32_e32 v12, 0xbfb8aa3b, v12
	v_mul_f32_e32 v13, 0xbfb8aa3b, v13
	v_exp_f32_e32 v42, v42
	v_exp_f32_e32 v43, v43
	v_exp_f32_e32 v44, v44
	v_exp_f32_e32 v45, v45
	v_exp_f32_e32 v10, v10
	v_exp_f32_e32 v11, v11
	v_exp_f32_e32 v12, v12
	v_exp_f32_e32 v13, v13
	v_add_f32_e32 v42, 1.0, v42
	v_add_f32_e32 v43, 1.0, v43
	v_add_f32_e32 v44, 1.0, v44
	v_add_f32_e32 v45, 1.0, v45
	v_add_f32_e32 v10, 1.0, v10
	v_add_f32_e32 v11, 1.0, v11
	v_add_f32_e32 v12, 1.0, v12
	v_add_f32_e32 v13, 1.0, v13
	v_rcp_f32_e32 v42, v42
	v_rcp_f32_e32 v43, v43
	v_rcp_f32_e32 v44, v44
	v_rcp_f32_e32 v45, v45
	v_rcp_f32_e32 v10, v10
	v_rcp_f32_e32 v11, v11
	v_rcp_f32_e32 v12, v12
	v_rcp_f32_e32 v13, v13
	v_cvt_pk_bf16_f32 v106, v106, v107
	v_cvt_pk_bf16_f32 v107, v108, v109
	v_cvt_pk_bf16_f32 v108, v74, v75
	v_cvt_pk_bf16_f32 v109, v76, v77
	v_cvt_pk_bf16_f32 v42, v42, v43
	v_cvt_pk_bf16_f32 v43, v44, v45
	v_cvt_pk_bf16_f32 v44, v10, v11
	v_cvt_pk_bf16_f32 v45, v12, v13
	v_permlane16_swap_b32_e32 v106, v108
	v_permlane16_swap_b32_e32 v107, v109
	v_permlane16_swap_b32_e32 v42, v44
	v_permlane16_swap_b32_e32 v43, v45
	global_store_dwordx4 v[156:157], v[106:109], off offset:0
	global_store_dwordx4 v[156:157], v[42:45], off offset:256
	s_mul_i32 s42, s52, 160
	v_lshl_add_u64 v[154:155], v[152:153], 0, s[42:43]
	v_add_f32_e32 v102, v102, v160
	v_add_f32_e32 v103, v103, v161
	v_add_f32_e32 v104, v104, v162
	v_add_f32_e32 v105, v105, v163
	v_add_f32_e32 v70, v70, v164
	v_add_f32_e32 v71, v71, v165
	v_add_f32_e32 v72, v72, v166
	v_add_f32_e32 v73, v73, v167
	v_mul_f32_e32 v102, 0xbfb8aa3b, v102
	v_mul_f32_e32 v103, 0xbfb8aa3b, v103
	v_mul_f32_e32 v104, 0xbfb8aa3b, v104
	v_mul_f32_e32 v105, 0xbfb8aa3b, v105
	v_mul_f32_e32 v70, 0xbfb8aa3b, v70
	v_mul_f32_e32 v71, 0xbfb8aa3b, v71
	v_mul_f32_e32 v72, 0xbfb8aa3b, v72
	v_mul_f32_e32 v73, 0xbfb8aa3b, v73
	v_exp_f32_e32 v102, v102
	v_exp_f32_e32 v103, v103
	v_exp_f32_e32 v104, v104
	v_exp_f32_e32 v105, v105
	v_exp_f32_e32 v70, v70
	v_exp_f32_e32 v71, v71
	v_exp_f32_e32 v72, v72
	v_exp_f32_e32 v73, v73
	v_add_f32_e32 v102, 1.0, v102
	v_add_f32_e32 v103, 1.0, v103
	v_add_f32_e32 v104, 1.0, v104
	v_add_f32_e32 v105, 1.0, v105
	v_add_f32_e32 v70, 1.0, v70
	v_add_f32_e32 v71, 1.0, v71
	v_add_f32_e32 v72, 1.0, v72
	v_add_f32_e32 v73, 1.0, v73
	v_rcp_f32_e32 v102, v102
	v_rcp_f32_e32 v103, v103
	v_rcp_f32_e32 v104, v104
	v_rcp_f32_e32 v105, v105
	v_rcp_f32_e32 v70, v70
	v_rcp_f32_e32 v71, v71
	v_rcp_f32_e32 v72, v72
	v_rcp_f32_e32 v73, v73
	v_add_f32_e32 v38, v38, v168
	v_add_f32_e32 v39, v39, v169
	v_add_f32_e32 v40, v40, v170
	v_add_f32_e32 v41, v41, v171
	v_add_f32_e32 v6, v6, v172
	v_add_f32_e32 v7, v7, v173
	v_add_f32_e32 v8, v8, v174
	v_add_f32_e32 v9, v9, v175
	v_mul_f32_e32 v38, 0xbfb8aa3b, v38
	v_mul_f32_e32 v39, 0xbfb8aa3b, v39
	v_mul_f32_e32 v40, 0xbfb8aa3b, v40
	v_mul_f32_e32 v41, 0xbfb8aa3b, v41
	v_mul_f32_e32 v6, 0xbfb8aa3b, v6
	v_mul_f32_e32 v7, 0xbfb8aa3b, v7
	v_mul_f32_e32 v8, 0xbfb8aa3b, v8
	v_mul_f32_e32 v9, 0xbfb8aa3b, v9
	v_exp_f32_e32 v38, v38
	v_exp_f32_e32 v39, v39
	v_exp_f32_e32 v40, v40
	v_exp_f32_e32 v41, v41
	v_exp_f32_e32 v6, v6
	v_exp_f32_e32 v7, v7
	v_exp_f32_e32 v8, v8
	v_exp_f32_e32 v9, v9
	v_add_f32_e32 v38, 1.0, v38
	v_add_f32_e32 v39, 1.0, v39
	v_add_f32_e32 v40, 1.0, v40
	v_add_f32_e32 v41, 1.0, v41
	v_add_f32_e32 v6, 1.0, v6
	v_add_f32_e32 v7, 1.0, v7
	v_add_f32_e32 v8, 1.0, v8
	v_add_f32_e32 v9, 1.0, v9
	v_rcp_f32_e32 v38, v38
	v_rcp_f32_e32 v39, v39
	v_rcp_f32_e32 v40, v40
	v_rcp_f32_e32 v41, v41
	v_rcp_f32_e32 v6, v6
	v_rcp_f32_e32 v7, v7
	v_rcp_f32_e32 v8, v8
	v_rcp_f32_e32 v9, v9
	v_cvt_pk_bf16_f32 v102, v102, v103
	v_cvt_pk_bf16_f32 v103, v104, v105
	v_cvt_pk_bf16_f32 v104, v70, v71
	v_cvt_pk_bf16_f32 v105, v72, v73
	v_cvt_pk_bf16_f32 v38, v38, v39
	v_cvt_pk_bf16_f32 v39, v40, v41
	v_cvt_pk_bf16_f32 v40, v6, v7
	v_cvt_pk_bf16_f32 v41, v8, v9
	v_permlane16_swap_b32_e32 v102, v104
	v_permlane16_swap_b32_e32 v103, v105
	v_permlane16_swap_b32_e32 v38, v40
	v_permlane16_swap_b32_e32 v39, v41
	global_store_dwordx4 v[154:155], v[102:105], off offset:0
	global_store_dwordx4 v[154:155], v[38:41], off offset:256
	s_mul_i32 s42, s52, 176
	v_lshl_add_u64 v[156:157], v[152:153], 0, s[42:43]
	v_add_f32_e32 v98, v98, v160
	v_add_f32_e32 v99, v99, v161
	v_add_f32_e32 v100, v100, v162
	v_add_f32_e32 v101, v101, v163
	v_add_f32_e32 v66, v66, v164
	v_add_f32_e32 v67, v67, v165
	v_add_f32_e32 v68, v68, v166
	v_add_f32_e32 v69, v69, v167
	v_mul_f32_e32 v98, 0xbfb8aa3b, v98
	v_mul_f32_e32 v99, 0xbfb8aa3b, v99
	v_mul_f32_e32 v100, 0xbfb8aa3b, v100
	v_mul_f32_e32 v101, 0xbfb8aa3b, v101
	v_mul_f32_e32 v66, 0xbfb8aa3b, v66
	v_mul_f32_e32 v67, 0xbfb8aa3b, v67
	v_mul_f32_e32 v68, 0xbfb8aa3b, v68
	v_mul_f32_e32 v69, 0xbfb8aa3b, v69
	v_exp_f32_e32 v98, v98
	v_exp_f32_e32 v99, v99
	v_exp_f32_e32 v100, v100
	v_exp_f32_e32 v101, v101
	v_exp_f32_e32 v66, v66
	v_exp_f32_e32 v67, v67
	v_exp_f32_e32 v68, v68
	v_exp_f32_e32 v69, v69
	v_add_f32_e32 v98, 1.0, v98
	v_add_f32_e32 v99, 1.0, v99
	v_add_f32_e32 v100, 1.0, v100
	v_add_f32_e32 v101, 1.0, v101
	v_add_f32_e32 v66, 1.0, v66
	v_add_f32_e32 v67, 1.0, v67
	v_add_f32_e32 v68, 1.0, v68
	v_add_f32_e32 v69, 1.0, v69
	v_rcp_f32_e32 v98, v98
	v_rcp_f32_e32 v99, v99
	v_rcp_f32_e32 v100, v100
	v_rcp_f32_e32 v101, v101
	v_rcp_f32_e32 v66, v66
	v_rcp_f32_e32 v67, v67
	v_rcp_f32_e32 v68, v68
	v_rcp_f32_e32 v69, v69
	v_add_f32_e32 v34, v34, v168
	v_add_f32_e32 v35, v35, v169
	v_add_f32_e32 v36, v36, v170
	v_add_f32_e32 v37, v37, v171
	v_add_f32_e32 v2, v2, v172
	v_add_f32_e32 v3, v3, v173
	v_add_f32_e32 v4, v4, v174
	v_add_f32_e32 v5, v5, v175
	v_mul_f32_e32 v34, 0xbfb8aa3b, v34
	v_mul_f32_e32 v35, 0xbfb8aa3b, v35
	v_mul_f32_e32 v36, 0xbfb8aa3b, v36
	v_mul_f32_e32 v37, 0xbfb8aa3b, v37
	v_mul_f32_e32 v2, 0xbfb8aa3b, v2
	v_mul_f32_e32 v3, 0xbfb8aa3b, v3
	v_mul_f32_e32 v4, 0xbfb8aa3b, v4
	v_mul_f32_e32 v5, 0xbfb8aa3b, v5
	v_exp_f32_e32 v34, v34
	v_exp_f32_e32 v35, v35
	v_exp_f32_e32 v36, v36
	v_exp_f32_e32 v37, v37
	v_exp_f32_e32 v2, v2
	v_exp_f32_e32 v3, v3
	v_exp_f32_e32 v4, v4
	v_exp_f32_e32 v5, v5
	v_add_f32_e32 v34, 1.0, v34
	v_add_f32_e32 v35, 1.0, v35
	v_add_f32_e32 v36, 1.0, v36
	v_add_f32_e32 v37, 1.0, v37
	v_add_f32_e32 v2, 1.0, v2
	v_add_f32_e32 v3, 1.0, v3
	v_add_f32_e32 v4, 1.0, v4
	v_add_f32_e32 v5, 1.0, v5
	v_rcp_f32_e32 v34, v34
	v_rcp_f32_e32 v35, v35
	v_rcp_f32_e32 v36, v36
	v_rcp_f32_e32 v37, v37
	v_rcp_f32_e32 v2, v2
	v_rcp_f32_e32 v3, v3
	v_rcp_f32_e32 v4, v4
	v_rcp_f32_e32 v5, v5
	v_cvt_pk_bf16_f32 v98, v98, v99
	v_cvt_pk_bf16_f32 v99, v100, v101
	v_cvt_pk_bf16_f32 v100, v66, v67
	v_cvt_pk_bf16_f32 v101, v68, v69
	v_cvt_pk_bf16_f32 v34, v34, v35
	v_cvt_pk_bf16_f32 v35, v36, v37
	v_cvt_pk_bf16_f32 v36, v2, v3
	v_cvt_pk_bf16_f32 v37, v4, v5
	v_permlane16_swap_b32_e32 v98, v100
	v_permlane16_swap_b32_e32 v99, v101
	v_permlane16_swap_b32_e32 v34, v36
	v_permlane16_swap_b32_e32 v35, v37
	global_store_dwordx4 v[156:157], v[98:101], off offset:0
	global_store_dwordx4 v[156:157], v[34:37], off offset:256
	s_branch .LBB0_986
.Lipf_plain:
	v_mov_b32_e32 v154, v152
	v_mov_b32_e32 v155, v153
	v_cvt_pk_bf16_f32 v130, v130, v131
	v_cvt_pk_bf16_f32 v131, v132, v133
	v_cvt_pk_bf16_f32 v132, v94, v95
	v_cvt_pk_bf16_f32 v133, v96, v97
	v_cvt_pk_bf16_f32 v62, v62, v63
	v_cvt_pk_bf16_f32 v63, v64, v65
	v_cvt_pk_bf16_f32 v64, v30, v31
	v_cvt_pk_bf16_f32 v65, v32, v33
	v_permlane16_swap_b32_e32 v130, v132
	v_permlane16_swap_b32_e32 v131, v133
	v_permlane16_swap_b32_e32 v62, v64
	v_permlane16_swap_b32_e32 v63, v65
	global_store_dwordx4 v[154:155], v[130:133], off offset:0
	global_store_dwordx4 v[154:155], v[62:65], off offset:256
	s_mul_i32 s42, s52, 16
	v_lshl_add_u64 v[156:157], v[152:153], 0, s[42:43]
	v_cvt_pk_bf16_f32 v126, v126, v127
	v_cvt_pk_bf16_f32 v127, v128, v129
	v_cvt_pk_bf16_f32 v128, v90, v91
	v_cvt_pk_bf16_f32 v129, v92, v93
	v_cvt_pk_bf16_f32 v58, v58, v59
	v_cvt_pk_bf16_f32 v59, v60, v61
	v_cvt_pk_bf16_f32 v60, v26, v27
	v_cvt_pk_bf16_f32 v61, v28, v29
	v_permlane16_swap_b32_e32 v126, v128
	v_permlane16_swap_b32_e32 v127, v129
	v_permlane16_swap_b32_e32 v58, v60
	v_permlane16_swap_b32_e32 v59, v61
	global_store_dwordx4 v[156:157], v[126:129], off offset:0
	global_store_dwordx4 v[156:157], v[58:61], off offset:256
	s_mul_i32 s42, s52, 32
	v_lshl_add_u64 v[154:155], v[152:153], 0, s[42:43]
	v_cvt_pk_bf16_f32 v122, v122, v123
	v_cvt_pk_bf16_f32 v123, v124, v125
	v_cvt_pk_bf16_f32 v124, v86, v87
	v_cvt_pk_bf16_f32 v125, v88, v89
	v_cvt_pk_bf16_f32 v54, v54, v55
	v_cvt_pk_bf16_f32 v55, v56, v57
	v_cvt_pk_bf16_f32 v56, v22, v23
	v_cvt_pk_bf16_f32 v57, v24, v25
	v_permlane16_swap_b32_e32 v122, v124
	v_permlane16_swap_b32_e32 v123, v125
	v_permlane16_swap_b32_e32 v54, v56
	v_permlane16_swap_b32_e32 v55, v57
	global_store_dwordx4 v[154:155], v[122:125], off offset:0
	global_store_dwordx4 v[154:155], v[54:57], off offset:256
	s_mul_i32 s42, s52, 48
	v_lshl_add_u64 v[156:157], v[152:153], 0, s[42:43]
	v_cvt_pk_bf16_f32 v118, v118, v119
	v_cvt_pk_bf16_f32 v119, v120, v121
	v_cvt_pk_bf16_f32 v120, v82, v83
	v_cvt_pk_bf16_f32 v121, v84, v85
	v_cvt_pk_bf16_f32 v50, v50, v51
	v_cvt_pk_bf16_f32 v51, v52, v53
	v_cvt_pk_bf16_f32 v52, v18, v19
	v_cvt_pk_bf16_f32 v53, v20, v21
	v_permlane16_swap_b32_e32 v118, v120
	v_permlane16_swap_b32_e32 v119, v121
	v_permlane16_swap_b32_e32 v50, v52
	v_permlane16_swap_b32_e32 v51, v53
	global_store_dwordx4 v[156:157], v[118:121], off offset:0
	global_store_dwordx4 v[156:157], v[50:53], off offset:256
	s_mul_i32 s42, s52, 128
	v_lshl_add_u64 v[154:155], v[152:153], 0, s[42:43]
	v_cvt_pk_bf16_f32 v114, v114, v115
	v_cvt_pk_bf16_f32 v115, v116, v117
	v_cvt_pk_bf16_f32 v116, v78, v79
	v_cvt_pk_bf16_f32 v117, v80, v81
	v_cvt_pk_bf16_f32 v46, v46, v47
	v_cvt_pk_bf16_f32 v47, v48, v49
	v_cvt_pk_bf16_f32 v48, v14, v15
	v_cvt_pk_bf16_f32 v49, v16, v17
	v_permlane16_swap_b32_e32 v114, v116
	v_permlane16_swap_b32_e32 v115, v117
	v_permlane16_swap_b32_e32 v46, v48
	v_permlane16_swap_b32_e32 v47, v49
	global_store_dwordx4 v[154:155], v[114:117], off offset:0
	global_store_dwordx4 v[154:155], v[46:49], off offset:256
	s_mul_i32 s42, s52, 144
	v_lshl_add_u64 v[156:157], v[152:153], 0, s[42:43]
	v_cvt_pk_bf16_f32 v106, v106, v107
	v_cvt_pk_bf16_f32 v107, v108, v109
	v_cvt_pk_bf16_f32 v108, v74, v75
	v_cvt_pk_bf16_f32 v109, v76, v77
	v_cvt_pk_bf16_f32 v42, v42, v43
	v_cvt_pk_bf16_f32 v43, v44, v45
	v_cvt_pk_bf16_f32 v44, v10, v11
	v_cvt_pk_bf16_f32 v45, v12, v13
	v_permlane16_swap_b32_e32 v106, v108
	v_permlane16_swap_b32_e32 v107, v109
	v_permlane16_swap_b32_e32 v42, v44
	v_permlane16_swap_b32_e32 v43, v45
	global_store_dwordx4 v[156:157], v[106:109], off offset:0
	global_store_dwordx4 v[156:157], v[42:45], off offset:256
	s_mul_i32 s42, s52, 160
	v_lshl_add_u64 v[154:155], v[152:153], 0, s[42:43]
	v_cvt_pk_bf16_f32 v102, v102, v103
	v_cvt_pk_bf16_f32 v103, v104, v105
	v_cvt_pk_bf16_f32 v104, v70, v71
	v_cvt_pk_bf16_f32 v105, v72, v73
	v_cvt_pk_bf16_f32 v38, v38, v39
	v_cvt_pk_bf16_f32 v39, v40, v41
	v_cvt_pk_bf16_f32 v40, v6, v7
	v_cvt_pk_bf16_f32 v41, v8, v9
	v_permlane16_swap_b32_e32 v102, v104
	v_permlane16_swap_b32_e32 v103, v105
	v_permlane16_swap_b32_e32 v38, v40
	v_permlane16_swap_b32_e32 v39, v41
	global_store_dwordx4 v[154:155], v[102:105], off offset:0
	global_store_dwordx4 v[154:155], v[38:41], off offset:256
	s_mul_i32 s42, s52, 176
	v_lshl_add_u64 v[156:157], v[152:153], 0, s[42:43]
	v_cvt_pk_bf16_f32 v98, v98, v99
	v_cvt_pk_bf16_f32 v99, v100, v101
	v_cvt_pk_bf16_f32 v100, v66, v67
	v_cvt_pk_bf16_f32 v101, v68, v69
	v_cvt_pk_bf16_f32 v34, v34, v35
	v_cvt_pk_bf16_f32 v35, v36, v37
	v_cvt_pk_bf16_f32 v36, v2, v3
	v_cvt_pk_bf16_f32 v37, v4, v5
	v_permlane16_swap_b32_e32 v98, v100
	v_permlane16_swap_b32_e32 v99, v101
	v_permlane16_swap_b32_e32 v34, v36
	v_permlane16_swap_b32_e32 v35, v37
	global_store_dwordx4 v[156:157], v[98:101], off offset:0
	global_store_dwordx4 v[156:157], v[34:37], off offset:256
	s_branch .LBB0_986
.Lipg_11:
	s_cmpk_gt_i32 s81, 0x7f
	s_cbranch_scc1 .Lipf_slow
	s_and_b32 s0, s81, 15
	s_cmp_eq_u32 s0, 15
	s_cbranch_scc1 .Lipf_slow
	s_mov_b32 s44, 0xa180000
	s_mov_b32 s45, 0x548
	s_mov_b32 s52, 0xc00
	s_mov_b32 s54, 0x10300000
	s_mov_b32 s60, 0xb50
	s_mov_b32 s62, 0x400
	s_mov_b32 s63, 0xb48
	s_mov_b32 s56, 0xb50
	s_mov_b32 s53, 0x7fffffff
	s_mov_b32 s57, 0x7fffffff
	s_mov_b32 s82, 0x1
	s_branch .Lipg_common
.Lipg_13:
	s_mov_b32 s44, 0x10300000
	s_mov_b32 s45, 0xb50
	s_mov_b32 s52, 0x400
	s_mov_b32 s54, 0x12380000
	s_mov_b32 s60, 0xd50
	s_mov_b32 s62, 0x1000
	s_mov_b32 s63, 0xd50
	s_mov_b32 s56, 0xd50
	s_mov_b32 s53, 0xd50
	s_mov_b32 s57, 0x7fffffff
	s_mov_b32 s82, 0x0
	s_branch .Lipg_common
.Lipg_21:
	s_mov_b32 s44, 0x12380000
	s_mov_b32 s45, 0xd50
	s_mov_b32 s52, 0x1000
	s_mov_b32 s54, 0x0
	s_mov_b32 s60, 0x0
	s_mov_b32 s62, 0x0
	s_mov_b32 s63, 0x1550
	s_mov_b32 s56, 0x7fffffff
	s_mov_b32 s53, 0x0
	s_mov_b32 s57, 0x1550
	s_mov_b32 s82, 0x0
.Lipg_common:
	s_lshl_b32 s83, s80, 8
	s_lshl_b32 s87, s81, 8
	s_mov_b32 s43, 0
	v_add_u32_e32 v176, s87, v150
	v_lshrrev_b32_e32 v178, 4, v219
	v_and_b32_e32 v179, 1, v178
	v_lshrrev_b32_e32 v178, 1, v178
	v_lshl_add_u32 v180, v179, 1, v178
	v_bfe_u32 v178, v211, 6, 2
	v_lshlrev_b32_e32 v178, 5, v178
	v_lshl_add_u32 v181, v180, 3, v178
	v_add_u32_e32 v181, s83, v181
	v_readfirstlane_b32 s88, v178
	v_mov_b32_e32 v194, s62
	v_mov_b32_e32 v195, s52
	v_cmp_gt_u32_e32 vcc, s63, v181
	v_cmp_le_u32_e64 s[48:49], s56, v181
	v_subrev_u32_e32 v192, s45, v181
	v_lshl_add_u32 v192, v192, 1, s44
	v_subrev_u32_e32 v193, s60, v181
	v_lshl_add_u32 v193, v193, 1, s54
	v_cndmask_b32_e32 v182, v193, v192, vcc
	v_cndmask_b32_e32 v186, v194, v195, vcc
	v_mov_b32_e32 v183, 0
	s_or_b64 s[48:49], s[48:49], vcc
	v_mad_u64_u32 v[188:189], s[58:59], v176, v186, v[182:183]
	v_lshl_add_u64 v[188:189], v[188:189], 0, s[12:13]
	v_add_u32_e32 v178, 0x80, v181
	v_cmp_gt_u32_e32 vcc, s63, v178
	v_cmp_le_u32_e64 s[50:51], s56, v178
	v_subrev_u32_e32 v192, s45, v178
	v_lshl_add_u32 v192, v192, 1, s44
	v_subrev_u32_e32 v193, s60, v178
	v_lshl_add_u32 v193, v193, 1, s54
	v_cndmask_b32_e32 v184, v193, v192, vcc
	v_cndmask_b32_e32 v187, v194, v195, vcc
	v_mov_b32_e32 v185, 0
	s_or_b64 s[50:51], s[50:51], vcc
	v_mad_u64_u32 v[190:191], s[58:59], v176, v187, v[184:185]
	v_lshl_add_u64 v[190:191], v[190:191], 0, s[12:13]
	s_add_u32 s88, s88, s83
	s_add_u32 s0, s88, 0
	s_cmp_ge_u32 s0, s53
	s_cselect_b32 s89, 1, 0
	s_cmp_lt_u32 s0, s57
	s_cselect_b32 s89, s89, 0
	s_add_u32 s0, s88, 16
	s_cmp_ge_u32 s0, s53
	s_cselect_b32 s90, 1, 0
	s_cmp_lt_u32 s0, s57
	s_cselect_b32 s90, s90, 0
	s_add_u32 s0, s88, 128
	s_cmp_ge_u32 s0, s53
	s_cselect_b32 s91, 1, 0
	s_cmp_lt_u32 s0, s57
	s_cselect_b32 s91, s91, 0
	s_add_u32 s0, s88, 144
	s_cmp_ge_u32 s0, s53
	s_cselect_b32 s92, 1, 0
	s_cmp_lt_u32 s0, s57
	s_cselect_b32 s92, s92, 0
	v_add_u32_e32 v178, s83, v135
	v_add_u32_e32 v178, 0xfffff2b0, v178
	v_ashrrev_i32_e32 v179, 31, v178
	v_lshl_add_u64 v[178:179], v[178:179], 2, s[10:11]
	s_cmp_eq_u32 s89, 0
	s_cbranch_scc1 .Lipg_nb0
	global_load_dwordx4 v[160:163], v[178:179], off offset:0
.Lipg_nb0:
	s_cmp_eq_u32 s90, 0
	s_cbranch_scc1 .Lipg_nb1
	global_load_dwordx4 v[164:167], v[178:179], off offset:64
.Lipg_nb1:
	s_cmp_eq_u32 s91, 0
	s_cbranch_scc1 .Lipg_nb2
	global_load_dwordx4 v[168:171], v[178:179], off offset:512
.Lipg_nb2:
	s_cmp_eq_u32 s92, 0
	s_cbranch_scc1 .Lipg_nb3
	global_load_dwordx4 v[172:175], v[178:179], off offset:576
.Lipg_nb3:
	s_waitcnt vmcnt(0)
	s_nop 7
	s_cmp_eq_u32 s89, 0
	s_cbranch_scc1 .Lipg_ns0
	v_add_f32_e32 v130, v130, v160
	v_add_f32_e32 v131, v131, v161
	v_add_f32_e32 v132, v132, v162
	v_add_f32_e32 v133, v133, v163
	v_add_f32_e32 v126, v126, v160
	v_add_f32_e32 v127, v127, v161
	v_add_f32_e32 v128, v128, v162
	v_add_f32_e32 v129, v129, v163
	v_mul_f32_e32 v130, 0xbfb8aa3b, v130
	v_mul_f32_e32 v131, 0xbfb8aa3b, v131
	v_mul_f32_e32 v132, 0xbfb8aa3b, v132
	v_mul_f32_e32 v133, 0xbfb8aa3b, v133
	v_mul_f32_e32 v126, 0xbfb8aa3b, v126
	v_mul_f32_e32 v127, 0xbfb8aa3b, v127
	v_mul_f32_e32 v128, 0xbfb8aa3b, v128
	v_mul_f32_e32 v129, 0xbfb8aa3b, v129
	v_exp_f32_e32 v130, v130
	v_exp_f32_e32 v131, v131
	v_exp_f32_e32 v132, v132
	v_exp_f32_e32 v133, v133
	v_exp_f32_e32 v126, v126
	v_exp_f32_e32 v127, v127
	v_exp_f32_e32 v128, v128
	v_exp_f32_e32 v129, v129
	v_add_f32_e32 v130, 1.0, v130
	v_add_f32_e32 v131, 1.0, v131
	v_add_f32_e32 v132, 1.0, v132
	v_add_f32_e32 v133, 1.0, v133
	v_add_f32_e32 v126, 1.0, v126
	v_add_f32_e32 v127, 1.0, v127
	v_add_f32_e32 v128, 1.0, v128
	v_add_f32_e32 v129, 1.0, v129
	v_rcp_f32_e32 v130, v130
	v_rcp_f32_e32 v131, v131
	v_rcp_f32_e32 v132, v132
	v_rcp_f32_e32 v133, v133
	v_rcp_f32_e32 v126, v126
	v_rcp_f32_e32 v127, v127
	v_rcp_f32_e32 v128, v128
	v_rcp_f32_e32 v129, v129
	v_add_f32_e32 v122, v122, v160
	v_add_f32_e32 v123, v123, v161
	v_add_f32_e32 v124, v124, v162
	v_add_f32_e32 v125, v125, v163
	v_add_f32_e32 v118, v118, v160
	v_add_f32_e32 v119, v119, v161
	v_add_f32_e32 v120, v120, v162
	v_add_f32_e32 v121, v121, v163
	v_mul_f32_e32 v122, 0xbfb8aa3b, v122
	v_mul_f32_e32 v123, 0xbfb8aa3b, v123
	v_mul_f32_e32 v124, 0xbfb8aa3b, v124
	v_mul_f32_e32 v125, 0xbfb8aa3b, v125
	v_mul_f32_e32 v118, 0xbfb8aa3b, v118
	v_mul_f32_e32 v119, 0xbfb8aa3b, v119
	v_mul_f32_e32 v120, 0xbfb8aa3b, v120
	v_mul_f32_e32 v121, 0xbfb8aa3b, v121
	v_exp_f32_e32 v122, v122
	v_exp_f32_e32 v123, v123
	v_exp_f32_e32 v124, v124
	v_exp_f32_e32 v125, v125
	v_exp_f32_e32 v118, v118
	v_exp_f32_e32 v119, v119
	v_exp_f32_e32 v120, v120
	v_exp_f32_e32 v121, v121
	v_add_f32_e32 v122, 1.0, v122
	v_add_f32_e32 v123, 1.0, v123
	v_add_f32_e32 v124, 1.0, v124
	v_add_f32_e32 v125, 1.0, v125
	v_add_f32_e32 v118, 1.0, v118
	v_add_f32_e32 v119, 1.0, v119
	v_add_f32_e32 v120, 1.0, v120
	v_add_f32_e32 v121, 1.0, v121
	v_rcp_f32_e32 v122, v122
	v_rcp_f32_e32 v123, v123
	v_rcp_f32_e32 v124, v124
	v_rcp_f32_e32 v125, v125
	v_rcp_f32_e32 v118, v118
	v_rcp_f32_e32 v119, v119
	v_rcp_f32_e32 v120, v120
	v_rcp_f32_e32 v121, v121
	v_add_f32_e32 v114, v114, v160
	v_add_f32_e32 v115, v115, v161
	v_add_f32_e32 v116, v116, v162
	v_add_f32_e32 v117, v117, v163
	v_add_f32_e32 v106, v106, v160
	v_add_f32_e32 v107, v107, v161
	v_add_f32_e32 v108, v108, v162
	v_add_f32_e32 v109, v109, v163
	v_mul_f32_e32 v114, 0xbfb8aa3b, v114
	v_mul_f32_e32 v115, 0xbfb8aa3b, v115
	v_mul_f32_e32 v116, 0xbfb8aa3b, v116
	v_mul_f32_e32 v117, 0xbfb8aa3b, v117
	v_mul_f32_e32 v106, 0xbfb8aa3b, v106
	v_mul_f32_e32 v107, 0xbfb8aa3b, v107
	v_mul_f32_e32 v108, 0xbfb8aa3b, v108
	v_mul_f32_e32 v109, 0xbfb8aa3b, v109
	v_exp_f32_e32 v114, v114
	v_exp_f32_e32 v115, v115
	v_exp_f32_e32 v116, v116
	v_exp_f32_e32 v117, v117
	v_exp_f32_e32 v106, v106
	v_exp_f32_e32 v107, v107
	v_exp_f32_e32 v108, v108
	v_exp_f32_e32 v109, v109
	v_add_f32_e32 v114, 1.0, v114
	v_add_f32_e32 v115, 1.0, v115
	v_add_f32_e32 v116, 1.0, v116
	v_add_f32_e32 v117, 1.0, v117
	v_add_f32_e32 v106, 1.0, v106
	v_add_f32_e32 v107, 1.0, v107
	v_add_f32_e32 v108, 1.0, v108
	v_add_f32_e32 v109, 1.0, v109
	v_rcp_f32_e32 v114, v114
	v_rcp_f32_e32 v115, v115
	v_rcp_f32_e32 v116, v116
	v_rcp_f32_e32 v117, v117
	v_rcp_f32_e32 v106, v106
	v_rcp_f32_e32 v107, v107
	v_rcp_f32_e32 v108, v108
	v_rcp_f32_e32 v109, v109
	v_add_f32_e32 v102, v102, v160
	v_add_f32_e32 v103, v103, v161
	v_add_f32_e32 v104, v104, v162
	v_add_f32_e32 v105, v105, v163
	v_add_f32_e32 v98, v98, v160
	v_add_f32_e32 v99, v99, v161
	v_add_f32_e32 v100, v100, v162
	v_add_f32_e32 v101, v101, v163
	v_mul_f32_e32 v102, 0xbfb8aa3b, v102
	v_mul_f32_e32 v103, 0xbfb8aa3b, v103
	v_mul_f32_e32 v104, 0xbfb8aa3b, v104
	v_mul_f32_e32 v105, 0xbfb8aa3b, v105
	v_mul_f32_e32 v98, 0xbfb8aa3b, v98
	v_mul_f32_e32 v99, 0xbfb8aa3b, v99
	v_mul_f32_e32 v100, 0xbfb8aa3b, v100
	v_mul_f32_e32 v101, 0xbfb8aa3b, v101
	v_exp_f32_e32 v102, v102
	v_exp_f32_e32 v103, v103
	v_exp_f32_e32 v104, v104
	v_exp_f32_e32 v105, v105
	v_exp_f32_e32 v98, v98
	v_exp_f32_e32 v99, v99
	v_exp_f32_e32 v100, v100
	v_exp_f32_e32 v101, v101
	v_add_f32_e32 v102, 1.0, v102
	v_add_f32_e32 v103, 1.0, v103
	v_add_f32_e32 v104, 1.0, v104
	v_add_f32_e32 v105, 1.0, v105
	v_add_f32_e32 v98, 1.0, v98
	v_add_f32_e32 v99, 1.0, v99
	v_add_f32_e32 v100, 1.0, v100
	v_add_f32_e32 v101, 1.0, v101
	v_rcp_f32_e32 v102, v102
	v_rcp_f32_e32 v103, v103
	v_rcp_f32_e32 v104, v104
	v_rcp_f32_e32 v105, v105
	v_rcp_f32_e32 v98, v98
	v_rcp_f32_e32 v99, v99
	v_rcp_f32_e32 v100, v100
	v_rcp_f32_e32 v101, v101
	s_nop 0
.Lipg_ns0:
	s_cmp_eq_u32 s90, 0
	s_cbranch_scc1 .Lipg_ns1
	v_add_f32_e32 v94, v94, v164
	v_add_f32_e32 v95, v95, v165
	v_add_f32_e32 v96, v96, v166
	v_add_f32_e32 v97, v97, v167
	v_add_f32_e32 v90, v90, v164
	v_add_f32_e32 v91, v91, v165
	v_add_f32_e32 v92, v92, v166
	v_add_f32_e32 v93, v93, v167
	v_mul_f32_e32 v94, 0xbfb8aa3b, v94
	v_mul_f32_e32 v95, 0xbfb8aa3b, v95
	v_mul_f32_e32 v96, 0xbfb8aa3b, v96
	v_mul_f32_e32 v97, 0xbfb8aa3b, v97
	v_mul_f32_e32 v90, 0xbfb8aa3b, v90
	v_mul_f32_e32 v91, 0xbfb8aa3b, v91
	v_mul_f32_e32 v92, 0xbfb8aa3b, v92
	v_mul_f32_e32 v93, 0xbfb8aa3b, v93
	v_exp_f32_e32 v94, v94
	v_exp_f32_e32 v95, v95
	v_exp_f32_e32 v96, v96
	v_exp_f32_e32 v97, v97
	v_exp_f32_e32 v90, v90
	v_exp_f32_e32 v91, v91
	v_exp_f32_e32 v92, v92
	v_exp_f32_e32 v93, v93
	v_add_f32_e32 v94, 1.0, v94
	v_add_f32_e32 v95, 1.0, v95
	v_add_f32_e32 v96, 1.0, v96
	v_add_f32_e32 v97, 1.0, v97
	v_add_f32_e32 v90, 1.0, v90
	v_add_f32_e32 v91, 1.0, v91
	v_add_f32_e32 v92, 1.0, v92
	v_add_f32_e32 v93, 1.0, v93
	v_rcp_f32_e32 v94, v94
	v_rcp_f32_e32 v95, v95
	v_rcp_f32_e32 v96, v96
	v_rcp_f32_e32 v97, v97
	v_rcp_f32_e32 v90, v90
	v_rcp_f32_e32 v91, v91
	v_rcp_f32_e32 v92, v92
	v_rcp_f32_e32 v93, v93
	v_add_f32_e32 v86, v86, v164
	v_add_f32_e32 v87, v87, v165
	v_add_f32_e32 v88, v88, v166
	v_add_f32_e32 v89, v89, v167
	v_add_f32_e32 v82, v82, v164
	v_add_f32_e32 v83, v83, v165
	v_add_f32_e32 v84, v84, v166
	v_add_f32_e32 v85, v85, v167
	v_mul_f32_e32 v86, 0xbfb8aa3b, v86
	v_mul_f32_e32 v87, 0xbfb8aa3b, v87
	v_mul_f32_e32 v88, 0xbfb8aa3b, v88
	v_mul_f32_e32 v89, 0xbfb8aa3b, v89
	v_mul_f32_e32 v82, 0xbfb8aa3b, v82
	v_mul_f32_e32 v83, 0xbfb8aa3b, v83
	v_mul_f32_e32 v84, 0xbfb8aa3b, v84
	v_mul_f32_e32 v85, 0xbfb8aa3b, v85
	v_exp_f32_e32 v86, v86
	v_exp_f32_e32 v87, v87
	v_exp_f32_e32 v88, v88
	v_exp_f32_e32 v89, v89
	v_exp_f32_e32 v82, v82
	v_exp_f32_e32 v83, v83
	v_exp_f32_e32 v84, v84
	v_exp_f32_e32 v85, v85
	v_add_f32_e32 v86, 1.0, v86
	v_add_f32_e32 v87, 1.0, v87
	v_add_f32_e32 v88, 1.0, v88
	v_add_f32_e32 v89, 1.0, v89
	v_add_f32_e32 v82, 1.0, v82
	v_add_f32_e32 v83, 1.0, v83
	v_add_f32_e32 v84, 1.0, v84
	v_add_f32_e32 v85, 1.0, v85
	v_rcp_f32_e32 v86, v86
	v_rcp_f32_e32 v87, v87
	v_rcp_f32_e32 v88, v88
	v_rcp_f32_e32 v89, v89
	v_rcp_f32_e32 v82, v82
	v_rcp_f32_e32 v83, v83
	v_rcp_f32_e32 v84, v84
	v_rcp_f32_e32 v85, v85
	v_add_f32_e32 v78, v78, v164
	v_add_f32_e32 v79, v79, v165
	v_add_f32_e32 v80, v80, v166
	v_add_f32_e32 v81, v81, v167
	v_add_f32_e32 v74, v74, v164
	v_add_f32_e32 v75, v75, v165
	v_add_f32_e32 v76, v76, v166
	v_add_f32_e32 v77, v77, v167
	v_mul_f32_e32 v78, 0xbfb8aa3b, v78
	v_mul_f32_e32 v79, 0xbfb8aa3b, v79
	v_mul_f32_e32 v80, 0xbfb8aa3b, v80
	v_mul_f32_e32 v81, 0xbfb8aa3b, v81
	v_mul_f32_e32 v74, 0xbfb8aa3b, v74
	v_mul_f32_e32 v75, 0xbfb8aa3b, v75
	v_mul_f32_e32 v76, 0xbfb8aa3b, v76
	v_mul_f32_e32 v77, 0xbfb8aa3b, v77
	v_exp_f32_e32 v78, v78
	v_exp_f32_e32 v79, v79
	v_exp_f32_e32 v80, v80
	v_exp_f32_e32 v81, v81
	v_exp_f32_e32 v74, v74
	v_exp_f32_e32 v75, v75
	v_exp_f32_e32 v76, v76
	v_exp_f32_e32 v77, v77
	v_add_f32_e32 v78, 1.0, v78
	v_add_f32_e32 v79, 1.0, v79
	v_add_f32_e32 v80, 1.0, v80
	v_add_f32_e32 v81, 1.0, v81
	v_add_f32_e32 v74, 1.0, v74
	v_add_f32_e32 v75, 1.0, v75
	v_add_f32_e32 v76, 1.0, v76
	v_add_f32_e32 v77, 1.0, v77
	v_rcp_f32_e32 v78, v78
	v_rcp_f32_e32 v79, v79
	v_rcp_f32_e32 v80, v80
	v_rcp_f32_e32 v81, v81
	v_rcp_f32_e32 v74, v74
	v_rcp_f32_e32 v75, v75
	v_rcp_f32_e32 v76, v76
	v_rcp_f32_e32 v77, v77
	v_add_f32_e32 v70, v70, v164
	v_add_f32_e32 v71, v71, v165
	v_add_f32_e32 v72, v72, v166
	v_add_f32_e32 v73, v73, v167
	v_add_f32_e32 v66, v66, v164
	v_add_f32_e32 v67, v67, v165
	v_add_f32_e32 v68, v68, v166
	v_add_f32_e32 v69, v69, v167
	v_mul_f32_e32 v70, 0xbfb8aa3b, v70
	v_mul_f32_e32 v71, 0xbfb8aa3b, v71
	v_mul_f32_e32 v72, 0xbfb8aa3b, v72
	v_mul_f32_e32 v73, 0xbfb8aa3b, v73
	v_mul_f32_e32 v66, 0xbfb8aa3b, v66
	v_mul_f32_e32 v67, 0xbfb8aa3b, v67
	v_mul_f32_e32 v68, 0xbfb8aa3b, v68
	v_mul_f32_e32 v69, 0xbfb8aa3b, v69
	v_exp_f32_e32 v70, v70
	v_exp_f32_e32 v71, v71
	v_exp_f32_e32 v72, v72
	v_exp_f32_e32 v73, v73
	v_exp_f32_e32 v66, v66
	v_exp_f32_e32 v67, v67
	v_exp_f32_e32 v68, v68
	v_exp_f32_e32 v69, v69
	v_add_f32_e32 v70, 1.0, v70
	v_add_f32_e32 v71, 1.0, v71
	v_add_f32_e32 v72, 1.0, v72
	v_add_f32_e32 v73, 1.0, v73
	v_add_f32_e32 v66, 1.0, v66
	v_add_f32_e32 v67, 1.0, v67
	v_add_f32_e32 v68, 1.0, v68
	v_add_f32_e32 v69, 1.0, v69
	v_rcp_f32_e32 v70, v70
	v_rcp_f32_e32 v71, v71
	v_rcp_f32_e32 v72, v72
	v_rcp_f32_e32 v73, v73
	v_rcp_f32_e32 v66, v66
	v_rcp_f32_e32 v67, v67
	v_rcp_f32_e32 v68, v68
	v_rcp_f32_e32 v69, v69
	s_nop 0
.Lipg_ns1:
	s_cmp_eq_u32 s91, 0
	s_cbranch_scc1 .Lipg_ns2
	v_add_f32_e32 v62, v62, v168
	v_add_f32_e32 v63, v63, v169
	v_add_f32_e32 v64, v64, v170
	v_add_f32_e32 v65, v65, v171
	v_add_f32_e32 v58, v58, v168
	v_add_f32_e32 v59, v59, v169
	v_add_f32_e32 v60, v60, v170
	v_add_f32_e32 v61, v61, v171
	v_mul_f32_e32 v62, 0xbfb8aa3b, v62
	v_mul_f32_e32 v63, 0xbfb8aa3b, v63
	v_mul_f32_e32 v64, 0xbfb8aa3b, v64
	v_mul_f32_e32 v65, 0xbfb8aa3b, v65
	v_mul_f32_e32 v58, 0xbfb8aa3b, v58
	v_mul_f32_e32 v59, 0xbfb8aa3b, v59
	v_mul_f32_e32 v60, 0xbfb8aa3b, v60
	v_mul_f32_e32 v61, 0xbfb8aa3b, v61
	v_exp_f32_e32 v62, v62
	v_exp_f32_e32 v63, v63
	v_exp_f32_e32 v64, v64
	v_exp_f32_e32 v65, v65
	v_exp_f32_e32 v58, v58
	v_exp_f32_e32 v59, v59
	v_exp_f32_e32 v60, v60
	v_exp_f32_e32 v61, v61
	v_add_f32_e32 v62, 1.0, v62
	v_add_f32_e32 v63, 1.0, v63
	v_add_f32_e32 v64, 1.0, v64
	v_add_f32_e32 v65, 1.0, v65
	v_add_f32_e32 v58, 1.0, v58
	v_add_f32_e32 v59, 1.0, v59
	v_add_f32_e32 v60, 1.0, v60
	v_add_f32_e32 v61, 1.0, v61
	v_rcp_f32_e32 v62, v62
	v_rcp_f32_e32 v63, v63
	v_rcp_f32_e32 v64, v64
	v_rcp_f32_e32 v65, v65
	v_rcp_f32_e32 v58, v58
	v_rcp_f32_e32 v59, v59
	v_rcp_f32_e32 v60, v60
	v_rcp_f32_e32 v61, v61
	v_add_f32_e32 v54, v54, v168
	v_add_f32_e32 v55, v55, v169
	v_add_f32_e32 v56, v56, v170
	v_add_f32_e32 v57, v57, v171
	v_add_f32_e32 v50, v50, v168
	v_add_f32_e32 v51, v51, v169
	v_add_f32_e32 v52, v52, v170
	v_add_f32_e32 v53, v53, v171
	v_mul_f32_e32 v54, 0xbfb8aa3b, v54
	v_mul_f32_e32 v55, 0xbfb8aa3b, v55
	v_mul_f32_e32 v56, 0xbfb8aa3b, v56
	v_mul_f32_e32 v57, 0xbfb8aa3b, v57
	v_mul_f32_e32 v50, 0xbfb8aa3b, v50
	v_mul_f32_e32 v51, 0xbfb8aa3b, v51
	v_mul_f32_e32 v52, 0xbfb8aa3b, v52
	v_mul_f32_e32 v53, 0xbfb8aa3b, v53
	v_exp_f32_e32 v54, v54
	v_exp_f32_e32 v55, v55
	v_exp_f32_e32 v56, v56
	v_exp_f32_e32 v57, v57
	v_exp_f32_e32 v50, v50
	v_exp_f32_e32 v51, v51
	v_exp_f32_e32 v52, v52
	v_exp_f32_e32 v53, v53
	v_add_f32_e32 v54, 1.0, v54
	v_add_f32_e32 v55, 1.0, v55
	v_add_f32_e32 v56, 1.0, v56
	v_add_f32_e32 v57, 1.0, v57
	v_add_f32_e32 v50, 1.0, v50
	v_add_f32_e32 v51, 1.0, v51
	v_add_f32_e32 v52, 1.0, v52
	v_add_f32_e32 v53, 1.0, v53
	v_rcp_f32_e32 v54, v54
	v_rcp_f32_e32 v55, v55
	v_rcp_f32_e32 v56, v56
	v_rcp_f32_e32 v57, v57
	v_rcp_f32_e32 v50, v50
	v_rcp_f32_e32 v51, v51
	v_rcp_f32_e32 v52, v52
	v_rcp_f32_e32 v53, v53
	v_add_f32_e32 v46, v46, v168
	v_add_f32_e32 v47, v47, v169
	v_add_f32_e32 v48, v48, v170
	v_add_f32_e32 v49, v49, v171
	v_add_f32_e32 v42, v42, v168
	v_add_f32_e32 v43, v43, v169
	v_add_f32_e32 v44, v44, v170
	v_add_f32_e32 v45, v45, v171
	v_mul_f32_e32 v46, 0xbfb8aa3b, v46
	v_mul_f32_e32 v47, 0xbfb8aa3b, v47
	v_mul_f32_e32 v48, 0xbfb8aa3b, v48
	v_mul_f32_e32 v49, 0xbfb8aa3b, v49
	v_mul_f32_e32 v42, 0xbfb8aa3b, v42
	v_mul_f32_e32 v43, 0xbfb8aa3b, v43
	v_mul_f32_e32 v44, 0xbfb8aa3b, v44
	v_mul_f32_e32 v45, 0xbfb8aa3b, v45
	v_exp_f32_e32 v46, v46
	v_exp_f32_e32 v47, v47
	v_exp_f32_e32 v48, v48
	v_exp_f32_e32 v49, v49
	v_exp_f32_e32 v42, v42
	v_exp_f32_e32 v43, v43
	v_exp_f32_e32 v44, v44
	v_exp_f32_e32 v45, v45
	v_add_f32_e32 v46, 1.0, v46
	v_add_f32_e32 v47, 1.0, v47
	v_add_f32_e32 v48, 1.0, v48
	v_add_f32_e32 v49, 1.0, v49
	v_add_f32_e32 v42, 1.0, v42
	v_add_f32_e32 v43, 1.0, v43
	v_add_f32_e32 v44, 1.0, v44
	v_add_f32_e32 v45, 1.0, v45
	v_rcp_f32_e32 v46, v46
	v_rcp_f32_e32 v47, v47
	v_rcp_f32_e32 v48, v48
	v_rcp_f32_e32 v49, v49
	v_rcp_f32_e32 v42, v42
	v_rcp_f32_e32 v43, v43
	v_rcp_f32_e32 v44, v44
	v_rcp_f32_e32 v45, v45
	v_add_f32_e32 v38, v38, v168
	v_add_f32_e32 v39, v39, v169
	v_add_f32_e32 v40, v40, v170
	v_add_f32_e32 v41, v41, v171
	v_add_f32_e32 v34, v34, v168
	v_add_f32_e32 v35, v35, v169
	v_add_f32_e32 v36, v36, v170
	v_add_f32_e32 v37, v37, v171
	v_mul_f32_e32 v38, 0xbfb8aa3b, v38
	v_mul_f32_e32 v39, 0xbfb8aa3b, v39
	v_mul_f32_e32 v40, 0xbfb8aa3b, v40
	v_mul_f32_e32 v41, 0xbfb8aa3b, v41
	v_mul_f32_e32 v34, 0xbfb8aa3b, v34
	v_mul_f32_e32 v35, 0xbfb8aa3b, v35
	v_mul_f32_e32 v36, 0xbfb8aa3b, v36
	v_mul_f32_e32 v37, 0xbfb8aa3b, v37
	v_exp_f32_e32 v38, v38
	v_exp_f32_e32 v39, v39
	v_exp_f32_e32 v40, v40
	v_exp_f32_e32 v41, v41
	v_exp_f32_e32 v34, v34
	v_exp_f32_e32 v35, v35
	v_exp_f32_e32 v36, v36
	v_exp_f32_e32 v37, v37
	v_add_f32_e32 v38, 1.0, v38
	v_add_f32_e32 v39, 1.0, v39
	v_add_f32_e32 v40, 1.0, v40
	v_add_f32_e32 v41, 1.0, v41
	v_add_f32_e32 v34, 1.0, v34
	v_add_f32_e32 v35, 1.0, v35
	v_add_f32_e32 v36, 1.0, v36
	v_add_f32_e32 v37, 1.0, v37
	v_rcp_f32_e32 v38, v38
	v_rcp_f32_e32 v39, v39
	v_rcp_f32_e32 v40, v40
	v_rcp_f32_e32 v41, v41
	v_rcp_f32_e32 v34, v34
	v_rcp_f32_e32 v35, v35
	v_rcp_f32_e32 v36, v36
	v_rcp_f32_e32 v37, v37
	s_nop 0
.Lipg_ns2:
	s_cmp_eq_u32 s92, 0
	s_cbranch_scc1 .Lipg_ns3
	v_add_f32_e32 v30, v30, v172
	v_add_f32_e32 v31, v31, v173
	v_add_f32_e32 v32, v32, v174
	v_add_f32_e32 v33, v33, v175
	v_add_f32_e32 v26, v26, v172
	v_add_f32_e32 v27, v27, v173
	v_add_f32_e32 v28, v28, v174
	v_add_f32_e32 v29, v29, v175
	v_mul_f32_e32 v30, 0xbfb8aa3b, v30
	v_mul_f32_e32 v31, 0xbfb8aa3b, v31
	v_mul_f32_e32 v32, 0xbfb8aa3b, v32
	v_mul_f32_e32 v33, 0xbfb8aa3b, v33
	v_mul_f32_e32 v26, 0xbfb8aa3b, v26
	v_mul_f32_e32 v27, 0xbfb8aa3b, v27
	v_mul_f32_e32 v28, 0xbfb8aa3b, v28
	v_mul_f32_e32 v29, 0xbfb8aa3b, v29
	v_exp_f32_e32 v30, v30
	v_exp_f32_e32 v31, v31
	v_exp_f32_e32 v32, v32
	v_exp_f32_e32 v33, v33
	v_exp_f32_e32 v26, v26
	v_exp_f32_e32 v27, v27
	v_exp_f32_e32 v28, v28
	v_exp_f32_e32 v29, v29
	v_add_f32_e32 v30, 1.0, v30
	v_add_f32_e32 v31, 1.0, v31
	v_add_f32_e32 v32, 1.0, v32
	v_add_f32_e32 v33, 1.0, v33
	v_add_f32_e32 v26, 1.0, v26
	v_add_f32_e32 v27, 1.0, v27
	v_add_f32_e32 v28, 1.0, v28
	v_add_f32_e32 v29, 1.0, v29
	v_rcp_f32_e32 v30, v30
	v_rcp_f32_e32 v31, v31
	v_rcp_f32_e32 v32, v32
	v_rcp_f32_e32 v33, v33
	v_rcp_f32_e32 v26, v26
	v_rcp_f32_e32 v27, v27
	v_rcp_f32_e32 v28, v28
	v_rcp_f32_e32 v29, v29
	v_add_f32_e32 v22, v22, v172
	v_add_f32_e32 v23, v23, v173
	v_add_f32_e32 v24, v24, v174
	v_add_f32_e32 v25, v25, v175
	v_add_f32_e32 v18, v18, v172
	v_add_f32_e32 v19, v19, v173
	v_add_f32_e32 v20, v20, v174
	v_add_f32_e32 v21, v21, v175
	v_mul_f32_e32 v22, 0xbfb8aa3b, v22
	v_mul_f32_e32 v23, 0xbfb8aa3b, v23
	v_mul_f32_e32 v24, 0xbfb8aa3b, v24
	v_mul_f32_e32 v25, 0xbfb8aa3b, v25
	v_mul_f32_e32 v18, 0xbfb8aa3b, v18
	v_mul_f32_e32 v19, 0xbfb8aa3b, v19
	v_mul_f32_e32 v20, 0xbfb8aa3b, v20
	v_mul_f32_e32 v21, 0xbfb8aa3b, v21
	v_exp_f32_e32 v22, v22
	v_exp_f32_e32 v23, v23
	v_exp_f32_e32 v24, v24
	v_exp_f32_e32 v25, v25
	v_exp_f32_e32 v18, v18
	v_exp_f32_e32 v19, v19
	v_exp_f32_e32 v20, v20
	v_exp_f32_e32 v21, v21
	v_add_f32_e32 v22, 1.0, v22
	v_add_f32_e32 v23, 1.0, v23
	v_add_f32_e32 v24, 1.0, v24
	v_add_f32_e32 v25, 1.0, v25
	v_add_f32_e32 v18, 1.0, v18
	v_add_f32_e32 v19, 1.0, v19
	v_add_f32_e32 v20, 1.0, v20
	v_add_f32_e32 v21, 1.0, v21
	v_rcp_f32_e32 v22, v22
	v_rcp_f32_e32 v23, v23
	v_rcp_f32_e32 v24, v24
	v_rcp_f32_e32 v25, v25
	v_rcp_f32_e32 v18, v18
	v_rcp_f32_e32 v19, v19
	v_rcp_f32_e32 v20, v20
	v_rcp_f32_e32 v21, v21
	v_add_f32_e32 v14, v14, v172
	v_add_f32_e32 v15, v15, v173
	v_add_f32_e32 v16, v16, v174
	v_add_f32_e32 v17, v17, v175
	v_add_f32_e32 v10, v10, v172
	v_add_f32_e32 v11, v11, v173
	v_add_f32_e32 v12, v12, v174
	v_add_f32_e32 v13, v13, v175
	v_mul_f32_e32 v14, 0xbfb8aa3b, v14
	v_mul_f32_e32 v15, 0xbfb8aa3b, v15
	v_mul_f32_e32 v16, 0xbfb8aa3b, v16
	v_mul_f32_e32 v17, 0xbfb8aa3b, v17
	v_mul_f32_e32 v10, 0xbfb8aa3b, v10
	v_mul_f32_e32 v11, 0xbfb8aa3b, v11
	v_mul_f32_e32 v12, 0xbfb8aa3b, v12
	v_mul_f32_e32 v13, 0xbfb8aa3b, v13
	v_exp_f32_e32 v14, v14
	v_exp_f32_e32 v15, v15
	v_exp_f32_e32 v16, v16
	v_exp_f32_e32 v17, v17
	v_exp_f32_e32 v10, v10
	v_exp_f32_e32 v11, v11
	v_exp_f32_e32 v12, v12
	v_exp_f32_e32 v13, v13
	v_add_f32_e32 v14, 1.0, v14
	v_add_f32_e32 v15, 1.0, v15
	v_add_f32_e32 v16, 1.0, v16
	v_add_f32_e32 v17, 1.0, v17
	v_add_f32_e32 v10, 1.0, v10
	v_add_f32_e32 v11, 1.0, v11
	v_add_f32_e32 v12, 1.0, v12
	v_add_f32_e32 v13, 1.0, v13
	v_rcp_f32_e32 v14, v14
	v_rcp_f32_e32 v15, v15
	v_rcp_f32_e32 v16, v16
	v_rcp_f32_e32 v17, v17
	v_rcp_f32_e32 v10, v10
	v_rcp_f32_e32 v11, v11
	v_rcp_f32_e32 v12, v12
	v_rcp_f32_e32 v13, v13
	v_add_f32_e32 v6, v6, v172
	v_add_f32_e32 v7, v7, v173
	v_add_f32_e32 v8, v8, v174
	v_add_f32_e32 v9, v9, v175
	v_add_f32_e32 v2, v2, v172
	v_add_f32_e32 v3, v3, v173
	v_add_f32_e32 v4, v4, v174
	v_add_f32_e32 v5, v5, v175
	v_mul_f32_e32 v6, 0xbfb8aa3b, v6
	v_mul_f32_e32 v7, 0xbfb8aa3b, v7
	v_mul_f32_e32 v8, 0xbfb8aa3b, v8
	v_mul_f32_e32 v9, 0xbfb8aa3b, v9
	v_mul_f32_e32 v2, 0xbfb8aa3b, v2
	v_mul_f32_e32 v3, 0xbfb8aa3b, v3
	v_mul_f32_e32 v4, 0xbfb8aa3b, v4
	v_mul_f32_e32 v5, 0xbfb8aa3b, v5
	v_exp_f32_e32 v6, v6
	v_exp_f32_e32 v7, v7
	v_exp_f32_e32 v8, v8
	v_exp_f32_e32 v9, v9
	v_exp_f32_e32 v2, v2
	v_exp_f32_e32 v3, v3
	v_exp_f32_e32 v4, v4
	v_exp_f32_e32 v5, v5
	v_add_f32_e32 v6, 1.0, v6
	v_add_f32_e32 v7, 1.0, v7
	v_add_f32_e32 v8, 1.0, v8
	v_add_f32_e32 v9, 1.0, v9
	v_add_f32_e32 v2, 1.0, v2
	v_add_f32_e32 v3, 1.0, v3
	v_add_f32_e32 v4, 1.0, v4
	v_add_f32_e32 v5, 1.0, v5
	v_rcp_f32_e32 v6, v6
	v_rcp_f32_e32 v7, v7
	v_rcp_f32_e32 v8, v8
	v_rcp_f32_e32 v9, v9
	v_rcp_f32_e32 v2, v2
	v_rcp_f32_e32 v3, v3
	v_rcp_f32_e32 v4, v4
	v_rcp_f32_e32 v5, v5
	s_nop 0
.Lipg_ns3:
	s_cmp_eq_u32 s82, 0
	s_cbranch_scc1 .Lipg_noab
	s_sub_u32 s0, s88, s83
	s_cmp_eq_u32 s0, 64
	s_cbranch_scc0 .Lipg_noab
	s_add_u32 s58, s12, 0x23d92200
	s_addc_u32 s59, s13, 0
	v_lshrrev_b32_e32 v192, 4, v219
	v_subrev_u32_e32 v192, 2, v192
	v_lshlrev_b32_e32 v192, 4, v192
	v_lshl_add_u32 v196, v176, 5, v192
	v_mov_b32_e32 v197, 0
	v_lshl_add_u64 v[196:197], v[196:197], 0, s[58:59]
	s_movk_i32 s42, 0x1000
	v_lshl_add_u64 v[198:199], v[196:197], 0, s[42:43]
	s_mov_b32 exec_lo, 0
	s_mov_b32 exec_hi, -1
	global_store_dwordx4 v[196:197], v[130:133], off offset:0
	global_store_dwordx4 v[196:197], v[126:129], off offset:512
	global_store_dwordx4 v[196:197], v[122:125], off offset:1024
	global_store_dwordx4 v[196:197], v[118:121], off offset:1536
	global_store_dwordx4 v[198:199], v[114:117], off offset:0
	global_store_dwordx4 v[198:199], v[106:109], off offset:512
	global_store_dwordx4 v[198:199], v[102:105], off offset:1024
	global_store_dwordx4 v[198:199], v[98:101], off offset:1536
	s_mov_b64 exec, -1
	s_nop 1
.Lipg_noab:
	s_movk_i32 s42, 0
	v_mad_u64_u32 v[154:155], s[58:59], v186, s42, v[188:189]
	v_mad_u64_u32 v[156:157], s[58:59], v187, s42, v[190:191]
	v_cvt_pk_bf16_f32 v130, v130, v131
	v_cvt_pk_bf16_f32 v131, v132, v133
	v_cvt_pk_bf16_f32 v132, v94, v95
	v_cvt_pk_bf16_f32 v133, v96, v97
	v_cvt_pk_bf16_f32 v62, v62, v63
	v_cvt_pk_bf16_f32 v63, v64, v65
	v_cvt_pk_bf16_f32 v64, v30, v31
	v_cvt_pk_bf16_f32 v65, v32, v33
	v_permlane16_swap_b32_e32 v130, v132
	v_permlane16_swap_b32_e32 v131, v133
	v_permlane16_swap_b32_e32 v62, v64
	v_permlane16_swap_b32_e32 v63, v65
	s_mov_b64 exec, s[48:49]
	global_store_dwordx4 v[154:155], v[130:133], off
	s_mov_b64 exec, s[50:51]
	global_store_dwordx4 v[156:157], v[62:65], off
	s_mov_b64 exec, -1
	s_movk_i32 s42, 16
	v_mad_u64_u32 v[154:155], s[58:59], v186, s42, v[188:189]
	v_mad_u64_u32 v[156:157], s[58:59], v187, s42, v[190:191]
	v_cvt_pk_bf16_f32 v126, v126, v127
	v_cvt_pk_bf16_f32 v127, v128, v129
	v_cvt_pk_bf16_f32 v128, v90, v91
	v_cvt_pk_bf16_f32 v129, v92, v93
	v_cvt_pk_bf16_f32 v58, v58, v59
	v_cvt_pk_bf16_f32 v59, v60, v61
	v_cvt_pk_bf16_f32 v60, v26, v27
	v_cvt_pk_bf16_f32 v61, v28, v29
	v_permlane16_swap_b32_e32 v126, v128
	v_permlane16_swap_b32_e32 v127, v129
	v_permlane16_swap_b32_e32 v58, v60
	v_permlane16_swap_b32_e32 v59, v61
	s_mov_b64 exec, s[48:49]
	global_store_dwordx4 v[154:155], v[126:129], off
	s_mov_b64 exec, s[50:51]
	global_store_dwordx4 v[156:157], v[58:61], off
	s_mov_b64 exec, -1
	s_movk_i32 s42, 32
	v_mad_u64_u32 v[154:155], s[58:59], v186, s42, v[188:189]
	v_mad_u64_u32 v[156:157], s[58:59], v187, s42, v[190:191]
	v_cvt_pk_bf16_f32 v122, v122, v123
	v_cvt_pk_bf16_f32 v123, v124, v125
	v_cvt_pk_bf16_f32 v124, v86, v87
	v_cvt_pk_bf16_f32 v125, v88, v89
	v_cvt_pk_bf16_f32 v54, v54, v55
	v_cvt_pk_bf16_f32 v55, v56, v57
	v_cvt_pk_bf16_f32 v56, v22, v23
	v_cvt_pk_bf16_f32 v57, v24, v25
	v_permlane16_swap_b32_e32 v122, v124
	v_permlane16_swap_b32_e32 v123, v125
	v_permlane16_swap_b32_e32 v54, v56
	v_permlane16_swap_b32_e32 v55, v57
	s_mov_b64 exec, s[48:49]
	global_store_dwordx4 v[154:155], v[122:125], off
	s_mov_b64 exec, s[50:51]
	global_store_dwordx4 v[156:157], v[54:57], off
	s_mov_b64 exec, -1
	s_movk_i32 s42, 48
	v_mad_u64_u32 v[154:155], s[58:59], v186, s42, v[188:189]
	v_mad_u64_u32 v[156:157], s[58:59], v187, s42, v[190:191]
	v_cvt_pk_bf16_f32 v118, v118, v119
	v_cvt_pk_bf16_f32 v119, v120, v121
	v_cvt_pk_bf16_f32 v120, v82, v83
	v_cvt_pk_bf16_f32 v121, v84, v85
	v_cvt_pk_bf16_f32 v50, v50, v51
	v_cvt_pk_bf16_f32 v51, v52, v53
	v_cvt_pk_bf16_f32 v52, v18, v19
	v_cvt_pk_bf16_f32 v53, v20, v21
	v_permlane16_swap_b32_e32 v118, v120
	v_permlane16_swap_b32_e32 v119, v121
	v_permlane16_swap_b32_e32 v50, v52
	v_permlane16_swap_b32_e32 v51, v53
	s_mov_b64 exec, s[48:49]
	global_store_dwordx4 v[154:155], v[118:121], off
	s_mov_b64 exec, s[50:51]
	global_store_dwordx4 v[156:157], v[50:53], off
	s_mov_b64 exec, -1
	s_movk_i32 s42, 128
	v_mad_u64_u32 v[154:155], s[58:59], v186, s42, v[188:189]
	v_mad_u64_u32 v[156:157], s[58:59], v187, s42, v[190:191]
	v_cvt_pk_bf16_f32 v114, v114, v115
	v_cvt_pk_bf16_f32 v115, v116, v117
	v_cvt_pk_bf16_f32 v116, v78, v79
	v_cvt_pk_bf16_f32 v117, v80, v81
	v_cvt_pk_bf16_f32 v46, v46, v47
	v_cvt_pk_bf16_f32 v47, v48, v49
	v_cvt_pk_bf16_f32 v48, v14, v15
	v_cvt_pk_bf16_f32 v49, v16, v17
	v_permlane16_swap_b32_e32 v114, v116
	v_permlane16_swap_b32_e32 v115, v117
	v_permlane16_swap_b32_e32 v46, v48
	v_permlane16_swap_b32_e32 v47, v49
	s_mov_b64 exec, s[48:49]
	global_store_dwordx4 v[154:155], v[114:117], off
	s_mov_b64 exec, s[50:51]
	global_store_dwordx4 v[156:157], v[46:49], off
	s_mov_b64 exec, -1
	s_movk_i32 s42, 144
	v_mad_u64_u32 v[154:155], s[58:59], v186, s42, v[188:189]
	v_mad_u64_u32 v[156:157], s[58:59], v187, s42, v[190:191]
	v_cvt_pk_bf16_f32 v106, v106, v107
	v_cvt_pk_bf16_f32 v107, v108, v109
	v_cvt_pk_bf16_f32 v108, v74, v75
	v_cvt_pk_bf16_f32 v109, v76, v77
	v_cvt_pk_bf16_f32 v42, v42, v43
	v_cvt_pk_bf16_f32 v43, v44, v45
	v_cvt_pk_bf16_f32 v44, v10, v11
	v_cvt_pk_bf16_f32 v45, v12, v13
	v_permlane16_swap_b32_e32 v106, v108
	v_permlane16_swap_b32_e32 v107, v109
	v_permlane16_swap_b32_e32 v42, v44
	v_permlane16_swap_b32_e32 v43, v45
	s_mov_b64 exec, s[48:49]
	global_store_dwordx4 v[154:155], v[106:109], off
	s_mov_b64 exec, s[50:51]
	global_store_dwordx4 v[156:157], v[42:45], off
	s_mov_b64 exec, -1
	s_movk_i32 s42, 160
	v_mad_u64_u32 v[154:155], s[58:59], v186, s42, v[188:189]
	v_mad_u64_u32 v[156:157], s[58:59], v187, s42, v[190:191]
	v_cvt_pk_bf16_f32 v102, v102, v103
	v_cvt_pk_bf16_f32 v103, v104, v105
	v_cvt_pk_bf16_f32 v104, v70, v71
	v_cvt_pk_bf16_f32 v105, v72, v73
	v_cvt_pk_bf16_f32 v38, v38, v39
	v_cvt_pk_bf16_f32 v39, v40, v41
	v_cvt_pk_bf16_f32 v40, v6, v7
	v_cvt_pk_bf16_f32 v41, v8, v9
	v_permlane16_swap_b32_e32 v102, v104
	v_permlane16_swap_b32_e32 v103, v105
	v_permlane16_swap_b32_e32 v38, v40
	v_permlane16_swap_b32_e32 v39, v41
	s_mov_b64 exec, s[48:49]
	global_store_dwordx4 v[154:155], v[102:105], off
	s_mov_b64 exec, s[50:51]
	global_store_dwordx4 v[156:157], v[38:41], off
	s_mov_b64 exec, -1
	s_movk_i32 s42, 176
	v_mad_u64_u32 v[154:155], s[58:59], v186, s42, v[188:189]
	v_mad_u64_u32 v[156:157], s[58:59], v187, s42, v[190:191]
	v_cvt_pk_bf16_f32 v98, v98, v99
	v_cvt_pk_bf16_f32 v99, v100, v101
	v_cvt_pk_bf16_f32 v100, v66, v67
	v_cvt_pk_bf16_f32 v101, v68, v69
	v_cvt_pk_bf16_f32 v34, v34, v35
	v_cvt_pk_bf16_f32 v35, v36, v37
	v_cvt_pk_bf16_f32 v36, v2, v3
	v_cvt_pk_bf16_f32 v37, v4, v5
	v_permlane16_swap_b32_e32 v98, v100
	v_permlane16_swap_b32_e32 v99, v101
	v_permlane16_swap_b32_e32 v34, v36
	v_permlane16_swap_b32_e32 v35, v37
	s_mov_b64 exec, s[48:49]
	global_store_dwordx4 v[154:155], v[98:101], off
	s_mov_b64 exec, s[50:51]
	global_store_dwordx4 v[156:157], v[34:37], off
	s_mov_b64 exec, -1
	s_branch .LBB0_986
.Lipf_slow:
	s_cmpk_gt_i32 s81, 0x7f
	s_cselect_b64 s[40:41], -1, 0
	s_cmpk_lt_i32 s81, 0x80
	s_cselect_b64 s[0:1], -1, 0
	s_and_b64 s[8:9], s[0:1], exec
	s_cselect_b32 s82, 0, 0x8000
	s_lshl_b32 s3, s82, 5
	v_or_b32_e32 v136, s42, v135
	s_add_u32 s44, s12, s3
	v_add_u32_e32 v151, s2, v150
	s_movk_i32 s2, 0x1550
	s_addc_u32 s45, s13, 0
	v_cmp_gt_i32_e32 vcc, s2, v136
	s_and_saveexec_b64 s[46:47], vcc
	s_cbranch_execz .LBB0_1155
	s_movk_i32 s2, 0x1ff
	v_cmp_lt_i32_e32 vcc, s2, v136
	s_and_saveexec_b64 s[8:9], vcc
	s_xor_b64 s[8:9], exec, s[8:9]
	s_cbranch_execz .LBB0_1039
	s_cmpk_gt_u32 s42, 0x27f
	s_mov_b64 s[52:53], -1
	s_cbranch_scc0 .LBB0_1037
	s_cmpk_gt_u32 s42, 0x2ff
	s_cbranch_scc0 .LBB0_1034
	s_cmpk_gt_u32 s42, 0x4ff
	s_cbranch_scc0 .LBB0_1031
	s_movk_i32 s2, 0x53f
	v_cmp_lt_u32_e32 vcc, s2, v136
	s_and_saveexec_b64 s[52:53], vcc
	s_xor_b64 s[52:53], exec, s[52:53]
	s_cbranch_execz .LBB0_1024
	s_movk_i32 s2, 0x547
	v_cmp_lt_u32_e32 vcc, s2, v136
	s_and_saveexec_b64 s[50:51], vcc
	s_xor_b64 s[50:51], exec, s[50:51]
	s_cbranch_execz .LBB0_1021
	s_movk_i32 s2, 0xb47
	v_cmp_lt_u32_e32 vcc, s2, v136
	s_and_saveexec_b64 s[48:49], vcc
	s_xor_b64 s[48:49], exec, s[48:49]
	s_cbranch_execz .LBB0_1018
	s_movk_i32 s2, 0xb4f
	v_cmp_lt_u32_e32 vcc, s2, v136
	s_and_saveexec_b64 s[54:55], vcc
	s_xor_b64 s[54:55], exec, s[54:55]
	s_cbranch_execz .LBB0_1015
	s_movk_i32 s2, 0xd4f
	v_cmp_lt_u32_e32 vcc, s2, v136
	s_and_saveexec_b64 s[2:3], vcc
	s_xor_b64 s[2:3], exec, s[2:3]
	s_cbranch_execz .LBB0_1012
	v_add_u32_e32 v0, 0xfffff2b0, v136
	v_lshl_add_u64 v[110:111], v[0:1], 2, s[10:11]
	global_load_dwordx4 v[110:113], v[110:111], off
	s_waitcnt vmcnt(0)
	v_lshl_add_u64 v[138:139], v[0:1], 1, s[18:19]
.LBB0_1012:
	s_or_saveexec_b64 s[56:57], s[2:3]
	s_mov_b64 s[2:3], -1
	v_mov_b64_e32 v[142:143], 0x800
	s_xor_b64 exec, exec, s[56:57]
	s_cbranch_execz .LBB0_1014
	v_mov_b32_e32 v137, v1
	v_lshl_add_u64 v[110:111], v[136:137], 1, s[12:13]
	s_mov_b64 s[2:3], 0x102fe960
	v_lshl_add_u64 v[138:139], v[110:111], 0, s[2:3]
	v_mov_b32_e32 v0, 0
	v_mov_b64_e32 v[142:143], 0x200
	v_mov_b32_e32 v113, 0
	s_xor_b64 s[2:3], exec, -1
	v_mov_b32_e32 v112, 0
	v_mov_b32_e32 v111, 0
	v_mov_b32_e32 v110, 0

.LBB0_1015:
	s_or_saveexec_b64 s[54:55], s[54:55]
	v_mov_b64_e32 v[140:141], 0
	v_mov_b64_e32 v[144:145], 0
	s_xor_b64 exec, exec, s[54:55]
	s_cbranch_execz .LBB0_1017
	v_mov_b32_e32 v137, v1
	v_lshl_add_u64 v[110:111], v[136:137], 2, s[44:45]
	s_mov_b64 s[56:57], 0x23d8f4e0
	v_lshl_add_u64 v[140:141], v[110:111], 0, s[56:57]
	v_mov_b64_e32 v[144:145], 8
	v_mov_b32_e32 v0, 0
	v_mov_b64_e32 v[138:139], 0
	v_mov_b32_e32 v113, 0
	s_andn2_b64 s[2:3], s[2:3], exec
	v_mov_b32_e32 v112, 0
	v_mov_b32_e32 v111, 0
	v_mov_b32_e32 v110, 0
	v_mov_b64_e32 v[142:143], 0

.LBB0_1018:
	s_or_saveexec_b64 s[54:55], s[48:49]
	s_mov_b64 s[48:49], 0
	s_xor_b64 exec, exec, s[54:55]
	s_cbranch_execz .LBB0_1020
	v_add_u32_e32 v0, 0xfffffab8, v136
	s_mov_b64 s[48:49], exec
	v_lshl_add_u64 v[138:139], v[0:1], 1, s[20:21]
	v_mov_b64_e32 v[140:141], 0
	v_mov_b64_e32 v[142:143], 0x600
	v_mov_b32_e32 v113, 0
	s_andn2_b64 s[2:3], s[2:3], exec
	v_mov_b32_e32 v112, 0
	v_mov_b32_e32 v111, 0
	v_mov_b32_e32 v110, 0
	v_mov_b64_e32 v[144:145], 0

.LBB0_1021:
	s_or_saveexec_b64 s[54:55], s[50:51]
	s_mov_b64 s[50:51], 0
	s_xor_b64 exec, exec, s[54:55]
	s_cbranch_execz .LBB0_1023
	v_mov_b32_e32 v137, v1
	v_lshl_add_u64 v[110:111], v[136:137], 2, s[44:45]
	s_mov_b64 s[56:57], 0x23e94d00
	s_mov_b64 s[50:51], exec
	v_lshl_add_u64 v[140:141], v[110:111], 0, s[56:57]
	v_mov_b64_e32 v[144:145], 8
	v_mov_b32_e32 v0, 0
	v_mov_b64_e32 v[138:139], 0
	v_mov_b32_e32 v113, 0
	s_andn2_b64 s[48:49], s[48:49], exec
	s_andn2_b64 s[2:3], s[2:3], exec
	v_mov_b32_e32 v112, 0
	v_mov_b32_e32 v111, 0
	v_mov_b32_e32 v110, 0
	v_mov_b64_e32 v[142:143], 0

.LBB0_1029:
	v_lshl_add_u64 v[140:141], v[0:1], 2, s[54:55]
	v_mov_b64_e32 v[142:143], 64
	v_mov_b32_e32 v113, 0
	v_mov_b32_e32 v137, s43
	s_andn2_b64 s[48:49], s[48:49], exec
	s_andn2_b64 s[50:51], s[50:51], exec
	s_andn2_b64 s[2:3], s[2:3], exec
	v_mov_b32_e32 v112, 0
	v_mov_b32_e32 v111, 0
	v_mov_b32_e32 v110, 0
	v_mov_b64_e32 v[144:145], 64

.LBB0_1031:
	s_andn2_b64 vcc, exec, s[52:53]
	s_cbranch_vccnz .LBB0_1033
	v_mov_b32_e32 v137, v1
	v_lshl_add_u64 v[110:111], v[136:137], 1, s[12:13]
	s_mov_b64 s[52:53], 0x80ffa00
	v_mov_b32_e32 v137, 0
	v_lshl_add_u64 v[138:139], v[110:111], 0, s[52:53]
	v_mov_b64_e32 v[140:141], 0
	v_mov_b64_e32 v[142:143], 0x200
	v_mov_b32_e32 v113, 0
	s_andn2_b64 s[48:49], s[48:49], exec
	s_andn2_b64 s[50:51], s[50:51], exec
	s_andn2_b64 s[2:3], s[2:3], exec
	v_mov_b32_e32 v112, 0
	v_mov_b32_e32 v111, 0
	v_mov_b32_e32 v110, 0
	v_mov_b32_e32 v0, v137
	v_mov_b64_e32 v[144:145], 0

.LBB0_1034:
	s_andn2_b64 vcc, exec, s[52:53]
	s_cbranch_vccnz .LBB0_1036
	s_and_b64 s[52:53], s[0:1], exec
	v_readlane_b32 s52, v252, 34
	v_readlane_b32 s53, v252, 35
	s_mov_b32 s55, s53
	s_cselect_b32 s53, s69, s71
	s_cselect_b32 s52, s68, s70
	s_cselect_b32 s54, 0x80, 0
	s_lshl_b64 s[52:53], s[52:53], 2
	v_add_u32_e32 v0, 0xfffffd80, v136
	s_add_u32 s52, s16, s52
	s_mov_b32 s43, s55
	s_addc_u32 s53, s17, s53
	v_lshl_add_u64 v[110:111], v[0:1], 1, s[26:27]
	v_writelane_b32 v252, s42, 34
	v_lshl_add_u64 v[140:141], v[0:1], 2, s[52:53]
	v_cndmask_b32_e64 v139, 0, v111, s[0:1]
	v_cndmask_b32_e64 v138, 0, v110, s[0:1]
	v_mov_b64_e32 v[144:145], 0x80
	v_mov_b32_e32 v137, 0
	v_mov_b32_e32 v113, 0
	v_writelane_b32 v252, s43, 35
	v_mov_b64_e32 v[142:143], s[54:55]
	s_andn2_b64 s[48:49], s[48:49], exec
	s_andn2_b64 s[50:51], s[50:51], exec
	s_andn2_b64 s[2:3], s[2:3], exec
	v_mov_b32_e32 v112, 0
	v_mov_b32_e32 v111, 0
	v_mov_b32_e32 v110, 0

.LBB0_1037:
	s_andn2_b64 vcc, exec, s[52:53]
	s_cbranch_vccnz .LBB0_1039
	s_and_b64 s[52:53], s[0:1], exec
	v_readlane_b32 s52, v252, 34
	v_readlane_b32 s53, v252, 35
	s_mov_b32 s55, s53
	s_cselect_b32 s53, s73, s75
	s_cselect_b32 s52, s72, s74
	s_cselect_b32 s54, 0x80, 0
	s_lshl_b64 s[52:53], s[52:53], 2
	v_add_u32_e32 v0, 0xfffffe00, v136
	s_add_u32 s52, s16, s52
	s_mov_b32 s43, s55
	s_addc_u32 s53, s17, s53
	v_lshl_add_u64 v[110:111], v[0:1], 1, s[28:29]
	v_writelane_b32 v252, s42, 34
	v_lshl_add_u64 v[140:141], v[0:1], 2, s[52:53]
	v_cndmask_b32_e64 v139, 0, v111, s[0:1]
	v_cndmask_b32_e64 v138, 0, v110, s[0:1]
	v_mov_b64_e32 v[144:145], 0x80
	v_mov_b32_e32 v137, 0
	v_mov_b32_e32 v113, 0
	v_writelane_b32 v252, s43, 35
	v_mov_b64_e32 v[142:143], s[54:55]
	s_andn2_b64 s[48:49], s[48:49], exec
	s_andn2_b64 s[50:51], s[50:51], exec
	s_andn2_b64 s[2:3], s[2:3], exec
	v_mov_b32_e32 v112, 0
	v_mov_b32_e32 v111, 0
	v_mov_b32_e32 v110, 0
.LBB0_1039:
	s_andn2_saveexec_b64 s[8:9], s[8:9]
	s_cbranch_execz .LBB0_1041
	v_ashrrev_i32_e32 v137, 31, v136
	v_mov_b32_e32 v0, 0
	v_lshl_add_u64 v[138:139], v[136:137], 1, s[30:31]
	v_mov_b32_e32 v110, 0
	v_mov_b64_e32 v[142:143], 0x200
	v_mov_b64_e32 v[144:145], 0
	s_andn2_b64 s[2:3], s[2:3], exec
	s_andn2_b64 s[50:51], s[50:51], exec
	s_andn2_b64 s[48:49], s[48:49], exec
	v_mov_b64_e32 v[140:141], 0
	v_mov_b32_e32 v137, v0
	v_mov_b32_e32 v111, 0
	v_mov_b32_e32 v112, 0
	v_mov_b32_e32 v113, 0

.LBB0_1046:
	v_add_u32_e32 v148, v137, v151
	v_ashrrev_i32_e32 v149, 31, v148
	v_mul_lo_u32 v152, v142, v149
	v_mul_lo_u32 v153, v143, v148
	v_mad_u64_u32 v[148:149], s[54:55], v142, v148, 0
	v_add3_u32 v149, v149, v152, v153
	v_cvt_pk_bf16_f32 v146, v130, v131
	v_cvt_pk_bf16_f32 v147, v132, v133
	v_lshl_add_u64 v[148:149], v[148:149], 1, v[138:139]
	flat_store_dwordx2 v[148:149], v[146:147]
	s_or_b64 exec, exec, s[8:9]
	v_cmp_ne_u64_e64 s[8:9], 0, v[140:141]
	s_and_saveexec_b64 s[54:55], s[8:9]
	s_cbranch_execnz .LBB0_1050
	s_branch .LBB0_1051

.LBB0_1048:
	v_add_f32_e32 v130, v130, v110
	v_add_f32_e32 v131, v131, v111
	v_add_f32_e32 v132, v132, v112
	v_add_f32_e32 v133, v133, v113
	v_mul_f32_e32 v130, 0xbfb8aa3b, v130
	v_mul_f32_e32 v131, 0xbfb8aa3b, v131
	v_mul_f32_e32 v132, 0xbfb8aa3b, v132
	v_mul_f32_e32 v133, 0xbfb8aa3b, v133
	v_exp_f32_e32 v130, v130
	v_exp_f32_e32 v131, v131
	v_exp_f32_e32 v132, v132
	v_exp_f32_e32 v133, v133
	v_add_f32_e32 v130, 1.0, v130
	v_add_f32_e32 v131, 1.0, v131
	v_add_f32_e32 v132, 1.0, v132
	v_add_f32_e32 v133, 1.0, v133
	v_rcp_f32_e32 v130, v130
	v_rcp_f32_e32 v131, v131
	v_rcp_f32_e32 v132, v132
	v_rcp_f32_e32 v133, v133
	s_or_b64 exec, exec, s[2:3]
	v_cmp_ne_u64_e64 s[2:3], 0, v[138:139]
	s_and_saveexec_b64 s[8:9], s[2:3]
	s_cbranch_execnz .LBB0_1046

.LBB0_1054:
	v_add_f32_e32 v126, v126, v110
	v_add_f32_e32 v127, v127, v111
	v_add_f32_e32 v128, v128, v112
	v_add_f32_e32 v129, v129, v113
	v_mul_f32_e32 v126, 0xbfb8aa3b, v126
	v_mul_f32_e32 v127, 0xbfb8aa3b, v127
	v_mul_f32_e32 v128, 0xbfb8aa3b, v128
	v_mul_f32_e32 v129, 0xbfb8aa3b, v129
	v_exp_f32_e32 v126, v126
	v_exp_f32_e32 v127, v127
	v_exp_f32_e32 v128, v128
	v_exp_f32_e32 v129, v129
	v_add_f32_e32 v126, 1.0, v126
	v_add_f32_e32 v127, 1.0, v127
	v_add_f32_e32 v128, 1.0, v128
	v_add_f32_e32 v129, 1.0, v129
	v_rcp_f32_e32 v126, v126
	v_rcp_f32_e32 v127, v127
	v_rcp_f32_e32 v128, v128
	v_rcp_f32_e32 v129, v129
	s_or_b64 exec, exec, s[56:57]
	v_or_b32_e32 v130, 16, v151
	s_and_saveexec_b64 s[56:57], s[2:3]
	s_cbranch_execnz .LBB0_1074

.LBB0_1062:
	v_add_u32_e32 v127, v137, v126
	v_ashrrev_i32_e32 v130, 31, v127
	v_mul_lo_u32 v132, v142, v130
	v_mul_lo_u32 v133, v143, v127
	v_mad_u64_u32 v[130:131], s[58:59], v142, v127, 0
	v_add3_u32 v131, v131, v132, v133
	v_cvt_pk_bf16_f32 v128, v122, v123
	v_cvt_pk_bf16_f32 v129, v124, v125
	v_lshl_add_u64 v[130:131], v[130:131], 1, v[138:139]
	flat_store_dwordx2 v[130:131], v[128:129]
	s_or_b64 exec, exec, s[56:57]
	s_and_saveexec_b64 s[56:57], s[8:9]
	s_cbranch_execnz .LBB0_1080

.LBB0_1066:
	v_add_f32_e32 v118, v118, v110
	v_add_f32_e32 v119, v119, v111
	v_add_f32_e32 v120, v120, v112
	v_add_f32_e32 v121, v121, v113
	v_mul_f32_e32 v118, 0xbfb8aa3b, v118
	v_mul_f32_e32 v119, 0xbfb8aa3b, v119
	v_mul_f32_e32 v120, 0xbfb8aa3b, v120
	v_mul_f32_e32 v121, 0xbfb8aa3b, v121
	v_exp_f32_e32 v118, v118
	v_exp_f32_e32 v119, v119
	v_exp_f32_e32 v120, v120
	v_exp_f32_e32 v121, v121
	v_add_f32_e32 v118, 1.0, v118
	v_add_f32_e32 v119, 1.0, v119
	v_add_f32_e32 v120, 1.0, v120
	v_add_f32_e32 v121, 1.0, v121
	v_rcp_f32_e32 v118, v118
	v_rcp_f32_e32 v119, v119
	v_rcp_f32_e32 v120, v120
	v_rcp_f32_e32 v121, v121
	s_or_b64 exec, exec, s[56:57]
	v_or_b32_e32 v124, 48, v151
	s_and_saveexec_b64 s[56:57], s[2:3]
	s_cbranch_execnz .LBB0_1086

.LBB0_1074:
	v_add_u32_e32 v131, v137, v130
	v_ashrrev_i32_e32 v146, 31, v131
	v_mul_lo_u32 v152, v142, v146
	v_mul_lo_u32 v153, v143, v131
	v_mad_u64_u32 v[146:147], s[58:59], v142, v131, 0
	v_add3_u32 v147, v147, v152, v153
	v_cvt_pk_bf16_f32 v132, v126, v127
	v_cvt_pk_bf16_f32 v133, v128, v129
	v_lshl_add_u64 v[146:147], v[146:147], 1, v[138:139]
	flat_store_dwordx2 v[146:147], v[132:133]
	s_or_b64 exec, exec, s[56:57]
	s_and_saveexec_b64 s[56:57], s[8:9]
	s_cbranch_execnz .LBB0_1056

.LBB0_1078:
	v_add_f32_e32 v122, v122, v110
	v_add_f32_e32 v123, v123, v111
	v_add_f32_e32 v124, v124, v112
	v_add_f32_e32 v125, v125, v113
	v_mul_f32_e32 v122, 0xbfb8aa3b, v122
	v_mul_f32_e32 v123, 0xbfb8aa3b, v123
	v_mul_f32_e32 v124, 0xbfb8aa3b, v124
	v_mul_f32_e32 v125, 0xbfb8aa3b, v125
	v_exp_f32_e32 v122, v122
	v_exp_f32_e32 v123, v123
	v_exp_f32_e32 v124, v124
	v_exp_f32_e32 v125, v125
	v_add_f32_e32 v122, 1.0, v122
	v_add_f32_e32 v123, 1.0, v123
	v_add_f32_e32 v124, 1.0, v124
	v_add_f32_e32 v125, 1.0, v125
	v_rcp_f32_e32 v122, v122
	v_rcp_f32_e32 v123, v123
	v_rcp_f32_e32 v124, v124
	v_rcp_f32_e32 v125, v125
	s_or_b64 exec, exec, s[56:57]
	v_or_b32_e32 v126, 32, v151
	s_and_saveexec_b64 s[56:57], s[2:3]
	s_cbranch_execnz .LBB0_1062

.LBB0_1086:
	v_add_u32_e32 v125, v137, v124
	v_ashrrev_i32_e32 v126, 31, v125
	v_mul_lo_u32 v128, v142, v126
	v_mul_lo_u32 v129, v143, v125
	v_mad_u64_u32 v[126:127], s[58:59], v142, v125, 0
	v_add3_u32 v127, v127, v128, v129
	v_cvt_pk_bf16_f32 v122, v118, v119
	v_cvt_pk_bf16_f32 v123, v120, v121
	v_lshl_add_u64 v[126:127], v[126:127], 1, v[138:139]
	flat_store_dwordx2 v[126:127], v[122:123]
	s_or_b64 exec, exec, s[56:57]
	v_subrev_u32_e32 v125, s82, v124
	s_and_saveexec_b64 s[56:57], s[8:9]
	s_cbranch_execnz .LBB0_1068

.LBB0_1103:
	v_add_u32_e32 v119, v137, v118
	v_ashrrev_i32_e32 v122, 31, v119
	v_mul_lo_u32 v124, v142, v122
	v_mul_lo_u32 v125, v143, v119
	v_mad_u64_u32 v[122:123], s[58:59], v142, v119, 0
	v_add3_u32 v123, v123, v124, v125
	v_cvt_pk_bf16_f32 v120, v114, v115
	v_cvt_pk_bf16_f32 v121, v116, v117
	v_lshl_add_u64 v[122:123], v[122:123], 1, v[138:139]
	flat_store_dwordx2 v[122:123], v[120:121]
	s_or_b64 exec, exec, s[56:57]
	s_and_saveexec_b64 s[56:57], s[8:9]
	s_cbranch_execnz .LBB0_1125

.LBB0_1107:
	v_add_f32_e32 v106, v106, v110
	v_add_f32_e32 v107, v107, v111
	v_add_f32_e32 v108, v108, v112
	v_add_f32_e32 v109, v109, v113
	v_mul_f32_e32 v106, 0xbfb8aa3b, v106
	v_mul_f32_e32 v107, 0xbfb8aa3b, v107
	v_mul_f32_e32 v108, 0xbfb8aa3b, v108
	v_mul_f32_e32 v109, 0xbfb8aa3b, v109
	v_exp_f32_e32 v106, v106
	v_exp_f32_e32 v107, v107
	v_exp_f32_e32 v108, v108
	v_exp_f32_e32 v109, v109
	v_add_f32_e32 v106, 1.0, v106
	v_add_f32_e32 v107, 1.0, v107
	v_add_f32_e32 v108, 1.0, v108
	v_add_f32_e32 v109, 1.0, v109
	v_rcp_f32_e32 v106, v106
	v_rcp_f32_e32 v107, v107
	v_rcp_f32_e32 v108, v108
	v_rcp_f32_e32 v109, v109
	s_or_b64 exec, exec, s[56:57]
	v_add_u32_e32 v114, 0x90, v151
	s_and_saveexec_b64 s[56:57], s[2:3]
	s_cbranch_execnz .LBB0_1131

.LBB0_1115:
	v_add_u32_e32 v107, v137, v106
	v_ashrrev_i32_e32 v114, 31, v107
	v_mul_lo_u32 v116, v142, v114
	v_mul_lo_u32 v117, v143, v107
	v_mad_u64_u32 v[114:115], s[58:59], v142, v107, 0
	v_add3_u32 v115, v115, v116, v117
	v_cvt_pk_bf16_f32 v108, v102, v103
	v_cvt_pk_bf16_f32 v109, v104, v105
	v_lshl_add_u64 v[114:115], v[114:115], 1, v[138:139]
	flat_store_dwordx2 v[114:115], v[108:109]
	s_or_b64 exec, exec, s[56:57]
	s_and_saveexec_b64 s[56:57], s[8:9]
	s_cbranch_execnz .LBB0_1137

.LBB0_1119:
	v_add_f32_e32 v98, v98, v110
	v_add_f32_e32 v99, v99, v111
	v_add_f32_e32 v100, v100, v112
	v_add_f32_e32 v101, v101, v113
	v_mul_f32_e32 v98, 0xbfb8aa3b, v98
	v_mul_f32_e32 v99, 0xbfb8aa3b, v99
	v_mul_f32_e32 v100, 0xbfb8aa3b, v100
	v_mul_f32_e32 v101, 0xbfb8aa3b, v101
	v_exp_f32_e32 v98, v98
	v_exp_f32_e32 v99, v99
	v_exp_f32_e32 v100, v100
	v_exp_f32_e32 v101, v101
	v_add_f32_e32 v98, 1.0, v98
	v_add_f32_e32 v99, 1.0, v99
	v_add_f32_e32 v100, 1.0, v100
	v_add_f32_e32 v101, 1.0, v101
	v_rcp_f32_e32 v98, v98
	v_rcp_f32_e32 v99, v99
	v_rcp_f32_e32 v100, v100
	v_rcp_f32_e32 v101, v101
	s_or_b64 exec, exec, s[50:51]
	v_add_u32_e32 v104, 0xb0, v151
	s_and_saveexec_b64 s[50:51], s[2:3]
	s_cbranch_execnz .LBB0_1143

.LBB0_1123:
	v_add_f32_e32 v114, v114, v110
	v_add_f32_e32 v115, v115, v111
	v_add_f32_e32 v116, v116, v112
	v_add_f32_e32 v117, v117, v113
	v_mul_f32_e32 v114, 0xbfb8aa3b, v114
	v_mul_f32_e32 v115, 0xbfb8aa3b, v115
	v_mul_f32_e32 v116, 0xbfb8aa3b, v116
	v_mul_f32_e32 v117, 0xbfb8aa3b, v117
	v_exp_f32_e32 v114, v114
	v_exp_f32_e32 v115, v115
	v_exp_f32_e32 v116, v116
	v_exp_f32_e32 v117, v117
	v_add_f32_e32 v114, 1.0, v114
	v_add_f32_e32 v115, 1.0, v115
	v_add_f32_e32 v116, 1.0, v116
	v_add_f32_e32 v117, 1.0, v117
	v_rcp_f32_e32 v114, v114
	v_rcp_f32_e32 v115, v115
	v_rcp_f32_e32 v116, v116
	v_rcp_f32_e32 v117, v117
	s_or_b64 exec, exec, s[56:57]
	v_add_u32_e32 v118, 0x80, v151
	s_and_saveexec_b64 s[56:57], s[2:3]
	s_cbranch_execnz .LBB0_1103

.LBB0_1131:
	v_add_u32_e32 v115, v137, v114
	v_ashrrev_i32_e32 v118, 31, v115
	v_mul_lo_u32 v120, v142, v118
	v_mul_lo_u32 v121, v143, v115
	v_mad_u64_u32 v[118:119], s[58:59], v142, v115, 0
	v_add3_u32 v119, v119, v120, v121
	v_cvt_pk_bf16_f32 v116, v106, v107
	v_cvt_pk_bf16_f32 v117, v108, v109
	v_lshl_add_u64 v[118:119], v[118:119], 1, v[138:139]
	flat_store_dwordx2 v[118:119], v[116:117]
	s_or_b64 exec, exec, s[56:57]
	s_and_saveexec_b64 s[56:57], s[8:9]
	s_cbranch_execnz .LBB0_1109

.LBB0_1135:
	v_add_f32_e32 v102, v102, v110
	v_add_f32_e32 v103, v103, v111
	v_add_f32_e32 v104, v104, v112
	v_add_f32_e32 v105, v105, v113
	v_mul_f32_e32 v102, 0xbfb8aa3b, v102
	v_mul_f32_e32 v103, 0xbfb8aa3b, v103
	v_mul_f32_e32 v104, 0xbfb8aa3b, v104
	v_mul_f32_e32 v105, 0xbfb8aa3b, v105
	v_exp_f32_e32 v102, v102
	v_exp_f32_e32 v103, v103
	v_exp_f32_e32 v104, v104
	v_exp_f32_e32 v105, v105
	v_add_f32_e32 v102, 1.0, v102
	v_add_f32_e32 v103, 1.0, v103
	v_add_f32_e32 v104, 1.0, v104
	v_add_f32_e32 v105, 1.0, v105
	v_rcp_f32_e32 v102, v102
	v_rcp_f32_e32 v103, v103
	v_rcp_f32_e32 v104, v104
	v_rcp_f32_e32 v105, v105
	s_or_b64 exec, exec, s[56:57]
	v_add_u32_e32 v106, 0xa0, v151
	s_and_saveexec_b64 s[56:57], s[2:3]
	s_cbranch_execnz .LBB0_1115

.LBB0_1143:
	v_add_u32_e32 v105, v137, v104
	v_ashrrev_i32_e32 v106, 31, v105
	v_mul_lo_u32 v108, v142, v106
	v_mul_lo_u32 v109, v143, v105
	v_mad_u64_u32 v[106:107], s[2:3], v142, v105, 0
	v_add3_u32 v107, v107, v108, v109
	v_cvt_pk_bf16_f32 v102, v98, v99
	v_cvt_pk_bf16_f32 v103, v100, v101
	v_lshl_add_u64 v[106:107], v[106:107], 1, v[138:139]
	flat_store_dwordx2 v[106:107], v[102:103]
	s_or_b64 exec, exec, s[50:51]
	v_subrev_u32_e32 v105, s82, v104
	s_and_saveexec_b64 s[2:3], s[8:9]
	s_cbranch_execnz .LBB0_1121

.LBB0_1155:
	s_or_b64 exec, exec, s[46:47]
	v_or_b32_e32 v110, 16, v136
	s_movk_i32 s2, 0x1550
	v_cmp_gt_i32_e32 vcc, s2, v110
	s_and_saveexec_b64 s[46:47], vcc
	s_cbranch_execz .LBB0_1276
	s_movk_i32 s2, 0x1ff
	v_cmp_lt_i32_e32 vcc, s2, v110
	s_and_saveexec_b64 s[8:9], vcc
	s_xor_b64 s[8:9], exec, s[8:9]
	s_cbranch_execz .LBB0_1190
	s_cmpk_lt_u32 s42, 0x280
	s_mov_b64 s[50:51], -1
	s_cbranch_scc1 .LBB0_1187
	s_cmpk_lt_u32 s42, 0x300
	s_cbranch_scc1 .LBB0_1184
	s_cmpk_lt_u32 s42, 0x500
	s_cbranch_scc1 .LBB0_1181
	s_movk_i32 s2, 0x53f
	v_cmp_lt_u32_e32 vcc, s2, v136
	s_and_saveexec_b64 s[50:51], vcc
	s_xor_b64 s[50:51], exec, s[50:51]
	s_cbranch_execz .LBB0_1174
	s_movk_i32 s2, 0xb47
	v_cmp_lt_u32_e32 vcc, s2, v110
	s_and_saveexec_b64 s[48:49], vcc
	s_xor_b64 s[48:49], exec, s[48:49]
	s_cbranch_execz .LBB0_1171
	s_movk_i32 s2, 0xb4f
	v_cmp_lt_u32_e32 vcc, s2, v110
	s_and_saveexec_b64 s[52:53], vcc
	s_xor_b64 s[52:53], exec, s[52:53]
	s_cbranch_execz .LBB0_1168
	s_movk_i32 s2, 0xd4f
	v_cmp_lt_u32_e32 vcc, s2, v110
	s_and_saveexec_b64 s[2:3], vcc
	s_xor_b64 s[2:3], exec, s[2:3]
	s_cbranch_execz .LBB0_1165
	v_add_u32_e32 v0, 0xfffff2c0, v136
	v_lshl_add_u64 v[98:99], v[0:1], 2, s[10:11]
	global_load_dwordx4 v[98:101], v[98:99], off
	s_waitcnt vmcnt(0)
	v_lshl_add_u64 v[102:103], v[0:1], 1, s[18:19]
.LBB0_1165:
	s_or_saveexec_b64 s[54:55], s[2:3]
	s_mov_b64 s[2:3], -1
	v_mov_b64_e32 v[104:105], 0x800
	s_xor_b64 exec, exec, s[54:55]
	s_cbranch_execz .LBB0_1167
	v_mov_b32_e32 v137, v1
	v_lshl_add_u64 v[98:99], v[136:137], 1, s[12:13]
	s_mov_b64 s[2:3], 0x102fe980
	v_mov_b32_e32 v101, 0
	v_lshl_add_u64 v[102:103], v[98:99], 0, s[2:3]
	v_mov_b32_e32 v0, 0
	v_mov_b64_e32 v[104:105], 0x200
	s_xor_b64 s[2:3], exec, -1
	v_mov_b32_e32 v100, v101
	v_mov_b32_e32 v99, v101
	v_mov_b32_e32 v98, v101

.LBB0_1168:
	s_or_saveexec_b64 s[52:53], s[52:53]
	v_mov_b64_e32 v[106:107], 0
	v_mov_b64_e32 v[108:109], 0
	s_xor_b64 exec, exec, s[52:53]
	s_cbranch_execz .LBB0_1170
	v_mov_b32_e32 v137, v1
	v_lshl_add_u64 v[98:99], v[136:137], 2, s[44:45]
	s_mov_b64 s[54:55], 0x23d8f520
	v_mov_b32_e32 v101, 0
	v_lshl_add_u64 v[106:107], v[98:99], 0, s[54:55]
	v_mov_b64_e32 v[108:109], 8
	v_mov_b32_e32 v0, 0
	v_mov_b64_e32 v[102:103], 0
	s_andn2_b64 s[2:3], s[2:3], exec
	v_mov_b32_e32 v100, v101
	v_mov_b32_e32 v99, v101
	v_mov_b32_e32 v98, v101
	v_mov_b64_e32 v[104:105], 0

.LBB0_1171:
	s_or_saveexec_b64 s[52:53], s[48:49]
	s_mov_b64 s[48:49], 0
	s_xor_b64 exec, exec, s[52:53]
	s_cbranch_execz .LBB0_1173
	v_add_u32_e32 v0, 0xfffffac8, v136
	v_mov_b32_e32 v101, 0
	s_mov_b64 s[48:49], exec
	v_lshl_add_u64 v[102:103], v[0:1], 1, s[20:21]
	v_mov_b64_e32 v[106:107], 0
	v_mov_b64_e32 v[104:105], 0x600
	s_andn2_b64 s[2:3], s[2:3], exec
	v_mov_b32_e32 v100, v101
	v_mov_b32_e32 v99, v101
	v_mov_b32_e32 v98, v101
	v_mov_b64_e32 v[108:109], 0

.LBB0_1179:
	v_lshl_add_u64 v[106:107], v[0:1], 2, s[52:53]
	v_mov_b64_e32 v[104:105], 64
	v_mov_b32_e32 v101, 0
	v_mov_b32_e32 v112, s43
	s_andn2_b64 s[48:49], s[48:49], exec
	s_andn2_b64 s[2:3], s[2:3], exec
	v_mov_b32_e32 v100, 0
	v_mov_b32_e32 v99, 0
	v_mov_b32_e32 v98, 0
	v_mov_b64_e32 v[108:109], 64

.LBB0_1181:
	s_andn2_b64 vcc, exec, s[50:51]
	s_cbranch_vccnz .LBB0_1183
	v_mov_b32_e32 v137, v1
	v_lshl_add_u64 v[98:99], v[136:137], 1, s[12:13]
	s_mov_b64 s[50:51], 0x80ffa20
	v_mov_b32_e32 v112, 0
	v_mov_b32_e32 v101, 0
	v_lshl_add_u64 v[102:103], v[98:99], 0, s[50:51]
	v_mov_b64_e32 v[106:107], 0
	v_mov_b64_e32 v[104:105], 0x200
	s_andn2_b64 s[48:49], s[48:49], exec
	s_andn2_b64 s[2:3], s[2:3], exec
	v_mov_b32_e32 v100, v101
	v_mov_b32_e32 v99, v101
	v_mov_b32_e32 v98, v101
	v_mov_b32_e32 v0, v112
	v_mov_b64_e32 v[108:109], 0

.LBB0_1184:
	s_andn2_b64 vcc, exec, s[50:51]
	s_cbranch_vccnz .LBB0_1186
	s_and_b64 s[50:51], s[0:1], exec
	v_readlane_b32 s50, v252, 34
	v_readlane_b32 s51, v252, 35
	s_mov_b32 s53, s51
	s_cselect_b32 s51, s69, s71
	s_cselect_b32 s50, s68, s70
	s_cselect_b32 s52, 0x80, 0
	s_lshl_b64 s[50:51], s[50:51], 2
	v_add_u32_e32 v0, 0xfffffd90, v136
	s_add_u32 s50, s16, s50
	s_mov_b32 s43, s53
	s_addc_u32 s51, s17, s51
	v_lshl_add_u64 v[98:99], v[0:1], 1, s[26:27]
	v_mov_b32_e32 v101, 0
	v_writelane_b32 v252, s42, 34
	v_lshl_add_u64 v[106:107], v[0:1], 2, s[50:51]
	v_cndmask_b32_e64 v103, 0, v99, s[0:1]
	v_cndmask_b32_e64 v102, 0, v98, s[0:1]
	v_mov_b64_e32 v[108:109], 0x80
	v_mov_b32_e32 v112, 0
	v_writelane_b32 v252, s43, 35
	v_mov_b64_e32 v[104:105], s[52:53]
	s_andn2_b64 s[48:49], s[48:49], exec
	s_andn2_b64 s[2:3], s[2:3], exec
	v_mov_b32_e32 v100, v101
	v_mov_b32_e32 v99, v101
	v_mov_b32_e32 v98, v101

.LBB0_1187:
	s_andn2_b64 vcc, exec, s[50:51]
	s_cbranch_vccnz .LBB0_1189
	s_and_b64 s[50:51], s[0:1], exec
	v_readlane_b32 s50, v252, 34
	v_readlane_b32 s51, v252, 35
	s_mov_b32 s53, s51
	s_cselect_b32 s51, s73, s75
	s_cselect_b32 s50, s72, s74
	s_cselect_b32 s52, 0x80, 0
	s_lshl_b64 s[50:51], s[50:51], 2
	v_add_u32_e32 v0, 0xfffffe10, v136
	s_add_u32 s50, s16, s50
	s_mov_b32 s43, s53
	s_addc_u32 s51, s17, s51
	v_lshl_add_u64 v[98:99], v[0:1], 1, s[28:29]
	v_mov_b32_e32 v101, 0
	v_writelane_b32 v252, s42, 34
	v_lshl_add_u64 v[106:107], v[0:1], 2, s[50:51]
	v_cndmask_b32_e64 v103, 0, v99, s[0:1]
	v_cndmask_b32_e64 v102, 0, v98, s[0:1]
	v_mov_b64_e32 v[108:109], 0x80
	v_mov_b32_e32 v112, 0
	v_writelane_b32 v252, s43, 35
	v_mov_b64_e32 v[104:105], s[52:53]
	s_andn2_b64 s[48:49], s[48:49], exec
	s_andn2_b64 s[2:3], s[2:3], exec
	v_mov_b32_e32 v100, v101
	v_mov_b32_e32 v99, v101
	v_mov_b32_e32 v98, v101
.LBB0_1189:
.LBB0_1190:
	s_andn2_saveexec_b64 s[8:9], s[8:9]
	s_cbranch_execz .LBB0_1192
	v_ashrrev_i32_e32 v111, 31, v110
	v_mov_b32_e32 v98, 0
	v_mov_b32_e32 v0, 0
	v_lshl_add_u64 v[102:103], v[110:111], 1, s[30:31]
	v_mov_b64_e32 v[104:105], 0x200
	v_mov_b64_e32 v[108:109], 0
	s_andn2_b64 s[2:3], s[2:3], exec
	s_andn2_b64 s[48:49], s[48:49], exec
	v_mov_b64_e32 v[106:107], 0
	v_mov_b32_e32 v112, v0
	v_mov_b32_e32 v99, v98
	v_mov_b32_e32 v100, v98
	v_mov_b32_e32 v101, v98
.LBB0_1192:
	s_or_b64 exec, exec, s[8:9]
	s_xor_b64 s[50:51], s[2:3], -1
	s_and_saveexec_b64 s[2:3], s[50:51]
	s_xor_b64 s[2:3], exec, s[2:3]
	s_andn2_saveexec_b64 s[2:3], s[2:3]
	s_cbranch_execz .LBB0_1202
	v_add_f32_e32 v94, v94, v98
	v_add_f32_e32 v95, v95, v99
	v_add_f32_e32 v96, v96, v100
	v_add_f32_e32 v97, v97, v101
	v_mul_f32_e32 v94, 0xbfb8aa3b, v94
	v_mul_f32_e32 v95, 0xbfb8aa3b, v95
	v_mul_f32_e32 v96, 0xbfb8aa3b, v96
	v_mul_f32_e32 v97, 0xbfb8aa3b, v97
	v_exp_f32_e32 v94, v94
	v_exp_f32_e32 v95, v95
	v_exp_f32_e32 v96, v96
	v_exp_f32_e32 v97, v97
	v_add_f32_e32 v94, 1.0, v94
	v_add_f32_e32 v95, 1.0, v95
	v_add_f32_e32 v96, 1.0, v96
	v_add_f32_e32 v97, 1.0, v97
	v_rcp_f32_e32 v94, v94
	v_rcp_f32_e32 v95, v95
	v_rcp_f32_e32 v96, v96
	v_rcp_f32_e32 v97, v97
	s_or_b64 exec, exec, s[2:3]
	v_cmp_ne_u64_e64 s[2:3], 0, v[102:103]
	s_and_saveexec_b64 s[8:9], s[2:3]
	s_cbranch_execnz .LBB0_1203

.LBB0_1198:
	s_or_b64 exec, exec, s[54:55]
	s_and_saveexec_b64 s[54:55], s[50:51]
	s_xor_b64 s[54:55], exec, s[54:55]
	s_andn2_saveexec_b64 s[54:55], s[54:55]
	s_cbranch_execz .LBB0_1204
	v_add_f32_e32 v90, v90, v98
	v_add_f32_e32 v91, v91, v99
	v_add_f32_e32 v92, v92, v100
	v_add_f32_e32 v93, v93, v101
	v_mul_f32_e32 v90, 0xbfb8aa3b, v90
	v_mul_f32_e32 v91, 0xbfb8aa3b, v91
	v_mul_f32_e32 v92, 0xbfb8aa3b, v92
	v_mul_f32_e32 v93, 0xbfb8aa3b, v93
	v_exp_f32_e32 v90, v90
	v_exp_f32_e32 v91, v91
	v_exp_f32_e32 v92, v92
	v_exp_f32_e32 v93, v93
	v_add_f32_e32 v90, 1.0, v90
	v_add_f32_e32 v91, 1.0, v91
	v_add_f32_e32 v92, 1.0, v92
	v_add_f32_e32 v93, 1.0, v93
	v_rcp_f32_e32 v90, v90
	v_rcp_f32_e32 v91, v91
	v_rcp_f32_e32 v92, v92
	v_rcp_f32_e32 v93, v93
	s_or_b64 exec, exec, s[54:55]
	v_or_b32_e32 v94, 16, v151
	s_and_saveexec_b64 s[54:55], s[2:3]
	s_cbranch_execnz .LBB0_1205

.LBB0_1208:
	s_or_b64 exec, exec, s[54:55]
	s_and_saveexec_b64 s[54:55], s[50:51]
	s_xor_b64 s[54:55], exec, s[54:55]
	s_andn2_saveexec_b64 s[54:55], s[54:55]
	s_cbranch_execz .LBB0_1212
	v_add_f32_e32 v86, v86, v98
	v_add_f32_e32 v87, v87, v99
	v_add_f32_e32 v88, v88, v100
	v_add_f32_e32 v89, v89, v101
	v_mul_f32_e32 v86, 0xbfb8aa3b, v86
	v_mul_f32_e32 v87, 0xbfb8aa3b, v87
	v_mul_f32_e32 v88, 0xbfb8aa3b, v88
	v_mul_f32_e32 v89, 0xbfb8aa3b, v89
	v_exp_f32_e32 v86, v86
	v_exp_f32_e32 v87, v87
	v_exp_f32_e32 v88, v88
	v_exp_f32_e32 v89, v89
	v_add_f32_e32 v86, 1.0, v86
	v_add_f32_e32 v87, 1.0, v87
	v_add_f32_e32 v88, 1.0, v88
	v_add_f32_e32 v89, 1.0, v89
	v_rcp_f32_e32 v86, v86
	v_rcp_f32_e32 v87, v87
	v_rcp_f32_e32 v88, v88
	v_rcp_f32_e32 v89, v89
	s_or_b64 exec, exec, s[54:55]
	v_or_b32_e32 v90, 32, v151
	s_and_saveexec_b64 s[54:55], s[2:3]
	s_cbranch_execnz .LBB0_1213

.LBB0_1216:
	s_or_b64 exec, exec, s[54:55]
	s_and_saveexec_b64 s[54:55], s[50:51]
	s_xor_b64 s[54:55], exec, s[54:55]
	s_andn2_saveexec_b64 s[54:55], s[54:55]
	s_cbranch_execz .LBB0_1220
	v_add_f32_e32 v82, v82, v98
	v_add_f32_e32 v83, v83, v99
	v_add_f32_e32 v84, v84, v100
	v_add_f32_e32 v85, v85, v101
	v_mul_f32_e32 v82, 0xbfb8aa3b, v82
	v_mul_f32_e32 v83, 0xbfb8aa3b, v83
	v_mul_f32_e32 v84, 0xbfb8aa3b, v84
	v_mul_f32_e32 v85, 0xbfb8aa3b, v85
	v_exp_f32_e32 v82, v82
	v_exp_f32_e32 v83, v83
	v_exp_f32_e32 v84, v84
	v_exp_f32_e32 v85, v85
	v_add_f32_e32 v82, 1.0, v82
	v_add_f32_e32 v83, 1.0, v83
	v_add_f32_e32 v84, 1.0, v84
	v_add_f32_e32 v85, 1.0, v85
	v_rcp_f32_e32 v82, v82
	v_rcp_f32_e32 v83, v83
	v_rcp_f32_e32 v84, v84
	v_rcp_f32_e32 v85, v85
	s_or_b64 exec, exec, s[54:55]
	v_or_b32_e32 v88, 48, v151
	s_and_saveexec_b64 s[54:55], s[2:3]
	s_cbranch_execnz .LBB0_1221

.LBB0_1233:
	s_or_b64 exec, exec, s[54:55]
	s_and_saveexec_b64 s[54:55], s[50:51]
	s_xor_b64 s[54:55], exec, s[54:55]
	s_andn2_saveexec_b64 s[54:55], s[54:55]
	s_cbranch_execz .LBB0_1237
	v_add_f32_e32 v78, v78, v98
	v_add_f32_e32 v79, v79, v99
	v_add_f32_e32 v80, v80, v100
	v_add_f32_e32 v81, v81, v101
	v_mul_f32_e32 v78, 0xbfb8aa3b, v78
	v_mul_f32_e32 v79, 0xbfb8aa3b, v79
	v_mul_f32_e32 v80, 0xbfb8aa3b, v80
	v_mul_f32_e32 v81, 0xbfb8aa3b, v81
	v_exp_f32_e32 v78, v78
	v_exp_f32_e32 v79, v79
	v_exp_f32_e32 v80, v80
	v_exp_f32_e32 v81, v81
	v_add_f32_e32 v78, 1.0, v78
	v_add_f32_e32 v79, 1.0, v79
	v_add_f32_e32 v80, 1.0, v80
	v_add_f32_e32 v81, 1.0, v81
	v_rcp_f32_e32 v78, v78
	v_rcp_f32_e32 v79, v79
	v_rcp_f32_e32 v80, v80
	v_rcp_f32_e32 v81, v81
	s_or_b64 exec, exec, s[54:55]
	v_add_u32_e32 v82, 0x80, v151
	s_and_saveexec_b64 s[54:55], s[2:3]
	s_cbranch_execnz .LBB0_1238

.LBB0_1241:
	s_or_b64 exec, exec, s[54:55]
	s_and_saveexec_b64 s[54:55], s[50:51]
	s_xor_b64 s[54:55], exec, s[54:55]
	s_andn2_saveexec_b64 s[54:55], s[54:55]
	s_cbranch_execz .LBB0_1245
	v_add_f32_e32 v74, v74, v98
	v_add_f32_e32 v75, v75, v99
	v_add_f32_e32 v76, v76, v100
	v_add_f32_e32 v77, v77, v101
	v_mul_f32_e32 v74, 0xbfb8aa3b, v74
	v_mul_f32_e32 v75, 0xbfb8aa3b, v75
	v_mul_f32_e32 v76, 0xbfb8aa3b, v76
	v_mul_f32_e32 v77, 0xbfb8aa3b, v77
	v_exp_f32_e32 v74, v74
	v_exp_f32_e32 v75, v75
	v_exp_f32_e32 v76, v76
	v_exp_f32_e32 v77, v77
	v_add_f32_e32 v74, 1.0, v74
	v_add_f32_e32 v75, 1.0, v75
	v_add_f32_e32 v76, 1.0, v76
	v_add_f32_e32 v77, 1.0, v77
	v_rcp_f32_e32 v74, v74
	v_rcp_f32_e32 v75, v75
	v_rcp_f32_e32 v76, v76
	v_rcp_f32_e32 v77, v77
	s_or_b64 exec, exec, s[54:55]
	v_add_u32_e32 v78, 0x90, v151
	s_and_saveexec_b64 s[54:55], s[2:3]
	s_cbranch_execnz .LBB0_1246

.LBB0_1249:
	s_or_b64 exec, exec, s[54:55]
	s_and_saveexec_b64 s[54:55], s[50:51]
	s_xor_b64 s[54:55], exec, s[54:55]
	s_andn2_saveexec_b64 s[54:55], s[54:55]
	s_cbranch_execz .LBB0_1258
	v_add_f32_e32 v70, v70, v98
	v_add_f32_e32 v71, v71, v99
	v_add_f32_e32 v72, v72, v100
	v_add_f32_e32 v73, v73, v101
	v_mul_f32_e32 v70, 0xbfb8aa3b, v70
	v_mul_f32_e32 v71, 0xbfb8aa3b, v71
	v_mul_f32_e32 v72, 0xbfb8aa3b, v72
	v_mul_f32_e32 v73, 0xbfb8aa3b, v73
	v_exp_f32_e32 v70, v70
	v_exp_f32_e32 v71, v71
	v_exp_f32_e32 v72, v72
	v_exp_f32_e32 v73, v73
	v_add_f32_e32 v70, 1.0, v70
	v_add_f32_e32 v71, 1.0, v71
	v_add_f32_e32 v72, 1.0, v72
	v_add_f32_e32 v73, 1.0, v73
	v_rcp_f32_e32 v70, v70
	v_rcp_f32_e32 v71, v71
	v_rcp_f32_e32 v72, v72
	v_rcp_f32_e32 v73, v73
	s_or_b64 exec, exec, s[54:55]
	v_add_u32_e32 v74, 0xa0, v151
	s_and_saveexec_b64 s[54:55], s[2:3]
	s_cbranch_execnz .LBB0_1259

.LBB0_1263:
	v_add_f32_e32 v66, v66, v98
	v_add_f32_e32 v67, v67, v99
	v_add_f32_e32 v68, v68, v100
	v_add_f32_e32 v69, v69, v101
	v_mul_f32_e32 v66, 0xbfb8aa3b, v66
	v_mul_f32_e32 v67, 0xbfb8aa3b, v67
	v_mul_f32_e32 v68, 0xbfb8aa3b, v68
	v_mul_f32_e32 v69, 0xbfb8aa3b, v69
	v_exp_f32_e32 v66, v66
	v_exp_f32_e32 v67, v67
	v_exp_f32_e32 v68, v68
	v_exp_f32_e32 v69, v69
	v_add_f32_e32 v66, 1.0, v66
	v_add_f32_e32 v67, 1.0, v67
	v_add_f32_e32 v68, 1.0, v68
	v_add_f32_e32 v69, 1.0, v69
	v_rcp_f32_e32 v66, v66
	v_rcp_f32_e32 v67, v67
	v_rcp_f32_e32 v68, v68
	v_rcp_f32_e32 v69, v69
	s_or_b64 exec, exec, s[50:51]
	v_add_u32_e32 v72, 0xb0, v151
	s_and_saveexec_b64 s[50:51], s[2:3]
	s_cbranch_execnz .LBB0_1256

.LBB0_1276:
	s_or_b64 exec, exec, s[46:47]
	v_or_b32_e32 v78, 0x80, v136
	s_movk_i32 s2, 0x1550
	v_cmp_gt_i32_e32 vcc, s2, v78
	s_and_saveexec_b64 s[46:47], vcc
	s_cbranch_execz .LBB0_1430
	s_movk_i32 s2, 0x1ff
	v_cmp_lt_i32_e32 vcc, s2, v78
	s_and_saveexec_b64 s[8:9], vcc
	s_xor_b64 s[8:9], exec, s[8:9]
	s_cbranch_execz .LBB0_1314
	s_movk_i32 s2, 0x27f
	v_cmp_lt_u32_e32 vcc, s2, v78
	s_and_saveexec_b64 s[52:53], vcc
	s_xor_b64 s[52:53], exec, s[52:53]
	s_cbranch_execz .LBB0_1311
	s_cmpk_lt_u32 s42, 0x300
	s_mov_b64 s[54:55], -1
	s_cbranch_scc1 .LBB0_1309
	s_cmpk_lt_u32 s42, 0x500
	s_cbranch_scc1 .LBB0_1306
	s_movk_i32 s2, 0x53f
	v_cmp_lt_u32_e32 vcc, s2, v78
	s_and_saveexec_b64 s[54:55], vcc
	s_xor_b64 s[54:55], exec, s[54:55]
	s_cbranch_execz .LBB0_1299
	s_movk_i32 s2, 0x547
	v_cmp_lt_u32_e32 vcc, s2, v78
	s_and_saveexec_b64 s[50:51], vcc
	s_xor_b64 s[50:51], exec, s[50:51]
	s_cbranch_execz .LBB0_1296
	s_movk_i32 s2, 0xb47
	v_cmp_lt_u32_e32 vcc, s2, v78
	s_and_saveexec_b64 s[48:49], vcc
	s_xor_b64 s[48:49], exec, s[48:49]
	s_cbranch_execz .LBB0_1293
	s_movk_i32 s2, 0xb4f
	v_cmp_lt_u32_e32 vcc, s2, v78
	s_and_saveexec_b64 s[56:57], vcc
	s_xor_b64 s[56:57], exec, s[56:57]
	s_cbranch_execz .LBB0_1290
	s_movk_i32 s2, 0xd4f
	v_cmp_lt_u32_e32 vcc, s2, v78
	s_and_saveexec_b64 s[2:3], vcc
	s_xor_b64 s[2:3], exec, s[2:3]
	s_cbranch_execz .LBB0_1287
	v_add_u32_e32 v0, 0xfffff330, v136
	v_lshl_add_u64 v[66:67], v[0:1], 2, s[10:11]
	global_load_dwordx4 v[66:69], v[66:67], off
	s_waitcnt vmcnt(0)
	v_lshl_add_u64 v[70:71], v[0:1], 1, s[18:19]
.LBB0_1287:
	s_or_saveexec_b64 s[58:59], s[2:3]
	s_mov_b64 s[2:3], -1
	v_mov_b64_e32 v[74:75], 0x800
	s_xor_b64 exec, exec, s[58:59]
	s_cbranch_execz .LBB0_1289
	v_mov_b32_e32 v137, v1
	v_lshl_add_u64 v[66:67], v[136:137], 1, s[12:13]
	s_mov_b64 s[2:3], 0x102fea60
	v_mov_b32_e32 v69, 0
	v_lshl_add_u64 v[70:71], v[66:67], 0, s[2:3]
	v_mov_b32_e32 v0, 0
	v_mov_b64_e32 v[74:75], 0x200
	s_xor_b64 s[2:3], exec, -1
	v_mov_b32_e32 v68, v69
	v_mov_b32_e32 v67, v69
	v_mov_b32_e32 v66, v69

.LBB0_1290:
	s_or_saveexec_b64 s[56:57], s[56:57]
	v_mov_b64_e32 v[72:73], 0
	v_mov_b64_e32 v[76:77], 0
	s_xor_b64 exec, exec, s[56:57]
	s_cbranch_execz .LBB0_1292
	v_mov_b32_e32 v137, v1
	v_lshl_add_u64 v[66:67], v[136:137], 2, s[44:45]
	s_mov_b64 s[58:59], 0x23d8f6e0
	v_mov_b32_e32 v69, 0
	v_lshl_add_u64 v[72:73], v[66:67], 0, s[58:59]
	v_mov_b64_e32 v[76:77], 8
	v_mov_b32_e32 v0, 0
	v_mov_b64_e32 v[70:71], 0
	s_andn2_b64 s[2:3], s[2:3], exec
	v_mov_b32_e32 v68, v69
	v_mov_b32_e32 v67, v69
	v_mov_b32_e32 v66, v69
	v_mov_b64_e32 v[74:75], 0

.LBB0_1293:
	s_or_saveexec_b64 s[56:57], s[48:49]
	s_mov_b64 s[48:49], 0
	s_xor_b64 exec, exec, s[56:57]
	s_cbranch_execz .LBB0_1295
	v_add_u32_e32 v0, 0xfffffb38, v136
	v_mov_b32_e32 v69, 0
	s_mov_b64 s[48:49], exec
	v_lshl_add_u64 v[70:71], v[0:1], 1, s[20:21]
	v_mov_b64_e32 v[72:73], 0
	v_mov_b64_e32 v[74:75], 0x600
	s_andn2_b64 s[2:3], s[2:3], exec
	v_mov_b32_e32 v68, v69
	v_mov_b32_e32 v67, v69
	v_mov_b32_e32 v66, v69
	v_mov_b64_e32 v[76:77], 0

.LBB0_1296:
	s_or_saveexec_b64 s[56:57], s[50:51]
	s_mov_b64 s[50:51], 0
	s_xor_b64 exec, exec, s[56:57]
	s_cbranch_execz .LBB0_1298
	v_mov_b32_e32 v137, v1
	v_lshl_add_u64 v[66:67], v[136:137], 2, s[44:45]
	s_mov_b64 s[58:59], 0x23e94f00
	v_mov_b32_e32 v69, 0
	s_mov_b64 s[50:51], exec
	v_lshl_add_u64 v[72:73], v[66:67], 0, s[58:59]
	v_mov_b64_e32 v[76:77], 8
	v_mov_b32_e32 v0, 0
	v_mov_b64_e32 v[70:71], 0
	s_andn2_b64 s[48:49], s[48:49], exec
	s_andn2_b64 s[2:3], s[2:3], exec
	v_mov_b32_e32 v68, v69
	v_mov_b32_e32 v67, v69
	v_mov_b32_e32 v66, v69
	v_mov_b64_e32 v[74:75], 0

.LBB0_1304:
	v_lshl_add_u64 v[72:73], v[0:1], 2, s[56:57]
	v_mov_b64_e32 v[74:75], 64
	v_mov_b32_e32 v69, 0
	v_mov_b32_e32 v80, s43
	s_andn2_b64 s[48:49], s[48:49], exec
	s_andn2_b64 s[50:51], s[50:51], exec
	s_andn2_b64 s[2:3], s[2:3], exec
	v_mov_b32_e32 v68, 0
	v_mov_b32_e32 v67, 0
	v_mov_b32_e32 v66, 0
	v_mov_b64_e32 v[76:77], 64

.LBB0_1306:
	s_andn2_b64 vcc, exec, s[54:55]
	s_cbranch_vccnz .LBB0_1308
	v_mov_b32_e32 v137, v1
	v_lshl_add_u64 v[66:67], v[136:137], 1, s[12:13]
	s_mov_b64 s[54:55], 0x80ffb00
	v_mov_b32_e32 v80, 0
	v_mov_b32_e32 v69, 0
	v_lshl_add_u64 v[70:71], v[66:67], 0, s[54:55]
	v_mov_b64_e32 v[72:73], 0
	v_mov_b64_e32 v[74:75], 0x200
	s_andn2_b64 s[48:49], s[48:49], exec
	s_andn2_b64 s[50:51], s[50:51], exec
	s_andn2_b64 s[2:3], s[2:3], exec
	v_mov_b32_e32 v68, v69
	v_mov_b32_e32 v67, v69
	v_mov_b32_e32 v66, v69
	v_mov_b32_e32 v0, v80
	v_mov_b64_e32 v[76:77], 0

.LBB0_1309:
	s_andn2_b64 vcc, exec, s[54:55]
	s_cbranch_vccnz .LBB0_1311
	s_and_b64 s[54:55], s[0:1], exec
	v_readlane_b32 s54, v252, 34
	v_readlane_b32 s55, v252, 35
	s_mov_b32 s57, s55
	s_cselect_b32 s55, s69, s71
	s_cselect_b32 s54, s68, s70
	s_cselect_b32 s56, 0x80, 0
	s_lshl_b64 s[54:55], s[54:55], 2
	v_add_u32_e32 v0, 0xfffffe00, v136
	s_add_u32 s54, s16, s54
	s_mov_b32 s43, s57
	s_addc_u32 s55, s17, s55
	v_lshl_add_u64 v[66:67], v[0:1], 1, s[26:27]
	v_mov_b32_e32 v69, 0
	v_writelane_b32 v252, s42, 34
	v_lshl_add_u64 v[72:73], v[0:1], 2, s[54:55]
	v_cndmask_b32_e64 v71, 0, v67, s[0:1]
	v_cndmask_b32_e64 v70, 0, v66, s[0:1]
	v_mov_b64_e32 v[76:77], 0x80
	v_mov_b32_e32 v80, 0
	v_writelane_b32 v252, s43, 35
	v_mov_b64_e32 v[74:75], s[56:57]
	s_andn2_b64 s[48:49], s[48:49], exec
	s_andn2_b64 s[50:51], s[50:51], exec
	s_andn2_b64 s[2:3], s[2:3], exec
	v_mov_b32_e32 v68, v69
	v_mov_b32_e32 v67, v69
	v_mov_b32_e32 v66, v69
.LBB0_1311:
	s_andn2_saveexec_b64 s[52:53], s[52:53]
	s_cbranch_execz .LBB0_1313
	s_and_b64 s[54:55], s[0:1], exec
	v_readlane_b32 s54, v252, 34
	v_readlane_b32 s55, v252, 35
	s_mov_b32 s57, s55
	s_cselect_b32 s55, s73, s75
	s_cselect_b32 s54, s72, s74
	s_cselect_b32 s56, 0x80, 0
	s_lshl_b64 s[54:55], s[54:55], 2
	v_add_u32_e32 v0, 0xfffffe80, v136
	s_add_u32 s54, s16, s54
	s_mov_b32 s43, s57
	s_addc_u32 s55, s17, s55
	v_lshl_add_u64 v[66:67], v[0:1], 1, s[28:29]
	v_mov_b32_e32 v69, 0
	v_writelane_b32 v252, s42, 34
	v_lshl_add_u64 v[72:73], v[0:1], 2, s[54:55]
	v_cndmask_b32_e64 v71, 0, v67, s[0:1]
	v_cndmask_b32_e64 v70, 0, v66, s[0:1]
	v_mov_b64_e32 v[76:77], 0x80
	v_mov_b32_e32 v80, 0
	v_writelane_b32 v252, s43, 35
	v_mov_b64_e32 v[74:75], s[56:57]
	s_andn2_b64 s[48:49], s[48:49], exec
	s_andn2_b64 s[50:51], s[50:51], exec
	s_andn2_b64 s[2:3], s[2:3], exec
	v_mov_b32_e32 v68, v69
	v_mov_b32_e32 v67, v69
	v_mov_b32_e32 v66, v69

.LBB0_1314:
	s_andn2_saveexec_b64 s[8:9], s[8:9]
	s_cbranch_execz .LBB0_1316
	v_ashrrev_i32_e32 v79, 31, v78
	v_mov_b32_e32 v66, 0
	v_mov_b32_e32 v0, 0
	v_lshl_add_u64 v[70:71], v[78:79], 1, s[30:31]
	v_mov_b64_e32 v[74:75], 0x200
	v_mov_b64_e32 v[76:77], 0
	s_andn2_b64 s[2:3], s[2:3], exec
	s_andn2_b64 s[50:51], s[50:51], exec
	s_andn2_b64 s[48:49], s[48:49], exec
	v_mov_b64_e32 v[72:73], 0
	v_mov_b32_e32 v80, v0
	v_mov_b32_e32 v67, v66
	v_mov_b32_e32 v68, v66
	v_mov_b32_e32 v69, v66

.LBB0_1323:
	v_add_f32_e32 v62, v62, v66
	v_add_f32_e32 v63, v63, v67
	v_add_f32_e32 v64, v64, v68
	v_add_f32_e32 v65, v65, v69
	v_mul_f32_e32 v62, 0xbfb8aa3b, v62
	v_mul_f32_e32 v63, 0xbfb8aa3b, v63
	v_mul_f32_e32 v64, 0xbfb8aa3b, v64
	v_mul_f32_e32 v65, 0xbfb8aa3b, v65
	v_exp_f32_e32 v62, v62
	v_exp_f32_e32 v63, v63
	v_exp_f32_e32 v64, v64
	v_exp_f32_e32 v65, v65
	v_add_f32_e32 v62, 1.0, v62
	v_add_f32_e32 v63, 1.0, v63
	v_add_f32_e32 v64, 1.0, v64
	v_add_f32_e32 v65, 1.0, v65
	v_rcp_f32_e32 v62, v62
	v_rcp_f32_e32 v63, v63
	v_rcp_f32_e32 v64, v64
	v_rcp_f32_e32 v65, v65
	s_or_b64 exec, exec, s[2:3]
	v_cmp_ne_u64_e64 s[2:3], 0, v[70:71]
	s_and_saveexec_b64 s[8:9], s[2:3]
	s_cbranch_execnz .LBB0_1321

.LBB0_1329:
	v_add_f32_e32 v58, v58, v66
	v_add_f32_e32 v59, v59, v67
	v_add_f32_e32 v60, v60, v68
	v_add_f32_e32 v61, v61, v69
	v_mul_f32_e32 v58, 0xbfb8aa3b, v58
	v_mul_f32_e32 v59, 0xbfb8aa3b, v59
	v_mul_f32_e32 v60, 0xbfb8aa3b, v60
	v_mul_f32_e32 v61, 0xbfb8aa3b, v61
	v_exp_f32_e32 v58, v58
	v_exp_f32_e32 v59, v59
	v_exp_f32_e32 v60, v60
	v_exp_f32_e32 v61, v61
	v_add_f32_e32 v58, 1.0, v58
	v_add_f32_e32 v59, 1.0, v59
	v_add_f32_e32 v60, 1.0, v60
	v_add_f32_e32 v61, 1.0, v61
	v_rcp_f32_e32 v58, v58
	v_rcp_f32_e32 v59, v59
	v_rcp_f32_e32 v60, v60
	v_rcp_f32_e32 v61, v61
	s_or_b64 exec, exec, s[56:57]
	v_or_b32_e32 v62, 16, v151
	s_and_saveexec_b64 s[56:57], s[2:3]
	s_cbranch_execnz .LBB0_1349

.LBB0_1341:
	v_add_f32_e32 v50, v50, v66
	v_add_f32_e32 v51, v51, v67
	v_add_f32_e32 v52, v52, v68
	v_add_f32_e32 v53, v53, v69
	v_mul_f32_e32 v50, 0xbfb8aa3b, v50
	v_mul_f32_e32 v51, 0xbfb8aa3b, v51
	v_mul_f32_e32 v52, 0xbfb8aa3b, v52
	v_mul_f32_e32 v53, 0xbfb8aa3b, v53
	v_exp_f32_e32 v50, v50
	v_exp_f32_e32 v51, v51
	v_exp_f32_e32 v52, v52
	v_exp_f32_e32 v53, v53
	v_add_f32_e32 v50, 1.0, v50
	v_add_f32_e32 v51, 1.0, v51
	v_add_f32_e32 v52, 1.0, v52
	v_add_f32_e32 v53, 1.0, v53
	v_rcp_f32_e32 v50, v50
	v_rcp_f32_e32 v51, v51
	v_rcp_f32_e32 v52, v52
	v_rcp_f32_e32 v53, v53
	s_or_b64 exec, exec, s[56:57]
	v_or_b32_e32 v56, 48, v151
	s_and_saveexec_b64 s[56:57], s[2:3]
	s_cbranch_execnz .LBB0_1361

.LBB0_1353:
	v_add_f32_e32 v54, v54, v66
	v_add_f32_e32 v55, v55, v67
	v_add_f32_e32 v56, v56, v68
	v_add_f32_e32 v57, v57, v69
	v_mul_f32_e32 v54, 0xbfb8aa3b, v54
	v_mul_f32_e32 v55, 0xbfb8aa3b, v55
	v_mul_f32_e32 v56, 0xbfb8aa3b, v56
	v_mul_f32_e32 v57, 0xbfb8aa3b, v57
	v_exp_f32_e32 v54, v54
	v_exp_f32_e32 v55, v55
	v_exp_f32_e32 v56, v56
	v_exp_f32_e32 v57, v57
	v_add_f32_e32 v54, 1.0, v54
	v_add_f32_e32 v55, 1.0, v55
	v_add_f32_e32 v56, 1.0, v56
	v_add_f32_e32 v57, 1.0, v57
	v_rcp_f32_e32 v54, v54
	v_rcp_f32_e32 v55, v55
	v_rcp_f32_e32 v56, v56
	v_rcp_f32_e32 v57, v57
	s_or_b64 exec, exec, s[56:57]
	v_or_b32_e32 v58, 32, v151
	s_and_saveexec_b64 s[56:57], s[2:3]
	s_cbranch_execnz .LBB0_1337

.LBB0_1382:
	v_add_f32_e32 v42, v42, v66
	v_add_f32_e32 v43, v43, v67
	v_add_f32_e32 v44, v44, v68
	v_add_f32_e32 v45, v45, v69
	v_mul_f32_e32 v42, 0xbfb8aa3b, v42
	v_mul_f32_e32 v43, 0xbfb8aa3b, v43
	v_mul_f32_e32 v44, 0xbfb8aa3b, v44
	v_mul_f32_e32 v45, 0xbfb8aa3b, v45
	v_exp_f32_e32 v42, v42
	v_exp_f32_e32 v43, v43
	v_exp_f32_e32 v44, v44
	v_exp_f32_e32 v45, v45
	v_add_f32_e32 v42, 1.0, v42
	v_add_f32_e32 v43, 1.0, v43
	v_add_f32_e32 v44, 1.0, v44
	v_add_f32_e32 v45, 1.0, v45
	v_rcp_f32_e32 v42, v42
	v_rcp_f32_e32 v43, v43
	v_rcp_f32_e32 v44, v44
	v_rcp_f32_e32 v45, v45
	s_or_b64 exec, exec, s[56:57]
	v_add_u32_e32 v46, 0x90, v151
	s_and_saveexec_b64 s[56:57], s[2:3]
	s_cbranch_execnz .LBB0_1406

.LBB0_1394:
	v_add_f32_e32 v34, v34, v66
	v_add_f32_e32 v35, v35, v67
	v_add_f32_e32 v36, v36, v68
	v_add_f32_e32 v37, v37, v69
	v_mul_f32_e32 v34, 0xbfb8aa3b, v34
	v_mul_f32_e32 v35, 0xbfb8aa3b, v35
	v_mul_f32_e32 v36, 0xbfb8aa3b, v36
	v_mul_f32_e32 v37, 0xbfb8aa3b, v37
	v_exp_f32_e32 v34, v34
	v_exp_f32_e32 v35, v35
	v_exp_f32_e32 v36, v36
	v_exp_f32_e32 v37, v37
	v_add_f32_e32 v34, 1.0, v34
	v_add_f32_e32 v35, 1.0, v35
	v_add_f32_e32 v36, 1.0, v36
	v_add_f32_e32 v37, 1.0, v37
	v_rcp_f32_e32 v34, v34
	v_rcp_f32_e32 v35, v35
	v_rcp_f32_e32 v36, v36
	v_rcp_f32_e32 v37, v37
	s_or_b64 exec, exec, s[50:51]
	v_add_u32_e32 v40, 0xb0, v151
	s_and_saveexec_b64 s[50:51], s[2:3]
	s_cbranch_execnz .LBB0_1418

.LBB0_1398:
	v_add_f32_e32 v46, v46, v66
	v_add_f32_e32 v47, v47, v67
	v_add_f32_e32 v48, v48, v68
	v_add_f32_e32 v49, v49, v69
	v_mul_f32_e32 v46, 0xbfb8aa3b, v46
	v_mul_f32_e32 v47, 0xbfb8aa3b, v47
	v_mul_f32_e32 v48, 0xbfb8aa3b, v48
	v_mul_f32_e32 v49, 0xbfb8aa3b, v49
	v_exp_f32_e32 v46, v46
	v_exp_f32_e32 v47, v47
	v_exp_f32_e32 v48, v48
	v_exp_f32_e32 v49, v49
	v_add_f32_e32 v46, 1.0, v46
	v_add_f32_e32 v47, 1.0, v47
	v_add_f32_e32 v48, 1.0, v48
	v_add_f32_e32 v49, 1.0, v49
	v_rcp_f32_e32 v46, v46
	v_rcp_f32_e32 v47, v47
	v_rcp_f32_e32 v48, v48
	v_rcp_f32_e32 v49, v49
	s_or_b64 exec, exec, s[56:57]
	v_add_u32_e32 v50, 0x80, v151
	s_and_saveexec_b64 s[56:57], s[2:3]
	s_cbranch_execnz .LBB0_1378

.LBB0_1410:
	v_add_f32_e32 v38, v38, v66
	v_add_f32_e32 v39, v39, v67
	v_add_f32_e32 v40, v40, v68
	v_add_f32_e32 v41, v41, v69
	v_mul_f32_e32 v38, 0xbfb8aa3b, v38
	v_mul_f32_e32 v39, 0xbfb8aa3b, v39
	v_mul_f32_e32 v40, 0xbfb8aa3b, v40
	v_mul_f32_e32 v41, 0xbfb8aa3b, v41
	v_exp_f32_e32 v38, v38
	v_exp_f32_e32 v39, v39
	v_exp_f32_e32 v40, v40
	v_exp_f32_e32 v41, v41
	v_add_f32_e32 v38, 1.0, v38
	v_add_f32_e32 v39, 1.0, v39
	v_add_f32_e32 v40, 1.0, v40
	v_add_f32_e32 v41, 1.0, v41
	v_rcp_f32_e32 v38, v38
	v_rcp_f32_e32 v39, v39
	v_rcp_f32_e32 v40, v40
	v_rcp_f32_e32 v41, v41
	s_or_b64 exec, exec, s[56:57]
	v_add_u32_e32 v42, 0xa0, v151
	s_and_saveexec_b64 s[56:57], s[2:3]
	s_cbranch_execnz .LBB0_1390

.LBB0_1430:
	s_or_b64 exec, exec, s[46:47]
	v_or_b32_e32 v46, 0x90, v136
	s_movk_i32 s2, 0x1550
	v_cmp_gt_i32_e32 vcc, s2, v46
	s_and_saveexec_b64 s[46:47], vcc
	s_cbranch_execz .LBB0_986
	s_movk_i32 s2, 0x1ff
	v_cmp_lt_i32_e32 vcc, s2, v46
	s_and_saveexec_b64 s[8:9], vcc
	s_xor_b64 s[8:9], exec, s[8:9]
	s_cbranch_execz .LBB0_1469
	s_movk_i32 s2, 0x27f
	v_cmp_lt_u32_e32 vcc, s2, v46
	s_and_saveexec_b64 s[52:53], vcc
	s_xor_b64 s[52:53], exec, s[52:53]
	s_cbranch_execz .LBB0_1466
	s_cmpk_lt_u32 s42, 0x300
	s_mov_b64 s[54:55], -1
	s_cbranch_scc1 .LBB0_1463
	s_cmpk_lt_u32 s42, 0x500
	s_mov_b64 s[42:43], -1
	s_cbranch_scc1 .LBB0_1460
	s_movk_i32 s2, 0x53f
	v_cmp_lt_u32_e32 vcc, s2, v46
	s_and_saveexec_b64 s[42:43], vcc
	s_xor_b64 s[42:43], exec, s[42:43]
	s_cbranch_execz .LBB0_1453
	s_movk_i32 s2, 0x547
	v_cmp_lt_u32_e32 vcc, s2, v46
	s_and_saveexec_b64 s[50:51], vcc
	s_xor_b64 s[50:51], exec, s[50:51]
	s_cbranch_execz .LBB0_1450
	s_movk_i32 s2, 0xb47
	v_cmp_lt_u32_e32 vcc, s2, v46
	s_and_saveexec_b64 s[48:49], vcc
	s_xor_b64 s[48:49], exec, s[48:49]
	s_cbranch_execz .LBB0_1447
	s_movk_i32 s2, 0xb4f
	v_cmp_lt_u32_e32 vcc, s2, v46
	s_and_saveexec_b64 s[54:55], vcc
	s_xor_b64 s[54:55], exec, s[54:55]
	s_cbranch_execz .LBB0_1444
	s_movk_i32 s2, 0xd4f
	v_cmp_lt_u32_e32 vcc, s2, v46
	s_and_saveexec_b64 s[2:3], vcc
	s_xor_b64 s[2:3], exec, s[2:3]
	s_cbranch_execz .LBB0_1441
	v_add_u32_e32 v0, 0xfffff340, v136
	v_lshl_add_u64 v[34:35], v[0:1], 2, s[10:11]
	global_load_dwordx4 v[34:37], v[34:35], off
	s_waitcnt vmcnt(0)
	v_lshl_add_u64 v[38:39], v[0:1], 1, s[18:19]
.LBB0_1441:
	s_or_saveexec_b64 s[56:57], s[2:3]
	s_mov_b64 s[2:3], -1
	v_mov_b64_e32 v[42:43], 0x800
	s_xor_b64 exec, exec, s[56:57]
	s_cbranch_execz .LBB0_1443
	v_mov_b32_e32 v137, v1
	v_lshl_add_u64 v[34:35], v[136:137], 1, s[12:13]
	s_mov_b64 s[2:3], 0x102fea80
	v_mov_b32_e32 v37, 0
	v_lshl_add_u64 v[38:39], v[34:35], 0, s[2:3]
	v_mov_b32_e32 v0, 0
	v_mov_b64_e32 v[42:43], 0x200
	s_xor_b64 s[2:3], exec, -1
	v_mov_b32_e32 v36, v37
	v_mov_b32_e32 v35, v37
	v_mov_b32_e32 v34, v37

.LBB0_1444:
	s_or_saveexec_b64 s[54:55], s[54:55]
	v_mov_b64_e32 v[40:41], 0
	v_mov_b64_e32 v[44:45], 0
	s_xor_b64 exec, exec, s[54:55]
	s_cbranch_execz .LBB0_1446
	v_mov_b32_e32 v137, v1
	v_lshl_add_u64 v[34:35], v[136:137], 2, s[44:45]
	s_mov_b64 s[56:57], 0x23d8f720
	v_mov_b32_e32 v37, 0
	v_lshl_add_u64 v[40:41], v[34:35], 0, s[56:57]
	v_mov_b64_e32 v[44:45], 8
	v_mov_b32_e32 v0, 0
	v_mov_b64_e32 v[38:39], 0
	s_andn2_b64 s[2:3], s[2:3], exec
	v_mov_b32_e32 v36, v37
	v_mov_b32_e32 v35, v37
	v_mov_b32_e32 v34, v37
	v_mov_b64_e32 v[42:43], 0

.LBB0_1447:
	s_or_saveexec_b64 s[54:55], s[48:49]
	s_mov_b64 s[48:49], 0
	s_xor_b64 exec, exec, s[54:55]
	s_cbranch_execz .LBB0_1449
	v_add_u32_e32 v0, 0xfffffb48, v136
	v_mov_b32_e32 v37, 0
	s_mov_b64 s[48:49], exec
	v_lshl_add_u64 v[38:39], v[0:1], 1, s[20:21]
	v_mov_b64_e32 v[40:41], 0
	v_mov_b64_e32 v[42:43], 0x600
	s_andn2_b64 s[2:3], s[2:3], exec
	v_mov_b32_e32 v36, v37
	v_mov_b32_e32 v35, v37
	v_mov_b32_e32 v34, v37
	v_mov_b64_e32 v[44:45], 0

.LBB0_1450:
	s_or_saveexec_b64 s[54:55], s[50:51]
	s_mov_b64 s[50:51], 0
	s_xor_b64 exec, exec, s[54:55]
	s_cbranch_execz .LBB0_1452
	v_mov_b32_e32 v137, v1
	v_lshl_add_u64 v[34:35], v[136:137], 2, s[44:45]
	s_mov_b64 s[44:45], 0x23e94f40
	v_mov_b32_e32 v37, 0
	v_lshl_add_u64 v[40:41], v[34:35], 0, s[44:45]
	v_mov_b64_e32 v[44:45], 8
	v_mov_b32_e32 v0, 0
	v_mov_b64_e32 v[38:39], 0
	s_andn2_b64 s[48:49], s[48:49], exec
	s_andn2_b64 s[2:3], s[2:3], exec
	s_mov_b64 s[50:51], exec
	v_mov_b32_e32 v36, v37
	v_mov_b32_e32 v35, v37
	v_mov_b32_e32 v34, v37
	v_mov_b64_e32 v[42:43], 0

.LBB0_1458:
	v_lshl_add_u64 v[40:41], v[0:1], 2, s[44:45]
	v_mov_b64_e32 v[42:43], 64
	v_mov_b32_e32 v37, 0
	v_mov_b32_e32 v48, s54
	s_andn2_b64 s[48:49], s[48:49], exec
	s_andn2_b64 s[50:51], s[50:51], exec
	s_andn2_b64 s[2:3], s[2:3], exec
	v_mov_b32_e32 v36, 0
	v_mov_b32_e32 v35, 0
	v_mov_b32_e32 v34, 0
	v_mov_b64_e32 v[44:45], 64

.LBB0_1460:
	s_andn2_b64 vcc, exec, s[42:43]
	s_cbranch_vccnz .LBB0_1462
	v_mov_b32_e32 v137, v1
	v_lshl_add_u64 v[34:35], v[136:137], 1, s[12:13]
	s_mov_b64 s[42:43], 0x80ffb20
	v_mov_b32_e32 v48, 0
	v_mov_b32_e32 v37, 0
	v_lshl_add_u64 v[38:39], v[34:35], 0, s[42:43]
	v_mov_b64_e32 v[40:41], 0
	v_mov_b64_e32 v[42:43], 0x200
	s_andn2_b64 s[48:49], s[48:49], exec
	s_andn2_b64 s[50:51], s[50:51], exec
	s_andn2_b64 s[2:3], s[2:3], exec
	v_mov_b32_e32 v36, v37
	v_mov_b32_e32 v35, v37
	v_mov_b32_e32 v34, v37
	v_mov_b32_e32 v0, v48
	v_mov_b64_e32 v[44:45], 0

.LBB0_1463:
	s_andn2_b64 vcc, exec, s[54:55]
	s_cbranch_vccnz .LBB0_1465
	s_and_b64 s[42:43], s[0:1], exec
	v_readlane_b32 s42, v252, 34
	v_readlane_b32 s43, v252, 35
	s_mov_b32 s45, s43
	s_cselect_b32 s43, s69, s71
	s_cselect_b32 s42, s68, s70
	s_cselect_b32 s44, 0x80, 0
	s_lshl_b64 s[42:43], s[42:43], 2
	s_add_u32 s42, s16, s42
	v_add_u32_e32 v0, 0xfffffe10, v136
	s_addc_u32 s43, s17, s43
	v_lshl_add_u64 v[40:41], v[0:1], 2, s[42:43]
	s_mov_b32 s43, s45
	v_lshl_add_u64 v[34:35], v[0:1], 1, s[26:27]
	v_mov_b32_e32 v37, 0
	v_writelane_b32 v252, s42, 34
	v_cndmask_b32_e64 v39, 0, v35, s[0:1]
	v_cndmask_b32_e64 v38, 0, v34, s[0:1]
	v_mov_b64_e32 v[44:45], 0x80
	v_mov_b32_e32 v48, 0
	v_writelane_b32 v252, s43, 35
	v_mov_b64_e32 v[42:43], s[44:45]
	s_andn2_b64 s[48:49], s[48:49], exec
	s_andn2_b64 s[50:51], s[50:51], exec
	s_andn2_b64 s[2:3], s[2:3], exec
	v_mov_b32_e32 v36, v37
	v_mov_b32_e32 v35, v37
	v_mov_b32_e32 v34, v37
.LBB0_1465:
.LBB0_1466:
	s_andn2_saveexec_b64 s[42:43], s[52:53]
	s_cbranch_execz .LBB0_1468
	s_and_b64 s[44:45], s[0:1], exec
	v_readlane_b32 s44, v252, 34
	v_readlane_b32 s45, v252, 35
	s_mov_b32 s53, s45
	s_cselect_b32 s45, s73, s75
	s_cselect_b32 s44, s72, s74
	s_cselect_b32 s52, 0x80, 0
	s_lshl_b64 s[44:45], s[44:45], 2
	s_add_u32 s44, s16, s44
	v_add_u32_e32 v0, 0xfffffe90, v136
	s_addc_u32 s45, s17, s45
	v_lshl_add_u64 v[40:41], v[0:1], 2, s[44:45]
	s_mov_b32 s45, s53
	v_lshl_add_u64 v[34:35], v[0:1], 1, s[28:29]
	v_mov_b32_e32 v37, 0
	v_writelane_b32 v252, s44, 34
	v_cndmask_b32_e64 v39, 0, v35, s[0:1]
	v_cndmask_b32_e64 v38, 0, v34, s[0:1]
	v_mov_b64_e32 v[44:45], 0x80
	v_mov_b32_e32 v48, 0
	v_writelane_b32 v252, s45, 35
	v_mov_b64_e32 v[42:43], s[52:53]
	s_andn2_b64 s[48:49], s[48:49], exec
	s_andn2_b64 s[50:51], s[50:51], exec
	s_andn2_b64 s[2:3], s[2:3], exec
	v_mov_b32_e32 v36, v37
	v_mov_b32_e32 v35, v37
	v_mov_b32_e32 v34, v37

.LBB0_1469:
	s_andn2_saveexec_b64 s[8:9], s[8:9]
	s_cbranch_execz .LBB0_1471
	v_ashrrev_i32_e32 v47, 31, v46
	v_mov_b32_e32 v34, 0
	v_mov_b32_e32 v0, 0
	v_lshl_add_u64 v[38:39], v[46:47], 1, s[30:31]
	v_mov_b64_e32 v[42:43], 0x200
	v_mov_b64_e32 v[44:45], 0
	s_andn2_b64 s[2:3], s[2:3], exec
	s_andn2_b64 s[50:51], s[50:51], exec
	s_andn2_b64 s[48:49], s[48:49], exec
	v_mov_b64_e32 v[40:41], 0
	v_mov_b32_e32 v48, v0
	v_mov_b32_e32 v35, v34
	v_mov_b32_e32 v36, v34
	v_mov_b32_e32 v37, v34

.LBB0_1478:
	v_add_f32_e32 v30, v30, v34
	v_add_f32_e32 v31, v31, v35
	v_add_f32_e32 v32, v32, v36
	v_add_f32_e32 v33, v33, v37
	v_mul_f32_e32 v30, 0xbfb8aa3b, v30
	v_mul_f32_e32 v31, 0xbfb8aa3b, v31
	v_mul_f32_e32 v32, 0xbfb8aa3b, v32
	v_mul_f32_e32 v33, 0xbfb8aa3b, v33
	v_exp_f32_e32 v30, v30
	v_exp_f32_e32 v31, v31
	v_exp_f32_e32 v32, v32
	v_exp_f32_e32 v33, v33
	v_add_f32_e32 v30, 1.0, v30
	v_add_f32_e32 v31, 1.0, v31
	v_add_f32_e32 v32, 1.0, v32
	v_add_f32_e32 v33, 1.0, v33
	v_rcp_f32_e32 v30, v30
	v_rcp_f32_e32 v31, v31
	v_rcp_f32_e32 v32, v32
	v_rcp_f32_e32 v33, v33
	s_or_b64 exec, exec, s[2:3]
	v_cmp_ne_u64_e64 s[2:3], 0, v[38:39]
	s_and_saveexec_b64 s[8:9], s[2:3]
	s_cbranch_execnz .LBB0_1476

.LBB0_1484:
	v_add_f32_e32 v26, v26, v34
	v_add_f32_e32 v27, v27, v35
	v_add_f32_e32 v28, v28, v36
	v_add_f32_e32 v29, v29, v37
	v_mul_f32_e32 v26, 0xbfb8aa3b, v26
	v_mul_f32_e32 v27, 0xbfb8aa3b, v27
	v_mul_f32_e32 v28, 0xbfb8aa3b, v28
	v_mul_f32_e32 v29, 0xbfb8aa3b, v29
	v_exp_f32_e32 v26, v26
	v_exp_f32_e32 v27, v27
	v_exp_f32_e32 v28, v28
	v_exp_f32_e32 v29, v29
	v_add_f32_e32 v26, 1.0, v26
	v_add_f32_e32 v27, 1.0, v27
	v_add_f32_e32 v28, 1.0, v28
	v_add_f32_e32 v29, 1.0, v29
	v_rcp_f32_e32 v26, v26
	v_rcp_f32_e32 v27, v27
	v_rcp_f32_e32 v28, v28
	v_rcp_f32_e32 v29, v29
	s_or_b64 exec, exec, s[44:45]
	v_or_b32_e32 v30, 16, v151
	s_and_saveexec_b64 s[44:45], s[2:3]
	s_cbranch_execnz .LBB0_1504

.LBB0_1496:
	v_add_f32_e32 v18, v18, v34
	v_add_f32_e32 v19, v19, v35
	v_add_f32_e32 v20, v20, v36
	v_add_f32_e32 v21, v21, v37
	v_mul_f32_e32 v18, 0xbfb8aa3b, v18
	v_mul_f32_e32 v19, 0xbfb8aa3b, v19
	v_mul_f32_e32 v20, 0xbfb8aa3b, v20
	v_mul_f32_e32 v21, 0xbfb8aa3b, v21
	v_exp_f32_e32 v18, v18
	v_exp_f32_e32 v19, v19
	v_exp_f32_e32 v20, v20
	v_exp_f32_e32 v21, v21
	v_add_f32_e32 v18, 1.0, v18
	v_add_f32_e32 v19, 1.0, v19
	v_add_f32_e32 v20, 1.0, v20
	v_add_f32_e32 v21, 1.0, v21
	v_rcp_f32_e32 v18, v18
	v_rcp_f32_e32 v19, v19
	v_rcp_f32_e32 v20, v20
	v_rcp_f32_e32 v21, v21
	s_or_b64 exec, exec, s[44:45]
	v_or_b32_e32 v24, 48, v151
	s_and_saveexec_b64 s[44:45], s[2:3]
	s_cbranch_execnz .LBB0_1516

.LBB0_1508:
	v_add_f32_e32 v22, v22, v34
	v_add_f32_e32 v23, v23, v35
	v_add_f32_e32 v24, v24, v36
	v_add_f32_e32 v25, v25, v37
	v_mul_f32_e32 v22, 0xbfb8aa3b, v22
	v_mul_f32_e32 v23, 0xbfb8aa3b, v23
	v_mul_f32_e32 v24, 0xbfb8aa3b, v24
	v_mul_f32_e32 v25, 0xbfb8aa3b, v25
	v_exp_f32_e32 v22, v22
	v_exp_f32_e32 v23, v23
	v_exp_f32_e32 v24, v24
	v_exp_f32_e32 v25, v25
	v_add_f32_e32 v22, 1.0, v22
	v_add_f32_e32 v23, 1.0, v23
	v_add_f32_e32 v24, 1.0, v24
	v_add_f32_e32 v25, 1.0, v25
	v_rcp_f32_e32 v22, v22
	v_rcp_f32_e32 v23, v23
	v_rcp_f32_e32 v24, v24
	v_rcp_f32_e32 v25, v25
	s_or_b64 exec, exec, s[44:45]
	v_or_b32_e32 v26, 32, v151
	s_and_saveexec_b64 s[44:45], s[2:3]
	s_cbranch_execnz .LBB0_1492

.LBB0_1537:
	v_add_f32_e32 v10, v10, v34
	v_add_f32_e32 v11, v11, v35
	v_add_f32_e32 v12, v12, v36
	v_add_f32_e32 v13, v13, v37
	v_mul_f32_e32 v10, 0xbfb8aa3b, v10
	v_mul_f32_e32 v11, 0xbfb8aa3b, v11
	v_mul_f32_e32 v12, 0xbfb8aa3b, v12
	v_mul_f32_e32 v13, 0xbfb8aa3b, v13
	v_exp_f32_e32 v10, v10
	v_exp_f32_e32 v11, v11
	v_exp_f32_e32 v12, v12
	v_exp_f32_e32 v13, v13
	v_add_f32_e32 v10, 1.0, v10
	v_add_f32_e32 v11, 1.0, v11
	v_add_f32_e32 v12, 1.0, v12
	v_add_f32_e32 v13, 1.0, v13
	v_rcp_f32_e32 v10, v10
	v_rcp_f32_e32 v11, v11
	v_rcp_f32_e32 v12, v12
	v_rcp_f32_e32 v13, v13
	s_or_b64 exec, exec, s[44:45]
	v_add_u32_e32 v14, 0x90, v151
	s_and_saveexec_b64 s[44:45], s[2:3]
	s_cbranch_execnz .LBB0_1561

.LBB0_1549:
	v_add_f32_e32 v2, v2, v34
	v_add_f32_e32 v3, v3, v35
	v_add_f32_e32 v4, v4, v36
	v_add_f32_e32 v5, v5, v37
	v_mul_f32_e32 v2, 0xbfb8aa3b, v2
	v_mul_f32_e32 v3, 0xbfb8aa3b, v3
	v_mul_f32_e32 v4, 0xbfb8aa3b, v4
	v_mul_f32_e32 v5, 0xbfb8aa3b, v5
	v_exp_f32_e32 v2, v2
	v_exp_f32_e32 v3, v3
	v_exp_f32_e32 v4, v4
	v_exp_f32_e32 v5, v5
	v_add_f32_e32 v2, 1.0, v2
	v_add_f32_e32 v3, 1.0, v3
	v_add_f32_e32 v4, 1.0, v4
	v_add_f32_e32 v5, 1.0, v5
	v_rcp_f32_e32 v2, v2
	v_rcp_f32_e32 v3, v3
	v_rcp_f32_e32 v4, v4
	v_rcp_f32_e32 v5, v5
	s_or_b64 exec, exec, s[0:1]
	v_add_u32_e32 v8, 0xb0, v151
	s_and_saveexec_b64 s[0:1], s[2:3]
	s_cbranch_execnz .LBB0_1573

.LBB0_1553:
	v_add_f32_e32 v14, v14, v34
	v_add_f32_e32 v15, v15, v35
	v_add_f32_e32 v16, v16, v36
	v_add_f32_e32 v17, v17, v37
	v_mul_f32_e32 v14, 0xbfb8aa3b, v14
	v_mul_f32_e32 v15, 0xbfb8aa3b, v15
	v_mul_f32_e32 v16, 0xbfb8aa3b, v16
	v_mul_f32_e32 v17, 0xbfb8aa3b, v17
	v_exp_f32_e32 v14, v14
	v_exp_f32_e32 v15, v15
	v_exp_f32_e32 v16, v16
	v_exp_f32_e32 v17, v17
	v_add_f32_e32 v14, 1.0, v14
	v_add_f32_e32 v15, 1.0, v15
	v_add_f32_e32 v16, 1.0, v16
	v_add_f32_e32 v17, 1.0, v17
	v_rcp_f32_e32 v14, v14
	v_rcp_f32_e32 v15, v15
	v_rcp_f32_e32 v16, v16
	v_rcp_f32_e32 v17, v17
	s_or_b64 exec, exec, s[44:45]
	v_add_u32_e32 v18, 0x80, v151
	s_and_saveexec_b64 s[44:45], s[2:3]
	s_cbranch_execnz .LBB0_1533

.LBB0_1565:
	v_add_f32_e32 v6, v6, v34
	v_add_f32_e32 v7, v7, v35
	v_add_f32_e32 v8, v8, v36
	v_add_f32_e32 v9, v9, v37
	v_mul_f32_e32 v6, 0xbfb8aa3b, v6
	v_mul_f32_e32 v7, 0xbfb8aa3b, v7
	v_mul_f32_e32 v8, 0xbfb8aa3b, v8
	v_mul_f32_e32 v9, 0xbfb8aa3b, v9
	v_exp_f32_e32 v6, v6
	v_exp_f32_e32 v7, v7
	v_exp_f32_e32 v8, v8
	v_exp_f32_e32 v9, v9
	v_add_f32_e32 v6, 1.0, v6
	v_add_f32_e32 v7, 1.0, v7
	v_add_f32_e32 v8, 1.0, v8
	v_add_f32_e32 v9, 1.0, v9
	v_rcp_f32_e32 v6, v6
	v_rcp_f32_e32 v7, v7
	v_rcp_f32_e32 v8, v8
	v_rcp_f32_e32 v9, v9
	s_or_b64 exec, exec, s[44:45]
	v_add_u32_e32 v10, 0xa0, v151
	s_and_saveexec_b64 s[44:45], s[2:3]
	s_cbranch_execnz .LBB0_1545
